# loop-edge edit on all 5 GEMM K-loops: the 14 loop-carried SALU instructions (tail counter/pointer bumps + head next-tile pointer selects) moved in front of the loop-back barrier, exit compare last; sa
# baseline (speedup 1.0000x reference)
; #define PG8_STAGE(bufoff, gbase, voff) do { _Pragma("unroll") for (int _i = 0; _i < 2; ++_i) \
;         __builtin_amdgcn_global_load_lds((const unsigned*)((const char*)(gbase) + (voff)[_i]), (PG8_LAS unsigned*)(lds + (bufoff) + ldsw + _i * 8192), 16, 0, 0); } while (0)
; #define PG8_LDA(dst, b, h) do { _Pragma("unroll") for (int m = 0; m < 4; ++m) _Pragma("unroll") for (int k = 0; k < 2; ++k) dst[m][k] = *(const PG8_LAS bf16x8*)(lds + PG8_SA(b, h) + aoff + m * 2048 + k * 1024); } while (0)
; #define PG8_LDB(dst, b, h) do { _Pragma("unroll") for (int n = 0; n < 2; ++n) _Pragma("unroll") for (int k = 0; k < 2; ++k) dst[n][k] = *(const PG8_LAS bf16x8*)(lds + PG8_SB(b, h) + boff + n * 2048 + k * 1024); } while (0)
; #define PG8_WAIT_V(n) asm volatile("s_waitcnt vmcnt(" #n ")" ::: "memory")
; #define PG8_WAIT_L(n) asm volatile("s_waitcnt lgkmcnt(" #n ")" ::: "memory")
; #define PG8_BAR __builtin_amdgcn_s_barrier()
; template <class Epi, class Sched, bool ALIGN_EPI = false, bool SP2 = false>
; __device__ __forceinline__ void gemm_phase(PG8_LAS unsigned char* lds, const Gemm g, const Sched& S, const Epi& E, int wave_s) {
;     ...
;         const bool has_next = S.next(ui + 1, nxt);
;         const char* nA = has_next ? (const char*)g.A + (size_t)nxt.pm * tstepA + (size_t)(nxt.pn / g.npg) * (size_t)(K * 2) : cA; const char* nB = has_next ? (const char*)g.Bt + (size_t)nxt.pn * tstepB : cB;
;         for (int t = 0; t < nt; t += 2) {
;             const bool last = (t == nt - 2);
;             const char* a1 = cA + (size_t)(t + 1) * kstep;
;             const char* a2 = last ? nA : cA + (size_t)(t + 2) * kstep; const char* b2 = last ? nB : cB + (size_t)(t + 2) * kstep;
;             const char* a3 = a2 + kstep; const char* b3 = b2 + kstep;
;             if (last && has_next) S.a_ready(nxt);
;             if constexpr (SP2) {
;             PG8_LDB(B0, 0, 0); PG8_LDB(B1, 0, 1); PG8_SCHED; PG8_LDA(At, 0, 0); PG8_STAGE(PG8_SA(1, 1), a1 + hstepA, voffA);
;             PG8_WAIT_V(8); PG8_WAIT_L(0); PG8_BAR; PG8_MMA(0, 0, At, B0); PG8_MMA(0, 1, At, B1); PG8_BAR; PG8_SCHED;
;             PG8_LDA(At, 0, 1); PG8_STAGE(PG8_SB(0, 0), b2, voffB); PG8_STAGE(PG8_SB(0, 1), b2 + hstepB, voffB); PG8_STAGE(PG8_SA(0, 0), a2, voffA);
;             PG8_WAIT_V(8); PG8_WAIT_L(0); PG8_BAR; PG8_MMA(1, 0, At, B0); PG8_MMA(1, 1, At, B1); PG8_BAR; PG8_SCHED;
.LBB0_313:
	s_ashr_i32 s29, s28, 31
	s_lshl_b64 s[2:3], s[28:29], 18
	s_add_u32 s96, s22, s2
	s_addc_u32 s97, s23, s3
	s_and_b64 s[2:3], s[4:5], exec
	s_cselect_b32 s2, s97, s31
	s_cselect_b32 s3, s96, s30
	s_add_u32 s4, s40, 0x80080
	s_addc_u32 s5, s41, 0
	s_add_u32 s29, s30, 0x100
	s_addc_u32 s81, s31, 0
	s_mov_b32 s84, -2
	s_add_u32 s30, s4, 0xfff80080
	s_addc_u32 s31, s5, -1
	s_add_i32 s85, 0, 0x10000
	s_cmp_eq_u32 s84, 4
	s_cselect_b32 s41, s91, s31
	s_cselect_b32 s40, s90, s30
	s_cselect_b32 s31, s2, s81
	s_cselect_b32 s30, s3, s29
	s_add_i32 s89, 0, 0x14000
	v_add_u32_e32 v118, s85, v229
	v_add_u32_e32 v150, s89, v229
	ds_read_b128 v[106:109], v118
	ds_read_b128 v[110:113], v118 offset:1024
	ds_read_b128 v[114:117], v118 offset:2048
	ds_read_b128 v[118:121], v118 offset:3072
	ds_read_b128 v[122:125], v150
	ds_read_b128 v[126:129], v150 offset:1024
	ds_read_b128 v[142:145], v150 offset:2048
	ds_read_b128 v[150:153], v150 offset:3072
	v_lshl_add_u64 v[194:195], s[4:5], 0, v[218:219]
	s_add_i32 m0, s35, 0xc000
	ds_read_b128 v[162:165], v230
	ds_read_b128 v[166:169], v230 offset:1024
	ds_read_b128 v[170:173], v230 offset:2048
	ds_read_b128 v[174:177], v230 offset:3072
	ds_read_b128 v[178:181], v230 offset:4096
	ds_read_b128 v[182:185], v230 offset:5120
	ds_read_b128 v[186:189], v230 offset:6144
	ds_read_b128 v[190:193], v230 offset:7168
	global_load_lds_dwordx4 v[194:195], off
	v_lshl_add_u64 v[194:195], s[4:5], 0, v[220:221]
	s_add_i32 m0, s35, 0xe000
	s_nop 0
	global_load_lds_dwordx4 v[194:195], off
	s_waitcnt vmcnt(8)
	s_waitcnt lgkmcnt(0)
	s_barrier
	s_waitcnt lgkmcnt(0)
	v_mfma_f32_16x16x32_bf16 v[158:161], v[106:109], v[162:165], 0
	v_mfma_f32_16x16x32_bf16 v[154:157], v[114:117], v[162:165], 0
	v_mfma_f32_16x16x32_bf16 v[134:137], v[106:109], v[170:173], 0
	v_mfma_f32_16x16x32_bf16 v[130:133], v[114:117], v[170:173], 0
	v_mfma_f32_16x16x32_bf16 v[94:97], v[106:109], v[178:181], 0
	v_mfma_f32_16x16x32_bf16 v[90:93], v[114:117], v[178:181], 0
	v_mfma_f32_16x16x32_bf16 v[78:81], v[106:109], v[186:189], 0
	v_mfma_f32_16x16x32_bf16 v[74:77], v[114:117], v[186:189], 0
	v_mfma_f32_16x16x32_bf16 v[158:161], v[110:113], v[166:169], v[158:161]
	v_mfma_f32_16x16x32_bf16 v[154:157], v[118:121], v[166:169], v[154:157]
	v_mfma_f32_16x16x32_bf16 v[134:137], v[110:113], v[174:177], v[134:137]
	v_mfma_f32_16x16x32_bf16 v[130:133], v[118:121], v[174:177], v[130:133]
	v_mfma_f32_16x16x32_bf16 v[94:97], v[110:113], v[182:185], v[94:97]
	v_mfma_f32_16x16x32_bf16 v[90:93], v[118:121], v[182:185], v[90:93]
	v_mfma_f32_16x16x32_bf16 v[78:81], v[110:113], v[190:193], v[78:81]
	v_mfma_f32_16x16x32_bf16 v[74:77], v[118:121], v[190:193], v[74:77]
	v_mfma_f32_16x16x32_bf16 v[146:149], v[122:125], v[162:165], 0
	v_mfma_f32_16x16x32_bf16 v[138:141], v[142:145], v[162:165], 0
	v_mfma_f32_16x16x32_bf16 v[102:105], v[122:125], v[170:173], 0
	v_mfma_f32_16x16x32_bf16 v[98:101], v[142:145], v[170:173], 0
	v_mfma_f32_16x16x32_bf16 v[86:89], v[122:125], v[178:181], 0
	v_mfma_f32_16x16x32_bf16 v[82:85], v[142:145], v[178:181], 0
	v_mfma_f32_16x16x32_bf16 v[70:73], v[122:125], v[186:189], 0
	v_mfma_f32_16x16x32_bf16 v[66:69], v[142:145], v[186:189], 0
	v_mfma_f32_16x16x32_bf16 v[146:149], v[126:129], v[166:169], v[146:149]
	v_mfma_f32_16x16x32_bf16 v[138:141], v[150:153], v[166:169], v[138:141]
	v_mfma_f32_16x16x32_bf16 v[102:105], v[126:129], v[174:177], v[102:105]
	v_mfma_f32_16x16x32_bf16 v[98:101], v[150:153], v[174:177], v[98:101]
	v_mfma_f32_16x16x32_bf16 v[86:89], v[126:129], v[182:185], v[86:89]
	v_mfma_f32_16x16x32_bf16 v[82:85], v[150:153], v[182:185], v[82:85]
	v_mfma_f32_16x16x32_bf16 v[70:73], v[126:129], v[190:193], v[70:73]
	v_mfma_f32_16x16x32_bf16 v[66:69], v[150:153], v[190:193], v[66:69]
	s_barrier
	s_add_i32 s85, s85, s34
	v_lshl_add_u64 v[194:195], s[30:31], 0, v[214:215]
	s_mov_b32 m0, s85
	ds_read_b128 v[162:165], v230 offset:16384
	ds_read_b128 v[166:169], v230 offset:17408
	ds_read_b128 v[170:173], v230 offset:18432
	ds_read_b128 v[174:177], v230 offset:19456
	ds_read_b128 v[178:181], v230 offset:20480
	ds_read_b128 v[182:185], v230 offset:21504
	ds_read_b128 v[186:189], v230 offset:22528
	ds_read_b128 v[190:193], v230 offset:23552
	global_load_lds_dwordx4 v[194:195], off
	s_add_i32 m0, s85, 0x2000
	s_add_u32 s94, s30, 0x20000
	v_lshl_add_u64 v[196:197], s[30:31], 0, v[210:211]
	s_addc_u32 s95, s31, 0
	s_add_i32 s85, s89, s34
	global_load_lds_dwordx4 v[196:197], off
	v_lshl_add_u64 v[198:199], s[94:95], 0, v[214:215]
	s_mov_b32 m0, s85
	v_lshl_add_u64 v[200:201], s[40:41], 0, v[212:213]
	global_load_lds_dwordx4 v[198:199], off
	v_lshl_add_u64 v[198:199], s[94:95], 0, v[210:211]
	s_add_i32 m0, s85, 0x2000
	s_nop 0
	global_load_lds_dwordx4 v[198:199], off
	v_lshl_add_u64 v[198:199], s[40:41], 0, v[216:217]
	s_mov_b32 m0, s35
	s_nop 0
	global_load_lds_dwordx4 v[198:199], off
	s_mov_b32 m0, s36
	s_nop 0
	global_load_lds_dwordx4 v[200:201], off
	s_waitcnt vmcnt(8)
	s_waitcnt lgkmcnt(0)
	s_barrier
; #define PG8_STAGE(bufoff, gbase, voff) do { _Pragma("unroll") for (int _i = 0; _i < 2; ++_i) \
;         __builtin_amdgcn_global_load_lds((const unsigned*)((const char*)(gbase) + (voff)[_i]), (PG8_LAS unsigned*)(lds + (bufoff) + ldsw + _i * 8192), 16, 0, 0); } while (0)
; #define PG8_LDA(dst, b, h) do { _Pragma("unroll") for (int m = 0; m < 4; ++m) _Pragma("unroll") for (int k = 0; k < 2; ++k) dst[m][k] = *(const PG8_LAS bf16x8*)(lds + PG8_SA(b, h) + aoff + m * 2048 + k * 1024); } while (0)
; #define PG8_LDB(dst, b, h) do { _Pragma("unroll") for (int n = 0; n < 2; ++n) _Pragma("unroll") for (int k = 0; k < 2; ++k) dst[n][k] = *(const PG8_LAS bf16x8*)(lds + PG8_SB(b, h) + boff + n * 2048 + k * 1024); } while (0)
; #define PG8_MMA(ai, bj, At, Bt) do { __builtin_amdgcn_s_setprio(1); _Pragma("unroll") for (int m = 0; m < 4; ++m) _Pragma("unroll") for (int n = 0; n < 2; ++n) _Pragma("unroll") for (int k = 0; k < 2; ++k) \
;         acc[ai][bj][m][n] = __builtin_amdgcn_mfma_f32_16x16x32_bf16(Bt[n][k], At[m][k], acc[ai][bj][m][n], 0, 0, 0); __builtin_amdgcn_s_setprio(0); } while (0)
; #define PG8_WAIT_V(n) asm volatile("s_waitcnt vmcnt(" #n ")" ::: "memory")
; #define PG8_WAIT_L(n) asm volatile("s_waitcnt lgkmcnt(" #n ")" ::: "memory")
; #define PG8_BAR __builtin_amdgcn_s_barrier()
; #define PG8_SCHED __builtin_amdgcn_sched_barrier(0)
; template <class Epi, class Sched, bool ALIGN_EPI = false, bool SP2 = false>
; __device__ __forceinline__ void gemm_phase(PG8_LAS unsigned char* lds, const Gemm g, const Sched& S, const Epi& E, int wave_s) {
;     ...
;             PG8_WAIT_V(8); PG8_WAIT_L(0); PG8_BAR; PG8_MMA(1, 0, At, B0); PG8_MMA(1, 1, At, B1); PG8_BAR; PG8_SCHED;
;             PG8_LDB(B0, 1, 0); PG8_LDB(B1, 1, 1); PG8_SCHED; PG8_LDA(At, 1, 0); PG8_STAGE(PG8_SA(0, 1), a2 + hstepA, voffA);
;             PG8_WAIT_V(8); PG8_WAIT_L(0); PG8_BAR; PG8_MMA(0, 0, At, B0); PG8_MMA(0, 1, At, B1); PG8_BAR; PG8_SCHED;
;             PG8_LDA(At, 1, 1); PG8_STAGE(PG8_SB(1, 0), b3, voffB); PG8_STAGE(PG8_SB(1, 1), b3 + hstepB, voffB); PG8_STAGE(PG8_SA(1, 0), a3, voffA);
	s_waitcnt lgkmcnt(0)
	v_mfma_f32_16x16x32_bf16 v[62:65], v[106:109], v[162:165], 0
	v_mfma_f32_16x16x32_bf16 v[58:61], v[114:117], v[162:165], 0
	v_mfma_f32_16x16x32_bf16 v[46:49], v[106:109], v[170:173], 0
	v_mfma_f32_16x16x32_bf16 v[42:45], v[114:117], v[170:173], 0
	v_mfma_f32_16x16x32_bf16 v[30:33], v[106:109], v[178:181], 0
	v_mfma_f32_16x16x32_bf16 v[26:29], v[114:117], v[178:181], 0
	v_mfma_f32_16x16x32_bf16 v[14:17], v[106:109], v[186:189], 0
	v_mfma_f32_16x16x32_bf16 v[10:13], v[114:117], v[186:189], 0
	v_mfma_f32_16x16x32_bf16 v[62:65], v[110:113], v[166:169], v[62:65]
	v_mfma_f32_16x16x32_bf16 v[58:61], v[118:121], v[166:169], v[58:61]
	v_mfma_f32_16x16x32_bf16 v[46:49], v[110:113], v[174:177], v[46:49]
	v_mfma_f32_16x16x32_bf16 v[42:45], v[118:121], v[174:177], v[42:45]
	v_mfma_f32_16x16x32_bf16 v[30:33], v[110:113], v[182:185], v[30:33]
	v_mfma_f32_16x16x32_bf16 v[26:29], v[118:121], v[182:185], v[26:29]
	v_mfma_f32_16x16x32_bf16 v[14:17], v[110:113], v[190:193], v[14:17]
	v_mfma_f32_16x16x32_bf16 v[10:13], v[118:121], v[190:193], v[10:13]
	v_mfma_f32_16x16x32_bf16 v[54:57], v[122:125], v[162:165], 0
	v_mfma_f32_16x16x32_bf16 v[50:53], v[142:145], v[162:165], 0
	v_mfma_f32_16x16x32_bf16 v[38:41], v[122:125], v[170:173], 0
	v_mfma_f32_16x16x32_bf16 v[34:37], v[142:145], v[170:173], 0
	v_mfma_f32_16x16x32_bf16 v[22:25], v[122:125], v[178:181], 0
	v_mfma_f32_16x16x32_bf16 v[18:21], v[142:145], v[178:181], 0
	v_mfma_f32_16x16x32_bf16 v[6:9], v[122:125], v[186:189], 0
	v_mfma_f32_16x16x32_bf16 v[2:5], v[142:145], v[186:189], 0
	v_mfma_f32_16x16x32_bf16 v[54:57], v[126:129], v[166:169], v[54:57]
	v_mfma_f32_16x16x32_bf16 v[50:53], v[150:153], v[166:169], v[50:53]
	v_mfma_f32_16x16x32_bf16 v[38:41], v[126:129], v[174:177], v[38:41]
	v_mfma_f32_16x16x32_bf16 v[34:37], v[150:153], v[174:177], v[34:37]
	v_mfma_f32_16x16x32_bf16 v[22:25], v[126:129], v[182:185], v[22:25]
	v_mfma_f32_16x16x32_bf16 v[18:21], v[150:153], v[182:185], v[18:21]
	v_mfma_f32_16x16x32_bf16 v[6:9], v[126:129], v[190:193], v[6:9]
	v_mfma_f32_16x16x32_bf16 v[2:5], v[150:153], v[190:193], v[2:5]
	s_barrier
	s_add_i32 s85, 0, 0x18000
	s_add_i32 s89, 0, 0x1c000
	v_add_u32_e32 v118, s85, v229
	v_add_u32_e32 v150, s89, v229
	ds_read_b128 v[106:109], v118
	ds_read_b128 v[110:113], v118 offset:1024
	ds_read_b128 v[114:117], v118 offset:2048
	ds_read_b128 v[118:121], v118 offset:3072
	ds_read_b128 v[122:125], v150
	ds_read_b128 v[126:129], v150 offset:1024
	ds_read_b128 v[142:145], v150 offset:2048
	ds_read_b128 v[150:153], v150 offset:3072
	s_add_u32 s40, s40, 0x80000
	s_addc_u32 s41, s41, 0
	s_mov_b32 m0, s37
	v_lshl_add_u64 v[202:203], s[40:41], 0, v[216:217]
	ds_read_b128 v[162:165], v230 offset:32768
	ds_read_b128 v[166:169], v230 offset:33792
	ds_read_b128 v[170:173], v230 offset:34816
	ds_read_b128 v[174:177], v230 offset:35840
	ds_read_b128 v[178:181], v230 offset:36864
	ds_read_b128 v[182:185], v230 offset:37888
	ds_read_b128 v[186:189], v230 offset:38912
	ds_read_b128 v[190:193], v230 offset:39936
	global_load_lds_dwordx4 v[202:203], off
	v_lshl_add_u64 v[202:203], s[40:41], 0, v[212:213]
	s_mov_b32 m0, s42
	s_nop 0
	global_load_lds_dwordx4 v[202:203], off
	s_waitcnt vmcnt(8)
	s_waitcnt lgkmcnt(0)
	s_barrier
	s_waitcnt lgkmcnt(0)
	v_mfma_f32_16x16x32_bf16 v[158:161], v[106:109], v[162:165], v[158:161]
	v_mfma_f32_16x16x32_bf16 v[154:157], v[114:117], v[162:165], v[154:157]
	v_mfma_f32_16x16x32_bf16 v[134:137], v[106:109], v[170:173], v[134:137]
	v_mfma_f32_16x16x32_bf16 v[130:133], v[114:117], v[170:173], v[130:133]
	v_mfma_f32_16x16x32_bf16 v[94:97], v[106:109], v[178:181], v[94:97]
	v_mfma_f32_16x16x32_bf16 v[90:93], v[114:117], v[178:181], v[90:93]
	v_mfma_f32_16x16x32_bf16 v[78:81], v[106:109], v[186:189], v[78:81]
	v_mfma_f32_16x16x32_bf16 v[74:77], v[114:117], v[186:189], v[74:77]
	v_mfma_f32_16x16x32_bf16 v[158:161], v[110:113], v[166:169], v[158:161]
	v_mfma_f32_16x16x32_bf16 v[154:157], v[118:121], v[166:169], v[154:157]
	v_mfma_f32_16x16x32_bf16 v[134:137], v[110:113], v[174:177], v[134:137]
	v_mfma_f32_16x16x32_bf16 v[130:133], v[118:121], v[174:177], v[130:133]
	v_mfma_f32_16x16x32_bf16 v[94:97], v[110:113], v[182:185], v[94:97]
	v_mfma_f32_16x16x32_bf16 v[90:93], v[118:121], v[182:185], v[90:93]
	v_mfma_f32_16x16x32_bf16 v[78:81], v[110:113], v[190:193], v[78:81]
	v_mfma_f32_16x16x32_bf16 v[74:77], v[118:121], v[190:193], v[74:77]
	v_mfma_f32_16x16x32_bf16 v[146:149], v[122:125], v[162:165], v[146:149]
	v_mfma_f32_16x16x32_bf16 v[138:141], v[142:145], v[162:165], v[138:141]
	v_mfma_f32_16x16x32_bf16 v[102:105], v[122:125], v[170:173], v[102:105]
	v_mfma_f32_16x16x32_bf16 v[98:101], v[142:145], v[170:173], v[98:101]
	v_mfma_f32_16x16x32_bf16 v[86:89], v[122:125], v[178:181], v[86:89]
	v_mfma_f32_16x16x32_bf16 v[82:85], v[142:145], v[178:181], v[82:85]
	v_mfma_f32_16x16x32_bf16 v[70:73], v[122:125], v[186:189], v[70:73]
	v_mfma_f32_16x16x32_bf16 v[66:69], v[142:145], v[186:189], v[66:69]
	v_mfma_f32_16x16x32_bf16 v[146:149], v[126:129], v[166:169], v[146:149]
	v_mfma_f32_16x16x32_bf16 v[138:141], v[150:153], v[166:169], v[138:141]
	v_mfma_f32_16x16x32_bf16 v[102:105], v[126:129], v[174:177], v[102:105]
	v_mfma_f32_16x16x32_bf16 v[98:101], v[150:153], v[174:177], v[98:101]
	v_mfma_f32_16x16x32_bf16 v[86:89], v[126:129], v[182:185], v[86:89]
	v_mfma_f32_16x16x32_bf16 v[82:85], v[150:153], v[182:185], v[82:85]
	v_mfma_f32_16x16x32_bf16 v[70:73], v[126:129], v[190:193], v[70:73]
	v_mfma_f32_16x16x32_bf16 v[66:69], v[150:153], v[190:193], v[66:69]
	s_barrier
; #define PG8_STAGE(bufoff, gbase, voff) do { _Pragma("unroll") for (int _i = 0; _i < 2; ++_i) \
;         __builtin_amdgcn_global_load_lds((const unsigned*)((const char*)(gbase) + (voff)[_i]), (PG8_LAS unsigned*)(lds + (bufoff) + ldsw + _i * 8192), 16, 0, 0); } while (0)
; #define PG8_LDA(dst, b, h) do { _Pragma("unroll") for (int m = 0; m < 4; ++m) _Pragma("unroll") for (int k = 0; k < 2; ++k) dst[m][k] = *(const PG8_LAS bf16x8*)(lds + PG8_SA(b, h) + aoff + m * 2048 + k * 1024); } while (0)
; #define PG8_WAIT_V(n) asm volatile("s_waitcnt vmcnt(" #n ")" ::: "memory")
; #define PG8_WAIT_L(n) asm volatile("s_waitcnt lgkmcnt(" #n ")" ::: "memory")
; #define PG8_BAR __builtin_amdgcn_s_barrier()
; template <class Epi, class Sched, bool ALIGN_EPI = false, bool SP2 = false>
; __device__ __forceinline__ void gemm_phase(PG8_LAS unsigned char* lds, const Gemm g, const Sched& S, const Epi& E, int wave_s) {
;     ...
;         for (int t = 0; t < nt; t += 2) {
;             const bool last = (t == nt - 2);
;             const char* a1 = cA + (size_t)(t + 1) * kstep;
;             const char* a2 = last ? nA : cA + (size_t)(t + 2) * kstep; const char* b2 = last ? nB : cB + (size_t)(t + 2) * kstep;
;             const char* a3 = a2 + kstep; const char* b3 = b2 + kstep;
;             if (last && has_next) S.a_ready(nxt);
;             if constexpr (SP2) {
;             PG8_LDB(B0, 0, 0); PG8_LDB(B1, 0, 1); PG8_SCHED; PG8_LDA(At, 0, 0); PG8_STAGE(PG8_SA(1, 1), a1 + hstepA, voffA);
;             PG8_WAIT_V(8); PG8_WAIT_L(0); PG8_BAR; PG8_MMA(0, 0, At, B0); PG8_MMA(0, 1, At, B1); PG8_BAR; PG8_SCHED;
;             PG8_LDA(At, 0, 1); PG8_STAGE(PG8_SB(0, 0), b2, voffB); PG8_STAGE(PG8_SB(0, 1), b2 + hstepB, voffB); PG8_STAGE(PG8_SA(0, 0), a2, voffA);
;             PG8_WAIT_V(8); PG8_WAIT_L(0); PG8_BAR; PG8_MMA(1, 0, At, B0); PG8_MMA(1, 1, At, B1); PG8_BAR; PG8_SCHED;
;             PG8_LDB(B0, 1, 0); PG8_LDB(B1, 1, 1); PG8_SCHED; PG8_LDA(At, 1, 0); PG8_STAGE(PG8_SA(0, 1), a2 + hstepA, voffA);
;             PG8_WAIT_V(8); PG8_WAIT_L(0); PG8_BAR; PG8_MMA(0, 0, At, B0); PG8_MMA(0, 1, At, B1); PG8_BAR; PG8_SCHED;
;             PG8_LDA(At, 1, 1); PG8_STAGE(PG8_SB(1, 0), b3, voffB); PG8_STAGE(PG8_SB(1, 1), b3 + hstepB, voffB); PG8_STAGE(PG8_SA(1, 0), a3, voffA);
;             PG8_WAIT_V(8); PG8_WAIT_L(0); PG8_BAR; PG8_MMA(1, 0, At, B0); PG8_MMA(1, 1, At, B1); PG8_BAR; PG8_SCHED;
	s_add_i32 s40, s85, s34
	v_lshl_add_u64 v[194:195], v[194:195], 0, s[60:61]
	s_mov_b32 m0, s40
	ds_read_b128 v[162:165], v230 offset:49152
	ds_read_b128 v[166:169], v230 offset:50176
	ds_read_b128 v[170:173], v230 offset:51200
	ds_read_b128 v[174:177], v230 offset:52224
	ds_read_b128 v[178:181], v230 offset:53248
	ds_read_b128 v[182:185], v230 offset:54272
	ds_read_b128 v[186:189], v230 offset:55296
	ds_read_b128 v[190:193], v230 offset:56320
	global_load_lds_dwordx4 v[194:195], off
	s_add_i32 m0, s40, 0x2000
	s_add_u32 s30, s30, 0x20080
	v_lshl_add_u64 v[194:195], v[196:197], 0, s[60:61]
	s_addc_u32 s31, s31, 0
	s_add_i32 s40, s89, s34
	global_load_lds_dwordx4 v[194:195], off
	v_lshl_add_u64 v[194:195], s[30:31], 0, v[214:215]
	s_mov_b32 m0, s40
	s_nop 0
	global_load_lds_dwordx4 v[194:195], off
	v_lshl_add_u64 v[194:195], s[30:31], 0, v[210:211]
	s_add_i32 m0, s40, 0x2000
	s_nop 0
	global_load_lds_dwordx4 v[194:195], off
	v_lshl_add_u64 v[194:195], v[198:199], 0, s[60:61]
	s_mov_b32 m0, s46
	s_nop 0
	global_load_lds_dwordx4 v[194:195], off
	v_lshl_add_u64 v[194:195], v[200:201], 0, s[60:61]
	s_mov_b32 m0, s47
	s_nop 0
	global_load_lds_dwordx4 v[194:195], off
	s_waitcnt vmcnt(8)
	s_waitcnt lgkmcnt(0)
	s_barrier
	s_waitcnt lgkmcnt(0)
	v_mfma_f32_16x16x32_bf16 v[62:65], v[106:109], v[162:165], v[62:65]
	v_mfma_f32_16x16x32_bf16 v[58:61], v[114:117], v[162:165], v[58:61]
	v_mfma_f32_16x16x32_bf16 v[46:49], v[106:109], v[170:173], v[46:49]
	v_mfma_f32_16x16x32_bf16 v[42:45], v[114:117], v[170:173], v[42:45]
	v_mfma_f32_16x16x32_bf16 v[30:33], v[106:109], v[178:181], v[30:33]
	v_mfma_f32_16x16x32_bf16 v[26:29], v[114:117], v[178:181], v[26:29]
	v_mfma_f32_16x16x32_bf16 v[14:17], v[106:109], v[186:189], v[14:17]
	v_mfma_f32_16x16x32_bf16 v[10:13], v[114:117], v[186:189], v[10:13]
	v_mfma_f32_16x16x32_bf16 v[62:65], v[110:113], v[166:169], v[62:65]
	v_mfma_f32_16x16x32_bf16 v[58:61], v[118:121], v[166:169], v[58:61]
	v_mfma_f32_16x16x32_bf16 v[46:49], v[110:113], v[174:177], v[46:49]
	v_mfma_f32_16x16x32_bf16 v[42:45], v[118:121], v[174:177], v[42:45]
	v_mfma_f32_16x16x32_bf16 v[30:33], v[110:113], v[182:185], v[30:33]
	v_mfma_f32_16x16x32_bf16 v[26:29], v[118:121], v[182:185], v[26:29]
	v_mfma_f32_16x16x32_bf16 v[14:17], v[110:113], v[190:193], v[14:17]
	v_mfma_f32_16x16x32_bf16 v[10:13], v[118:121], v[190:193], v[10:13]
	v_mfma_f32_16x16x32_bf16 v[54:57], v[122:125], v[162:165], v[54:57]
	v_mfma_f32_16x16x32_bf16 v[50:53], v[142:145], v[162:165], v[50:53]
	v_mfma_f32_16x16x32_bf16 v[38:41], v[122:125], v[170:173], v[38:41]
	v_mfma_f32_16x16x32_bf16 v[34:37], v[142:145], v[170:173], v[34:37]
	v_mfma_f32_16x16x32_bf16 v[22:25], v[122:125], v[178:181], v[22:25]
	v_mfma_f32_16x16x32_bf16 v[18:21], v[142:145], v[178:181], v[18:21]
	v_mfma_f32_16x16x32_bf16 v[6:9], v[122:125], v[186:189], v[6:9]
	v_mfma_f32_16x16x32_bf16 v[2:5], v[142:145], v[186:189], v[2:5]
	v_mfma_f32_16x16x32_bf16 v[54:57], v[126:129], v[166:169], v[54:57]
	v_mfma_f32_16x16x32_bf16 v[50:53], v[150:153], v[166:169], v[50:53]
	v_mfma_f32_16x16x32_bf16 v[38:41], v[126:129], v[174:177], v[38:41]
	v_mfma_f32_16x16x32_bf16 v[34:37], v[150:153], v[174:177], v[34:37]
	v_mfma_f32_16x16x32_bf16 v[22:25], v[126:129], v[182:185], v[22:25]
	v_mfma_f32_16x16x32_bf16 v[18:21], v[150:153], v[182:185], v[18:21]
	v_mfma_f32_16x16x32_bf16 v[6:9], v[126:129], v[190:193], v[6:9]
	v_mfma_f32_16x16x32_bf16 v[2:5], v[150:153], v[190:193], v[2:5]
	s_add_i32 s84, s84, 2
	s_add_u32 s4, s4, 0x100
	s_addc_u32 s5, s5, 0
	s_add_u32 s29, s29, 0x100
	s_addc_u32 s81, s81, 0
	s_add_u32 s30, s4, 0xfff80080
	s_addc_u32 s31, s5, -1
	s_add_i32 s85, 0, 0x10000
	s_cmp_eq_u32 s84, 4
	s_cselect_b32 s41, s91, s31
	s_cselect_b32 s40, s90, s30
	s_cselect_b32 s31, s2, s81
	s_cselect_b32 s30, s3, s29
	s_add_i32 s89, 0, 0x14000
	s_cmp_gt_u32 s84, 5
	s_barrier
.LBB0_314:
	v_add_u32_e32 v118, s85, v229
	v_add_u32_e32 v150, s89, v229
	ds_read_b128 v[106:109], v118
	ds_read_b128 v[110:113], v118 offset:1024
	ds_read_b128 v[114:117], v118 offset:2048
	ds_read_b128 v[118:121], v118 offset:3072
	ds_read_b128 v[122:125], v150
	ds_read_b128 v[126:129], v150 offset:1024
	ds_read_b128 v[142:145], v150 offset:2048
	ds_read_b128 v[150:153], v150 offset:3072
	v_lshl_add_u64 v[194:195], s[4:5], 0, v[218:219]
	s_add_i32 m0, s35, 0xc000
	ds_read_b128 v[162:165], v230
	ds_read_b128 v[166:169], v230 offset:1024
	ds_read_b128 v[170:173], v230 offset:2048
	ds_read_b128 v[174:177], v230 offset:3072
	ds_read_b128 v[178:181], v230 offset:4096
	ds_read_b128 v[182:185], v230 offset:5120
	ds_read_b128 v[186:189], v230 offset:6144
	ds_read_b128 v[190:193], v230 offset:7168
	global_load_lds_dwordx4 v[194:195], off
	v_lshl_add_u64 v[194:195], s[4:5], 0, v[220:221]
	s_add_i32 m0, s35, 0xe000
	s_nop 0
	global_load_lds_dwordx4 v[194:195], off
	s_waitcnt vmcnt(8)
	s_waitcnt lgkmcnt(0)
	s_barrier
; #define PG8_STAGE(bufoff, gbase, voff) do { _Pragma("unroll") for (int _i = 0; _i < 2; ++_i) \
;         __builtin_amdgcn_global_load_lds((const unsigned*)((const char*)(gbase) + (voff)[_i]), (PG8_LAS unsigned*)(lds + (bufoff) + ldsw + _i * 8192), 16, 0, 0); } while (0)
; #define PG8_LDA(dst, b, h) do { _Pragma("unroll") for (int m = 0; m < 4; ++m) _Pragma("unroll") for (int k = 0; k < 2; ++k) dst[m][k] = *(const PG8_LAS bf16x8*)(lds + PG8_SA(b, h) + aoff + m * 2048 + k * 1024); } while (0)
; #define PG8_LDB(dst, b, h) do { _Pragma("unroll") for (int n = 0; n < 2; ++n) _Pragma("unroll") for (int k = 0; k < 2; ++k) dst[n][k] = *(const PG8_LAS bf16x8*)(lds + PG8_SB(b, h) + boff + n * 2048 + k * 1024); } while (0)
; #define PG8_MMA(ai, bj, At, Bt) do { __builtin_amdgcn_s_setprio(1); _Pragma("unroll") for (int m = 0; m < 4; ++m) _Pragma("unroll") for (int n = 0; n < 2; ++n) _Pragma("unroll") for (int k = 0; k < 2; ++k) \
;         acc[ai][bj][m][n] = __builtin_amdgcn_mfma_f32_16x16x32_bf16(Bt[n][k], At[m][k], acc[ai][bj][m][n], 0, 0, 0); __builtin_amdgcn_s_setprio(0); } while (0)
; #define PG8_WAIT_V(n) asm volatile("s_waitcnt vmcnt(" #n ")" ::: "memory")
; #define PG8_WAIT_L(n) asm volatile("s_waitcnt lgkmcnt(" #n ")" ::: "memory")
; #define PG8_BAR __builtin_amdgcn_s_barrier()
; #define PG8_SCHED __builtin_amdgcn_sched_barrier(0)
; template <class Epi, class Sched, bool ALIGN_EPI = false, bool SP2 = false>
; __device__ __forceinline__ void gemm_phase(PG8_LAS unsigned char* lds, const Gemm g, const Sched& S, const Epi& E, int wave_s) {
;     ...
;             PG8_WAIT_V(8); PG8_WAIT_L(0); PG8_BAR; PG8_MMA(0, 0, At, B0); PG8_MMA(0, 1, At, B1); PG8_BAR; PG8_SCHED;
;             PG8_LDA(At, 0, 1); PG8_STAGE(PG8_SB(0, 0), b2, voffB); PG8_STAGE(PG8_SB(0, 1), b2 + hstepB, voffB); PG8_STAGE(PG8_SA(0, 0), a2, voffA);
;             PG8_WAIT_V(8); PG8_WAIT_L(0); PG8_BAR; PG8_MMA(1, 0, At, B0); PG8_MMA(1, 1, At, B1); PG8_BAR; PG8_SCHED;
;             PG8_LDB(B0, 1, 0); PG8_LDB(B1, 1, 1); PG8_SCHED; PG8_LDA(At, 1, 0); PG8_STAGE(PG8_SA(0, 1), a2 + hstepA, voffA);
;             PG8_WAIT_V(8); PG8_WAIT_L(0); PG8_BAR; PG8_MMA(0, 0, At, B0); PG8_MMA(0, 1, At, B1); PG8_BAR; PG8_SCHED;
	s_waitcnt lgkmcnt(0)
	v_mfma_f32_16x16x32_bf16 v[158:161], v[106:109], v[162:165], v[158:161]
	v_mfma_f32_16x16x32_bf16 v[154:157], v[114:117], v[162:165], v[154:157]
	v_mfma_f32_16x16x32_bf16 v[134:137], v[106:109], v[170:173], v[134:137]
	v_mfma_f32_16x16x32_bf16 v[130:133], v[114:117], v[170:173], v[130:133]
	v_mfma_f32_16x16x32_bf16 v[94:97], v[106:109], v[178:181], v[94:97]
	v_mfma_f32_16x16x32_bf16 v[90:93], v[114:117], v[178:181], v[90:93]
	v_mfma_f32_16x16x32_bf16 v[78:81], v[106:109], v[186:189], v[78:81]
	v_mfma_f32_16x16x32_bf16 v[74:77], v[114:117], v[186:189], v[74:77]
	v_mfma_f32_16x16x32_bf16 v[158:161], v[110:113], v[166:169], v[158:161]
	v_mfma_f32_16x16x32_bf16 v[154:157], v[118:121], v[166:169], v[154:157]
	v_mfma_f32_16x16x32_bf16 v[134:137], v[110:113], v[174:177], v[134:137]
	v_mfma_f32_16x16x32_bf16 v[130:133], v[118:121], v[174:177], v[130:133]
	v_mfma_f32_16x16x32_bf16 v[94:97], v[110:113], v[182:185], v[94:97]
	v_mfma_f32_16x16x32_bf16 v[90:93], v[118:121], v[182:185], v[90:93]
	v_mfma_f32_16x16x32_bf16 v[78:81], v[110:113], v[190:193], v[78:81]
	v_mfma_f32_16x16x32_bf16 v[74:77], v[118:121], v[190:193], v[74:77]
	v_mfma_f32_16x16x32_bf16 v[146:149], v[122:125], v[162:165], v[146:149]
	v_mfma_f32_16x16x32_bf16 v[138:141], v[142:145], v[162:165], v[138:141]
	v_mfma_f32_16x16x32_bf16 v[102:105], v[122:125], v[170:173], v[102:105]
	v_mfma_f32_16x16x32_bf16 v[98:101], v[142:145], v[170:173], v[98:101]
	v_mfma_f32_16x16x32_bf16 v[86:89], v[122:125], v[178:181], v[86:89]
	v_mfma_f32_16x16x32_bf16 v[82:85], v[142:145], v[178:181], v[82:85]
	v_mfma_f32_16x16x32_bf16 v[70:73], v[122:125], v[186:189], v[70:73]
	v_mfma_f32_16x16x32_bf16 v[66:69], v[142:145], v[186:189], v[66:69]
	v_mfma_f32_16x16x32_bf16 v[146:149], v[126:129], v[166:169], v[146:149]
	v_mfma_f32_16x16x32_bf16 v[138:141], v[150:153], v[166:169], v[138:141]
	v_mfma_f32_16x16x32_bf16 v[102:105], v[126:129], v[174:177], v[102:105]
	v_mfma_f32_16x16x32_bf16 v[98:101], v[150:153], v[174:177], v[98:101]
	v_mfma_f32_16x16x32_bf16 v[86:89], v[126:129], v[182:185], v[86:89]
	v_mfma_f32_16x16x32_bf16 v[82:85], v[150:153], v[182:185], v[82:85]
	v_mfma_f32_16x16x32_bf16 v[70:73], v[126:129], v[190:193], v[70:73]
	v_mfma_f32_16x16x32_bf16 v[66:69], v[150:153], v[190:193], v[66:69]
	s_barrier
	s_add_i32 s85, s85, s34
	v_lshl_add_u64 v[194:195], s[30:31], 0, v[214:215]
	s_mov_b32 m0, s85
	ds_read_b128 v[162:165], v230 offset:16384
	ds_read_b128 v[166:169], v230 offset:17408
	ds_read_b128 v[170:173], v230 offset:18432
	ds_read_b128 v[174:177], v230 offset:19456
	ds_read_b128 v[178:181], v230 offset:20480
	ds_read_b128 v[182:185], v230 offset:21504
	ds_read_b128 v[186:189], v230 offset:22528
	ds_read_b128 v[190:193], v230 offset:23552
	global_load_lds_dwordx4 v[194:195], off
	s_add_i32 m0, s85, 0x2000
	s_add_u32 s94, s30, 0x20000
	v_lshl_add_u64 v[196:197], s[30:31], 0, v[210:211]
	s_addc_u32 s95, s31, 0
	s_add_i32 s85, s89, s34
	global_load_lds_dwordx4 v[196:197], off
	v_lshl_add_u64 v[198:199], s[94:95], 0, v[214:215]
	s_mov_b32 m0, s85
	v_lshl_add_u64 v[200:201], s[40:41], 0, v[212:213]
	global_load_lds_dwordx4 v[198:199], off
	v_lshl_add_u64 v[198:199], s[94:95], 0, v[210:211]
	s_add_i32 m0, s85, 0x2000
	s_nop 0
	global_load_lds_dwordx4 v[198:199], off
	v_lshl_add_u64 v[198:199], s[40:41], 0, v[216:217]
	s_mov_b32 m0, s35
	s_nop 0
	global_load_lds_dwordx4 v[198:199], off
	s_mov_b32 m0, s36
	s_nop 0
	global_load_lds_dwordx4 v[200:201], off
	s_waitcnt vmcnt(8)
	s_waitcnt lgkmcnt(0)
	s_barrier
	s_waitcnt lgkmcnt(0)
	v_mfma_f32_16x16x32_bf16 v[62:65], v[106:109], v[162:165], v[62:65]
	v_mfma_f32_16x16x32_bf16 v[58:61], v[114:117], v[162:165], v[58:61]
	v_mfma_f32_16x16x32_bf16 v[46:49], v[106:109], v[170:173], v[46:49]
	v_mfma_f32_16x16x32_bf16 v[42:45], v[114:117], v[170:173], v[42:45]
	v_mfma_f32_16x16x32_bf16 v[30:33], v[106:109], v[178:181], v[30:33]
	v_mfma_f32_16x16x32_bf16 v[26:29], v[114:117], v[178:181], v[26:29]
	v_mfma_f32_16x16x32_bf16 v[14:17], v[106:109], v[186:189], v[14:17]
	v_mfma_f32_16x16x32_bf16 v[10:13], v[114:117], v[186:189], v[10:13]
	v_mfma_f32_16x16x32_bf16 v[62:65], v[110:113], v[166:169], v[62:65]
	v_mfma_f32_16x16x32_bf16 v[58:61], v[118:121], v[166:169], v[58:61]
	v_mfma_f32_16x16x32_bf16 v[46:49], v[110:113], v[174:177], v[46:49]
	v_mfma_f32_16x16x32_bf16 v[42:45], v[118:121], v[174:177], v[42:45]
	v_mfma_f32_16x16x32_bf16 v[30:33], v[110:113], v[182:185], v[30:33]
	v_mfma_f32_16x16x32_bf16 v[26:29], v[118:121], v[182:185], v[26:29]
	v_mfma_f32_16x16x32_bf16 v[14:17], v[110:113], v[190:193], v[14:17]
	v_mfma_f32_16x16x32_bf16 v[10:13], v[118:121], v[190:193], v[10:13]
	v_mfma_f32_16x16x32_bf16 v[54:57], v[122:125], v[162:165], v[54:57]
	v_mfma_f32_16x16x32_bf16 v[50:53], v[142:145], v[162:165], v[50:53]
	v_mfma_f32_16x16x32_bf16 v[38:41], v[122:125], v[170:173], v[38:41]
	v_mfma_f32_16x16x32_bf16 v[34:37], v[142:145], v[170:173], v[34:37]
	v_mfma_f32_16x16x32_bf16 v[22:25], v[122:125], v[178:181], v[22:25]
	v_mfma_f32_16x16x32_bf16 v[18:21], v[142:145], v[178:181], v[18:21]
	v_mfma_f32_16x16x32_bf16 v[6:9], v[122:125], v[186:189], v[6:9]
	v_mfma_f32_16x16x32_bf16 v[2:5], v[142:145], v[186:189], v[2:5]
	v_mfma_f32_16x16x32_bf16 v[54:57], v[126:129], v[166:169], v[54:57]
	v_mfma_f32_16x16x32_bf16 v[50:53], v[150:153], v[166:169], v[50:53]
	v_mfma_f32_16x16x32_bf16 v[38:41], v[126:129], v[174:177], v[38:41]
	v_mfma_f32_16x16x32_bf16 v[34:37], v[150:153], v[174:177], v[34:37]
	v_mfma_f32_16x16x32_bf16 v[22:25], v[126:129], v[182:185], v[22:25]
	v_mfma_f32_16x16x32_bf16 v[18:21], v[150:153], v[182:185], v[18:21]
	v_mfma_f32_16x16x32_bf16 v[6:9], v[126:129], v[190:193], v[6:9]
	v_mfma_f32_16x16x32_bf16 v[2:5], v[150:153], v[190:193], v[2:5]
	s_barrier
; #define PG8_STAGE(bufoff, gbase, voff) do { _Pragma("unroll") for (int _i = 0; _i < 2; ++_i) \
;         __builtin_amdgcn_global_load_lds((const unsigned*)((const char*)(gbase) + (voff)[_i]), (PG8_LAS unsigned*)(lds + (bufoff) + ldsw + _i * 8192), 16, 0, 0); } while (0)
; #define PG8_LDA(dst, b, h) do { _Pragma("unroll") for (int m = 0; m < 4; ++m) _Pragma("unroll") for (int k = 0; k < 2; ++k) dst[m][k] = *(const PG8_LAS bf16x8*)(lds + PG8_SA(b, h) + aoff + m * 2048 + k * 1024); } while (0)
; #define PG8_LDB(dst, b, h) do { _Pragma("unroll") for (int n = 0; n < 2; ++n) _Pragma("unroll") for (int k = 0; k < 2; ++k) dst[n][k] = *(const PG8_LAS bf16x8*)(lds + PG8_SB(b, h) + boff + n * 2048 + k * 1024); } while (0)
; #define PG8_MMA(ai, bj, At, Bt) do { __builtin_amdgcn_s_setprio(1); _Pragma("unroll") for (int m = 0; m < 4; ++m) _Pragma("unroll") for (int n = 0; n < 2; ++n) _Pragma("unroll") for (int k = 0; k < 2; ++k) \
;         acc[ai][bj][m][n] = __builtin_amdgcn_mfma_f32_16x16x32_bf16(Bt[n][k], At[m][k], acc[ai][bj][m][n], 0, 0, 0); __builtin_amdgcn_s_setprio(0); } while (0)
; #define PG8_WAIT_V(n) asm volatile("s_waitcnt vmcnt(" #n ")" ::: "memory")
; #define PG8_WAIT_L(n) asm volatile("s_waitcnt lgkmcnt(" #n ")" ::: "memory")
; #define PG8_BAR __builtin_amdgcn_s_barrier()
; #define PG8_SCHED __builtin_amdgcn_sched_barrier(0)
; template <class Epi, class Sched, bool ALIGN_EPI = false, bool SP2 = false>
; __device__ __forceinline__ void gemm_phase(PG8_LAS unsigned char* lds, const Gemm g, const Sched& S, const Epi& E, int wave_s) {
;     ...
;             PG8_LDB(B0, 1, 0); PG8_LDB(B1, 1, 1); PG8_SCHED; PG8_LDA(At, 1, 0); PG8_STAGE(PG8_SA(0, 1), a2 + hstepA, voffA);
;             PG8_WAIT_V(8); PG8_WAIT_L(0); PG8_BAR; PG8_MMA(0, 0, At, B0); PG8_MMA(0, 1, At, B1); PG8_BAR; PG8_SCHED;
;             PG8_LDA(At, 1, 1); PG8_STAGE(PG8_SB(1, 0), b3, voffB); PG8_STAGE(PG8_SB(1, 1), b3 + hstepB, voffB); PG8_STAGE(PG8_SA(1, 0), a3, voffA);
	s_add_i32 s85, 0, 0x18000
	s_add_i32 s89, 0, 0x1c000
	v_add_u32_e32 v118, s85, v229
	v_add_u32_e32 v150, s89, v229
	ds_read_b128 v[106:109], v118
	ds_read_b128 v[110:113], v118 offset:1024
	ds_read_b128 v[114:117], v118 offset:2048
	ds_read_b128 v[118:121], v118 offset:3072
	ds_read_b128 v[122:125], v150
	ds_read_b128 v[126:129], v150 offset:1024
	ds_read_b128 v[142:145], v150 offset:2048
	ds_read_b128 v[150:153], v150 offset:3072
	s_add_u32 s40, s40, 0x80000
	s_addc_u32 s41, s41, 0
	s_mov_b32 m0, s37
	v_lshl_add_u64 v[202:203], s[40:41], 0, v[216:217]
	ds_read_b128 v[162:165], v230 offset:32768
	ds_read_b128 v[166:169], v230 offset:33792
	ds_read_b128 v[170:173], v230 offset:34816
	ds_read_b128 v[174:177], v230 offset:35840
	ds_read_b128 v[178:181], v230 offset:36864
	ds_read_b128 v[182:185], v230 offset:37888
	ds_read_b128 v[186:189], v230 offset:38912
	ds_read_b128 v[190:193], v230 offset:39936
	global_load_lds_dwordx4 v[202:203], off
	v_lshl_add_u64 v[202:203], s[40:41], 0, v[212:213]
	s_mov_b32 m0, s42
	s_nop 0
	global_load_lds_dwordx4 v[202:203], off
	s_waitcnt vmcnt(8)
	s_waitcnt lgkmcnt(0)
	s_barrier
	s_waitcnt lgkmcnt(0)
	v_mfma_f32_16x16x32_bf16 v[158:161], v[106:109], v[162:165], v[158:161]
	v_mfma_f32_16x16x32_bf16 v[154:157], v[114:117], v[162:165], v[154:157]
	v_mfma_f32_16x16x32_bf16 v[134:137], v[106:109], v[170:173], v[134:137]
	v_mfma_f32_16x16x32_bf16 v[130:133], v[114:117], v[170:173], v[130:133]
	v_mfma_f32_16x16x32_bf16 v[94:97], v[106:109], v[178:181], v[94:97]
	v_mfma_f32_16x16x32_bf16 v[90:93], v[114:117], v[178:181], v[90:93]
	v_mfma_f32_16x16x32_bf16 v[78:81], v[106:109], v[186:189], v[78:81]
	v_mfma_f32_16x16x32_bf16 v[74:77], v[114:117], v[186:189], v[74:77]
	v_mfma_f32_16x16x32_bf16 v[158:161], v[110:113], v[166:169], v[158:161]
	v_mfma_f32_16x16x32_bf16 v[154:157], v[118:121], v[166:169], v[154:157]
	v_mfma_f32_16x16x32_bf16 v[134:137], v[110:113], v[174:177], v[134:137]
	v_mfma_f32_16x16x32_bf16 v[130:133], v[118:121], v[174:177], v[130:133]
	v_mfma_f32_16x16x32_bf16 v[94:97], v[110:113], v[182:185], v[94:97]
	v_mfma_f32_16x16x32_bf16 v[90:93], v[118:121], v[182:185], v[90:93]
	v_mfma_f32_16x16x32_bf16 v[78:81], v[110:113], v[190:193], v[78:81]
	v_mfma_f32_16x16x32_bf16 v[74:77], v[118:121], v[190:193], v[74:77]
	v_mfma_f32_16x16x32_bf16 v[146:149], v[122:125], v[162:165], v[146:149]
	v_mfma_f32_16x16x32_bf16 v[138:141], v[142:145], v[162:165], v[138:141]
	v_mfma_f32_16x16x32_bf16 v[102:105], v[122:125], v[170:173], v[102:105]
	v_mfma_f32_16x16x32_bf16 v[98:101], v[142:145], v[170:173], v[98:101]
	v_mfma_f32_16x16x32_bf16 v[86:89], v[122:125], v[178:181], v[86:89]
	v_mfma_f32_16x16x32_bf16 v[82:85], v[142:145], v[178:181], v[82:85]
	v_mfma_f32_16x16x32_bf16 v[70:73], v[122:125], v[186:189], v[70:73]
	v_mfma_f32_16x16x32_bf16 v[66:69], v[142:145], v[186:189], v[66:69]
	v_mfma_f32_16x16x32_bf16 v[146:149], v[126:129], v[166:169], v[146:149]
	v_mfma_f32_16x16x32_bf16 v[138:141], v[150:153], v[166:169], v[138:141]
	v_mfma_f32_16x16x32_bf16 v[102:105], v[126:129], v[174:177], v[102:105]
	v_mfma_f32_16x16x32_bf16 v[98:101], v[150:153], v[174:177], v[98:101]
	v_mfma_f32_16x16x32_bf16 v[86:89], v[126:129], v[182:185], v[86:89]
	v_mfma_f32_16x16x32_bf16 v[82:85], v[150:153], v[182:185], v[82:85]
	v_mfma_f32_16x16x32_bf16 v[70:73], v[126:129], v[190:193], v[70:73]
	v_mfma_f32_16x16x32_bf16 v[66:69], v[150:153], v[190:193], v[66:69]
	s_barrier
; #define PG8_STAGE(bufoff, gbase, voff) do { _Pragma("unroll") for (int _i = 0; _i < 2; ++_i) \
;         __builtin_amdgcn_global_load_lds((const unsigned*)((const char*)(gbase) + (voff)[_i]), (PG8_LAS unsigned*)(lds + (bufoff) + ldsw + _i * 8192), 16, 0, 0); } while (0)
; #define PG8_LDA(dst, b, h) do { _Pragma("unroll") for (int m = 0; m < 4; ++m) _Pragma("unroll") for (int k = 0; k < 2; ++k) dst[m][k] = *(const PG8_LAS bf16x8*)(lds + PG8_SA(b, h) + aoff + m * 2048 + k * 1024); } while (0)
; #define PG8_WAIT_V(n) asm volatile("s_waitcnt vmcnt(" #n ")" ::: "memory")
; #define PG8_WAIT_L(n) asm volatile("s_waitcnt lgkmcnt(" #n ")" ::: "memory")
; #define PG8_BAR __builtin_amdgcn_s_barrier()
; template <class Epi, class Sched, bool ALIGN_EPI = false, bool SP2 = false>
; __device__ __forceinline__ void gemm_phase(PG8_LAS unsigned char* lds, const Gemm g, const Sched& S, const Epi& E, int wave_s) {
;     ...
;         for (int t = 0; t < nt; t += 2) {
;             const bool last = (t == nt - 2);
;             const char* a1 = cA + (size_t)(t + 1) * kstep;
;             const char* a2 = last ? nA : cA + (size_t)(t + 2) * kstep; const char* b2 = last ? nB : cB + (size_t)(t + 2) * kstep;
;             const char* a3 = a2 + kstep; const char* b3 = b2 + kstep;
;             if (last && has_next) S.a_ready(nxt);
;             if constexpr (SP2) {
;             PG8_LDB(B0, 0, 0); PG8_LDB(B1, 0, 1); PG8_SCHED; PG8_LDA(At, 0, 0); PG8_STAGE(PG8_SA(1, 1), a1 + hstepA, voffA);
;             PG8_WAIT_V(8); PG8_WAIT_L(0); PG8_BAR; PG8_MMA(0, 0, At, B0); PG8_MMA(0, 1, At, B1); PG8_BAR; PG8_SCHED;
;             PG8_LDA(At, 0, 1); PG8_STAGE(PG8_SB(0, 0), b2, voffB); PG8_STAGE(PG8_SB(0, 1), b2 + hstepB, voffB); PG8_STAGE(PG8_SA(0, 0), a2, voffA);
;             PG8_WAIT_V(8); PG8_WAIT_L(0); PG8_BAR; PG8_MMA(1, 0, At, B0); PG8_MMA(1, 1, At, B1); PG8_BAR; PG8_SCHED;
;             PG8_LDB(B0, 1, 0); PG8_LDB(B1, 1, 1); PG8_SCHED; PG8_LDA(At, 1, 0); PG8_STAGE(PG8_SA(0, 1), a2 + hstepA, voffA);
;             PG8_WAIT_V(8); PG8_WAIT_L(0); PG8_BAR; PG8_MMA(0, 0, At, B0); PG8_MMA(0, 1, At, B1); PG8_BAR; PG8_SCHED;
;             PG8_LDA(At, 1, 1); PG8_STAGE(PG8_SB(1, 0), b3, voffB); PG8_STAGE(PG8_SB(1, 1), b3 + hstepB, voffB); PG8_STAGE(PG8_SA(1, 0), a3, voffA);
;             PG8_WAIT_V(8); PG8_WAIT_L(0); PG8_BAR; PG8_MMA(1, 0, At, B0); PG8_MMA(1, 1, At, B1); PG8_BAR; PG8_SCHED;
	s_add_i32 s40, s85, s34
	v_lshl_add_u64 v[194:195], v[194:195], 0, s[60:61]
	s_mov_b32 m0, s40
	ds_read_b128 v[162:165], v230 offset:49152
	ds_read_b128 v[166:169], v230 offset:50176
	ds_read_b128 v[170:173], v230 offset:51200
	ds_read_b128 v[174:177], v230 offset:52224
	ds_read_b128 v[178:181], v230 offset:53248
	ds_read_b128 v[182:185], v230 offset:54272
	ds_read_b128 v[186:189], v230 offset:55296
	ds_read_b128 v[190:193], v230 offset:56320
	global_load_lds_dwordx4 v[194:195], off
	s_add_i32 m0, s40, 0x2000
	s_add_u32 s30, s30, 0x20080
	v_lshl_add_u64 v[194:195], v[196:197], 0, s[60:61]
	s_addc_u32 s31, s31, 0
	s_add_i32 s40, s89, s34
	global_load_lds_dwordx4 v[194:195], off
	v_lshl_add_u64 v[194:195], s[30:31], 0, v[214:215]
	s_mov_b32 m0, s40
	s_nop 0
	global_load_lds_dwordx4 v[194:195], off
	v_lshl_add_u64 v[194:195], s[30:31], 0, v[210:211]
	s_add_i32 m0, s40, 0x2000
	s_nop 0
	global_load_lds_dwordx4 v[194:195], off
	v_lshl_add_u64 v[194:195], v[198:199], 0, s[60:61]
	s_mov_b32 m0, s46
	s_nop 0
	global_load_lds_dwordx4 v[194:195], off
	v_lshl_add_u64 v[194:195], v[200:201], 0, s[60:61]
	s_mov_b32 m0, s47
	s_nop 0
	global_load_lds_dwordx4 v[194:195], off
	s_waitcnt vmcnt(8)
	s_waitcnt lgkmcnt(0)
	s_barrier
	s_waitcnt lgkmcnt(0)
	v_mfma_f32_16x16x32_bf16 v[62:65], v[106:109], v[162:165], v[62:65]
	v_mfma_f32_16x16x32_bf16 v[58:61], v[114:117], v[162:165], v[58:61]
	v_mfma_f32_16x16x32_bf16 v[46:49], v[106:109], v[170:173], v[46:49]
	v_mfma_f32_16x16x32_bf16 v[42:45], v[114:117], v[170:173], v[42:45]
	v_mfma_f32_16x16x32_bf16 v[30:33], v[106:109], v[178:181], v[30:33]
	v_mfma_f32_16x16x32_bf16 v[26:29], v[114:117], v[178:181], v[26:29]
	v_mfma_f32_16x16x32_bf16 v[14:17], v[106:109], v[186:189], v[14:17]
	v_mfma_f32_16x16x32_bf16 v[10:13], v[114:117], v[186:189], v[10:13]
	v_mfma_f32_16x16x32_bf16 v[62:65], v[110:113], v[166:169], v[62:65]
	v_mfma_f32_16x16x32_bf16 v[58:61], v[118:121], v[166:169], v[58:61]
	v_mfma_f32_16x16x32_bf16 v[46:49], v[110:113], v[174:177], v[46:49]
	v_mfma_f32_16x16x32_bf16 v[42:45], v[118:121], v[174:177], v[42:45]
	v_mfma_f32_16x16x32_bf16 v[30:33], v[110:113], v[182:185], v[30:33]
	v_mfma_f32_16x16x32_bf16 v[26:29], v[118:121], v[182:185], v[26:29]
	v_mfma_f32_16x16x32_bf16 v[14:17], v[110:113], v[190:193], v[14:17]
	v_mfma_f32_16x16x32_bf16 v[10:13], v[118:121], v[190:193], v[10:13]
	v_mfma_f32_16x16x32_bf16 v[54:57], v[122:125], v[162:165], v[54:57]
	v_mfma_f32_16x16x32_bf16 v[50:53], v[142:145], v[162:165], v[50:53]
	v_mfma_f32_16x16x32_bf16 v[38:41], v[122:125], v[170:173], v[38:41]
	v_mfma_f32_16x16x32_bf16 v[34:37], v[142:145], v[170:173], v[34:37]
	v_mfma_f32_16x16x32_bf16 v[22:25], v[122:125], v[178:181], v[22:25]
	v_mfma_f32_16x16x32_bf16 v[18:21], v[142:145], v[178:181], v[18:21]
	v_mfma_f32_16x16x32_bf16 v[6:9], v[122:125], v[186:189], v[6:9]
	v_mfma_f32_16x16x32_bf16 v[2:5], v[142:145], v[186:189], v[2:5]
	v_mfma_f32_16x16x32_bf16 v[54:57], v[126:129], v[166:169], v[54:57]
	v_mfma_f32_16x16x32_bf16 v[50:53], v[150:153], v[166:169], v[50:53]
	v_mfma_f32_16x16x32_bf16 v[38:41], v[126:129], v[174:177], v[38:41]
	v_mfma_f32_16x16x32_bf16 v[34:37], v[150:153], v[174:177], v[34:37]
	v_mfma_f32_16x16x32_bf16 v[22:25], v[126:129], v[182:185], v[22:25]
	v_mfma_f32_16x16x32_bf16 v[18:21], v[150:153], v[182:185], v[18:21]
	v_mfma_f32_16x16x32_bf16 v[6:9], v[126:129], v[190:193], v[6:9]
	v_mfma_f32_16x16x32_bf16 v[2:5], v[150:153], v[190:193], v[2:5]
	s_add_i32 s84, s84, 2
	s_add_u32 s4, s4, 0x100
	s_addc_u32 s5, s5, 0
	s_add_u32 s29, s29, 0x100
	s_addc_u32 s81, s81, 0
	s_add_u32 s30, s4, 0xfff80080
	s_addc_u32 s31, s5, -1
	s_add_i32 s85, 0, 0x10000
	s_cmp_eq_u32 s84, 4
	s_cselect_b32 s41, s91, s31
	s_cselect_b32 s40, s90, s30
	s_cselect_b32 s31, s2, s81
	s_cselect_b32 s30, s3, s29
	s_add_i32 s89, 0, 0x14000
	s_cmp_gt_u32 s84, 5
	s_barrier
	s_cbranch_scc0 .LBB0_314
	s_and_b64 vcc, exec, s[20:21]
	s_cbranch_vccz .LBB0_317
	s_barrier

; #define PG8_STAGE(bufoff, gbase, voff) do { _Pragma("unroll") for (int _i = 0; _i < 2; ++_i) \
;         __builtin_amdgcn_global_load_lds((const unsigned*)((const char*)(gbase) + (voff)[_i]), (PG8_LAS unsigned*)(lds + (bufoff) + ldsw + _i * 8192), 16, 0, 0); } while (0)
; #define PG8_LDA(dst, b, h) do { _Pragma("unroll") for (int m = 0; m < 4; ++m) _Pragma("unroll") for (int k = 0; k < 2; ++k) dst[m][k] = *(const PG8_LAS bf16x8*)(lds + PG8_SA(b, h) + aoff + m * 2048 + k * 1024); } while (0)
; #define PG8_LDB(dst, b, h) do { _Pragma("unroll") for (int n = 0; n < 2; ++n) _Pragma("unroll") for (int k = 0; k < 2; ++k) dst[n][k] = *(const PG8_LAS bf16x8*)(lds + PG8_SB(b, h) + boff + n * 2048 + k * 1024); } while (0)
; #define PG8_WAIT_V(n) asm volatile("s_waitcnt vmcnt(" #n ")" ::: "memory")
; #define PG8_WAIT_L(n) asm volatile("s_waitcnt lgkmcnt(" #n ")" ::: "memory")
; #define PG8_BAR __builtin_amdgcn_s_barrier()
; template <class Epi, class Sched, bool ALIGN_EPI = false, bool SP2 = false>
; __device__ __forceinline__ void gemm_phase(PG8_LAS unsigned char* lds, const Gemm g, const Sched& S, const Epi& E, int wave_s) {
;     ...
;         const bool has_next = S.next(ui + 1, nxt);
;         const char* nA = has_next ? (const char*)g.A + (size_t)nxt.pm * tstepA + (size_t)(nxt.pn / g.npg) * (size_t)(K * 2) : cA; const char* nB = has_next ? (const char*)g.Bt + (size_t)nxt.pn * tstepB : cB;
;         for (int t = 0; t < nt; t += 2) {
;             const bool last = (t == nt - 2);
;             const char* a1 = cA + (size_t)(t + 1) * kstep;
;             const char* a2 = last ? nA : cA + (size_t)(t + 2) * kstep; const char* b2 = last ? nB : cB + (size_t)(t + 2) * kstep;
;             const char* a3 = a2 + kstep; const char* b3 = b2 + kstep;
;             if (last && has_next) S.a_ready(nxt);
;             if constexpr (SP2) {
;             PG8_LDB(B0, 0, 0); PG8_LDB(B1, 0, 1); PG8_SCHED; PG8_LDA(At, 0, 0); PG8_STAGE(PG8_SA(1, 1), a1 + hstepA, voffA);
;             PG8_WAIT_V(8); PG8_WAIT_L(0); PG8_BAR; PG8_MMA(0, 0, At, B0); PG8_MMA(0, 1, At, B1); PG8_BAR; PG8_SCHED;
;             PG8_LDA(At, 0, 1); PG8_STAGE(PG8_SB(0, 0), b2, voffB); PG8_STAGE(PG8_SB(0, 1), b2 + hstepB, voffB); PG8_STAGE(PG8_SA(0, 0), a2, voffA);
;             PG8_WAIT_V(8); PG8_WAIT_L(0); PG8_BAR; PG8_MMA(1, 0, At, B0); PG8_MMA(1, 1, At, B1); PG8_BAR; PG8_SCHED;
.LBB0_411:
	s_ashr_i32 s15, s14, 31
	s_lshl_b64 s[2:3], s[14:15], 20
	s_add_u32 s28, s22, s2
	s_addc_u32 s29, s23, s3
	s_and_b64 s[2:3], s[4:5], exec
	s_cselect_b32 s2, s29, s31
	s_cselect_b32 s3, s28, s30
	s_add_u32 s4, s40, 0x80080
	s_addc_u32 s5, s41, 0
	s_add_u32 s15, s30, 0x100
	s_addc_u32 s21, s31, 0
	s_mov_b32 s94, -2
	s_add_u32 s30, s4, 0xfff80080
	s_addc_u32 s31, s5, -1
	s_add_i32 s95, 0, 0x10000
	s_cmp_eq_u32 s94, 28
	s_cselect_b32 s41, s27, s31
	s_cselect_b32 s40, s26, s30
	v_add_u32_e32 v149, s95, v147
	s_cselect_b32 s31, s2, s21
	s_cselect_b32 s30, s3, s15
	s_add_i32 vcc_lo, 0, 0x14000
	ds_read_b128 v[142:145], v149
	ds_read_b128 v[150:153], v149 offset:1024
	ds_read_b128 v[154:157], v149 offset:2048
	ds_read_b128 v[158:161], v149 offset:3072
	v_add_u32_e32 v149, vcc_lo, v147
	ds_read_b128 v[162:165], v149
	ds_read_b128 v[166:169], v149 offset:1024
	ds_read_b128 v[170:173], v149 offset:2048
	ds_read_b128 v[174:177], v149 offset:3072
	v_lshl_add_u64 v[210:211], s[4:5], 0, v[138:139]
	s_add_i32 m0, s35, 0xc000
	ds_read_b128 v[178:181], v148
	ds_read_b128 v[182:185], v148 offset:1024
	ds_read_b128 v[186:189], v148 offset:2048
	ds_read_b128 v[190:193], v148 offset:3072
	ds_read_b128 v[194:197], v148 offset:4096
	ds_read_b128 v[198:201], v148 offset:5120
	ds_read_b128 v[202:205], v148 offset:6144
	ds_read_b128 v[206:209], v148 offset:7168
	global_load_lds_dwordx4 v[210:211], off
	v_lshl_add_u64 v[210:211], s[4:5], 0, v[140:141]
	s_add_i32 m0, s35, 0xe000
	s_nop 0
	global_load_lds_dwordx4 v[210:211], off
	s_waitcnt vmcnt(8)
	s_waitcnt lgkmcnt(0)
	s_barrier
	s_waitcnt lgkmcnt(0)
	v_mfma_f32_16x16x32_bf16 v[126:129], v[142:145], v[178:181], 0
	v_mfma_f32_16x16x32_bf16 v[122:125], v[154:157], v[178:181], 0
	v_mfma_f32_16x16x32_bf16 v[110:113], v[142:145], v[186:189], 0
	v_mfma_f32_16x16x32_bf16 v[106:109], v[154:157], v[186:189], 0
	v_mfma_f32_16x16x32_bf16 v[94:97], v[142:145], v[194:197], 0
	v_mfma_f32_16x16x32_bf16 v[90:93], v[154:157], v[194:197], 0
	v_mfma_f32_16x16x32_bf16 v[78:81], v[142:145], v[202:205], 0
	v_mfma_f32_16x16x32_bf16 v[74:77], v[154:157], v[202:205], 0
	v_mfma_f32_16x16x32_bf16 v[126:129], v[150:153], v[182:185], v[126:129]
	v_mfma_f32_16x16x32_bf16 v[122:125], v[158:161], v[182:185], v[122:125]
	v_mfma_f32_16x16x32_bf16 v[110:113], v[150:153], v[190:193], v[110:113]
	v_mfma_f32_16x16x32_bf16 v[106:109], v[158:161], v[190:193], v[106:109]
	v_mfma_f32_16x16x32_bf16 v[94:97], v[150:153], v[198:201], v[94:97]
	v_mfma_f32_16x16x32_bf16 v[90:93], v[158:161], v[198:201], v[90:93]
	v_mfma_f32_16x16x32_bf16 v[78:81], v[150:153], v[206:209], v[78:81]
	v_mfma_f32_16x16x32_bf16 v[74:77], v[158:161], v[206:209], v[74:77]
	v_mfma_f32_16x16x32_bf16 v[118:121], v[162:165], v[178:181], 0
	v_mfma_f32_16x16x32_bf16 v[114:117], v[170:173], v[178:181], 0
	v_mfma_f32_16x16x32_bf16 v[102:105], v[162:165], v[186:189], 0
	v_mfma_f32_16x16x32_bf16 v[98:101], v[170:173], v[186:189], 0
	v_mfma_f32_16x16x32_bf16 v[86:89], v[162:165], v[194:197], 0
	v_mfma_f32_16x16x32_bf16 v[82:85], v[170:173], v[194:197], 0
	v_mfma_f32_16x16x32_bf16 v[70:73], v[162:165], v[202:205], 0
	v_mfma_f32_16x16x32_bf16 v[66:69], v[170:173], v[202:205], 0
	v_mfma_f32_16x16x32_bf16 v[118:121], v[166:169], v[182:185], v[118:121]
	v_mfma_f32_16x16x32_bf16 v[114:117], v[174:177], v[182:185], v[114:117]
	v_mfma_f32_16x16x32_bf16 v[102:105], v[166:169], v[190:193], v[102:105]
	v_mfma_f32_16x16x32_bf16 v[98:101], v[174:177], v[190:193], v[98:101]
	v_mfma_f32_16x16x32_bf16 v[86:89], v[166:169], v[198:201], v[86:89]
	v_mfma_f32_16x16x32_bf16 v[82:85], v[174:177], v[198:201], v[82:85]
	v_mfma_f32_16x16x32_bf16 v[70:73], v[166:169], v[206:209], v[70:73]
	v_mfma_f32_16x16x32_bf16 v[66:69], v[174:177], v[206:209], v[66:69]
	s_barrier
	s_add_i32 s95, s95, s34
	v_lshl_add_u64 v[210:211], s[30:31], 0, v[132:133]
	s_mov_b32 m0, s95
	ds_read_b128 v[178:181], v148 offset:16384
	ds_read_b128 v[182:185], v148 offset:17408
	ds_read_b128 v[186:189], v148 offset:18432
	ds_read_b128 v[190:193], v148 offset:19456
	ds_read_b128 v[194:197], v148 offset:20480
	ds_read_b128 v[198:201], v148 offset:21504
	ds_read_b128 v[202:205], v148 offset:22528
	ds_read_b128 v[206:209], v148 offset:23552
	global_load_lds_dwordx4 v[210:211], off
	s_add_i32 m0, s95, 0x2000
	s_add_u32 s96, s30, 0x80000
	v_lshl_add_u64 v[212:213], s[30:31], 0, v[136:137]
	s_addc_u32 s97, s31, 0
	s_add_i32 s95, vcc_lo, s34
	global_load_lds_dwordx4 v[212:213], off
	v_lshl_add_u64 v[214:215], s[96:97], 0, v[132:133]
	s_mov_b32 m0, s95
	v_lshl_add_u64 v[216:217], s[40:41], 0, v[134:135]
	global_load_lds_dwordx4 v[214:215], off
	v_lshl_add_u64 v[214:215], s[96:97], 0, v[136:137]
	s_add_i32 m0, s95, 0x2000
	s_nop 0
	global_load_lds_dwordx4 v[214:215], off
	v_lshl_add_u64 v[214:215], s[40:41], 0, v[130:131]
	s_mov_b32 m0, s35
	s_nop 0
	global_load_lds_dwordx4 v[214:215], off
	s_mov_b32 m0, s36
	s_nop 0
	global_load_lds_dwordx4 v[216:217], off
	s_waitcnt vmcnt(8)
	s_waitcnt lgkmcnt(0)
	s_barrier
; #define PG8_STAGE(bufoff, gbase, voff) do { _Pragma("unroll") for (int _i = 0; _i < 2; ++_i) \
;         __builtin_amdgcn_global_load_lds((const unsigned*)((const char*)(gbase) + (voff)[_i]), (PG8_LAS unsigned*)(lds + (bufoff) + ldsw + _i * 8192), 16, 0, 0); } while (0)
; #define PG8_LDA(dst, b, h) do { _Pragma("unroll") for (int m = 0; m < 4; ++m) _Pragma("unroll") for (int k = 0; k < 2; ++k) dst[m][k] = *(const PG8_LAS bf16x8*)(lds + PG8_SA(b, h) + aoff + m * 2048 + k * 1024); } while (0)
; #define PG8_LDB(dst, b, h) do { _Pragma("unroll") for (int n = 0; n < 2; ++n) _Pragma("unroll") for (int k = 0; k < 2; ++k) dst[n][k] = *(const PG8_LAS bf16x8*)(lds + PG8_SB(b, h) + boff + n * 2048 + k * 1024); } while (0)
; #define PG8_MMA(ai, bj, At, Bt) do { __builtin_amdgcn_s_setprio(1); _Pragma("unroll") for (int m = 0; m < 4; ++m) _Pragma("unroll") for (int n = 0; n < 2; ++n) _Pragma("unroll") for (int k = 0; k < 2; ++k) \
;         acc[ai][bj][m][n] = __builtin_amdgcn_mfma_f32_16x16x32_bf16(Bt[n][k], At[m][k], acc[ai][bj][m][n], 0, 0, 0); __builtin_amdgcn_s_setprio(0); } while (0)
; #define PG8_WAIT_V(n) asm volatile("s_waitcnt vmcnt(" #n ")" ::: "memory")
; #define PG8_WAIT_L(n) asm volatile("s_waitcnt lgkmcnt(" #n ")" ::: "memory")
; #define PG8_BAR __builtin_amdgcn_s_barrier()
; #define PG8_SCHED __builtin_amdgcn_sched_barrier(0)
; template <class Epi, class Sched, bool ALIGN_EPI = false, bool SP2 = false>
; __device__ __forceinline__ void gemm_phase(PG8_LAS unsigned char* lds, const Gemm g, const Sched& S, const Epi& E, int wave_s) {
;     ...
;             PG8_WAIT_V(8); PG8_WAIT_L(0); PG8_BAR; PG8_MMA(1, 0, At, B0); PG8_MMA(1, 1, At, B1); PG8_BAR; PG8_SCHED;
;             PG8_LDB(B0, 1, 0); PG8_LDB(B1, 1, 1); PG8_SCHED; PG8_LDA(At, 1, 0); PG8_STAGE(PG8_SA(0, 1), a2 + hstepA, voffA);
;             PG8_WAIT_V(8); PG8_WAIT_L(0); PG8_BAR; PG8_MMA(0, 0, At, B0); PG8_MMA(0, 1, At, B1); PG8_BAR; PG8_SCHED;
;             PG8_LDA(At, 1, 1); PG8_STAGE(PG8_SB(1, 0), b3, voffB); PG8_STAGE(PG8_SB(1, 1), b3 + hstepB, voffB); PG8_STAGE(PG8_SA(1, 0), a3, voffA);
	s_waitcnt lgkmcnt(0)
	v_mfma_f32_16x16x32_bf16 v[62:65], v[142:145], v[178:181], 0
	v_mfma_f32_16x16x32_bf16 v[58:61], v[154:157], v[178:181], 0
	v_mfma_f32_16x16x32_bf16 v[46:49], v[142:145], v[186:189], 0
	v_mfma_f32_16x16x32_bf16 v[42:45], v[154:157], v[186:189], 0
	v_mfma_f32_16x16x32_bf16 v[30:33], v[142:145], v[194:197], 0
	v_mfma_f32_16x16x32_bf16 v[26:29], v[154:157], v[194:197], 0
	v_mfma_f32_16x16x32_bf16 v[14:17], v[142:145], v[202:205], 0
	v_mfma_f32_16x16x32_bf16 v[10:13], v[154:157], v[202:205], 0
	v_mfma_f32_16x16x32_bf16 v[62:65], v[150:153], v[182:185], v[62:65]
	v_mfma_f32_16x16x32_bf16 v[58:61], v[158:161], v[182:185], v[58:61]
	v_mfma_f32_16x16x32_bf16 v[46:49], v[150:153], v[190:193], v[46:49]
	v_mfma_f32_16x16x32_bf16 v[42:45], v[158:161], v[190:193], v[42:45]
	v_mfma_f32_16x16x32_bf16 v[30:33], v[150:153], v[198:201], v[30:33]
	v_mfma_f32_16x16x32_bf16 v[26:29], v[158:161], v[198:201], v[26:29]
	v_mfma_f32_16x16x32_bf16 v[14:17], v[150:153], v[206:209], v[14:17]
	v_mfma_f32_16x16x32_bf16 v[10:13], v[158:161], v[206:209], v[10:13]
	v_mfma_f32_16x16x32_bf16 v[54:57], v[162:165], v[178:181], 0
	v_mfma_f32_16x16x32_bf16 v[50:53], v[170:173], v[178:181], 0
	v_mfma_f32_16x16x32_bf16 v[38:41], v[162:165], v[186:189], 0
	v_mfma_f32_16x16x32_bf16 v[34:37], v[170:173], v[186:189], 0
	v_mfma_f32_16x16x32_bf16 v[22:25], v[162:165], v[194:197], 0
	v_mfma_f32_16x16x32_bf16 v[18:21], v[170:173], v[194:197], 0
	v_mfma_f32_16x16x32_bf16 v[6:9], v[162:165], v[202:205], 0
	v_mfma_f32_16x16x32_bf16 v[2:5], v[170:173], v[202:205], 0
	v_mfma_f32_16x16x32_bf16 v[54:57], v[166:169], v[182:185], v[54:57]
	v_mfma_f32_16x16x32_bf16 v[50:53], v[174:177], v[182:185], v[50:53]
	v_mfma_f32_16x16x32_bf16 v[38:41], v[166:169], v[190:193], v[38:41]
	v_mfma_f32_16x16x32_bf16 v[34:37], v[174:177], v[190:193], v[34:37]
	v_mfma_f32_16x16x32_bf16 v[22:25], v[166:169], v[198:201], v[22:25]
	v_mfma_f32_16x16x32_bf16 v[18:21], v[174:177], v[198:201], v[18:21]
	v_mfma_f32_16x16x32_bf16 v[6:9], v[166:169], v[206:209], v[6:9]
	v_mfma_f32_16x16x32_bf16 v[2:5], v[174:177], v[206:209], v[2:5]
	s_barrier
	s_add_i32 s95, 0, 0x18000
	v_add_u32_e32 v149, s95, v147
	s_add_i32 s96, 0, 0x1c000
	ds_read_b128 v[142:145], v149
	ds_read_b128 v[150:153], v149 offset:1024
	ds_read_b128 v[154:157], v149 offset:2048
	ds_read_b128 v[158:161], v149 offset:3072
	v_add_u32_e32 v149, s96, v147
	ds_read_b128 v[162:165], v149
	ds_read_b128 v[166:169], v149 offset:1024
	ds_read_b128 v[170:173], v149 offset:2048
	ds_read_b128 v[174:177], v149 offset:3072
	s_add_u32 s40, s40, 0x80000
	s_addc_u32 s41, s41, 0
	s_mov_b32 m0, s37
	v_lshl_add_u64 v[218:219], s[40:41], 0, v[130:131]
	ds_read_b128 v[178:181], v148 offset:32768
	ds_read_b128 v[182:185], v148 offset:33792
	ds_read_b128 v[186:189], v148 offset:34816
	ds_read_b128 v[190:193], v148 offset:35840
	ds_read_b128 v[194:197], v148 offset:36864
	ds_read_b128 v[198:201], v148 offset:37888
	ds_read_b128 v[202:205], v148 offset:38912
	ds_read_b128 v[206:209], v148 offset:39936
	global_load_lds_dwordx4 v[218:219], off
	v_lshl_add_u64 v[218:219], s[40:41], 0, v[134:135]
	s_mov_b32 m0, s42
	s_nop 0
	global_load_lds_dwordx4 v[218:219], off
	s_waitcnt vmcnt(8)
	s_waitcnt lgkmcnt(0)
	s_barrier
	s_waitcnt lgkmcnt(0)
	v_mfma_f32_16x16x32_bf16 v[126:129], v[142:145], v[178:181], v[126:129]
	v_mfma_f32_16x16x32_bf16 v[122:125], v[154:157], v[178:181], v[122:125]
	v_mfma_f32_16x16x32_bf16 v[110:113], v[142:145], v[186:189], v[110:113]
	v_mfma_f32_16x16x32_bf16 v[106:109], v[154:157], v[186:189], v[106:109]
	v_mfma_f32_16x16x32_bf16 v[94:97], v[142:145], v[194:197], v[94:97]
	v_mfma_f32_16x16x32_bf16 v[90:93], v[154:157], v[194:197], v[90:93]
	v_mfma_f32_16x16x32_bf16 v[78:81], v[142:145], v[202:205], v[78:81]
	v_mfma_f32_16x16x32_bf16 v[74:77], v[154:157], v[202:205], v[74:77]
	v_mfma_f32_16x16x32_bf16 v[126:129], v[150:153], v[182:185], v[126:129]
	v_mfma_f32_16x16x32_bf16 v[122:125], v[158:161], v[182:185], v[122:125]
	v_mfma_f32_16x16x32_bf16 v[110:113], v[150:153], v[190:193], v[110:113]
	v_mfma_f32_16x16x32_bf16 v[106:109], v[158:161], v[190:193], v[106:109]
	v_mfma_f32_16x16x32_bf16 v[94:97], v[150:153], v[198:201], v[94:97]
	v_mfma_f32_16x16x32_bf16 v[90:93], v[158:161], v[198:201], v[90:93]
	v_mfma_f32_16x16x32_bf16 v[78:81], v[150:153], v[206:209], v[78:81]
	v_mfma_f32_16x16x32_bf16 v[74:77], v[158:161], v[206:209], v[74:77]
	v_mfma_f32_16x16x32_bf16 v[118:121], v[162:165], v[178:181], v[118:121]
	v_mfma_f32_16x16x32_bf16 v[114:117], v[170:173], v[178:181], v[114:117]
	v_mfma_f32_16x16x32_bf16 v[102:105], v[162:165], v[186:189], v[102:105]
	v_mfma_f32_16x16x32_bf16 v[98:101], v[170:173], v[186:189], v[98:101]
	v_mfma_f32_16x16x32_bf16 v[86:89], v[162:165], v[194:197], v[86:89]
	v_mfma_f32_16x16x32_bf16 v[82:85], v[170:173], v[194:197], v[82:85]
	v_mfma_f32_16x16x32_bf16 v[70:73], v[162:165], v[202:205], v[70:73]
	v_mfma_f32_16x16x32_bf16 v[66:69], v[170:173], v[202:205], v[66:69]
	v_mfma_f32_16x16x32_bf16 v[118:121], v[166:169], v[182:185], v[118:121]
	v_mfma_f32_16x16x32_bf16 v[114:117], v[174:177], v[182:185], v[114:117]
	v_mfma_f32_16x16x32_bf16 v[102:105], v[166:169], v[190:193], v[102:105]
	v_mfma_f32_16x16x32_bf16 v[98:101], v[174:177], v[190:193], v[98:101]
	v_mfma_f32_16x16x32_bf16 v[86:89], v[166:169], v[198:201], v[86:89]
	v_mfma_f32_16x16x32_bf16 v[82:85], v[174:177], v[198:201], v[82:85]
	v_mfma_f32_16x16x32_bf16 v[70:73], v[166:169], v[206:209], v[70:73]
	v_mfma_f32_16x16x32_bf16 v[66:69], v[174:177], v[206:209], v[66:69]
	s_barrier
; #define PG8_STAGE(bufoff, gbase, voff) do { _Pragma("unroll") for (int _i = 0; _i < 2; ++_i) \
;         __builtin_amdgcn_global_load_lds((const unsigned*)((const char*)(gbase) + (voff)[_i]), (PG8_LAS unsigned*)(lds + (bufoff) + ldsw + _i * 8192), 16, 0, 0); } while (0)
; #define PG8_LDA(dst, b, h) do { _Pragma("unroll") for (int m = 0; m < 4; ++m) _Pragma("unroll") for (int k = 0; k < 2; ++k) dst[m][k] = *(const PG8_LAS bf16x8*)(lds + PG8_SA(b, h) + aoff + m * 2048 + k * 1024); } while (0)
; #define PG8_WAIT_V(n) asm volatile("s_waitcnt vmcnt(" #n ")" ::: "memory")
; #define PG8_WAIT_L(n) asm volatile("s_waitcnt lgkmcnt(" #n ")" ::: "memory")
; #define PG8_BAR __builtin_amdgcn_s_barrier()
; template <class Epi, class Sched, bool ALIGN_EPI = false, bool SP2 = false>
; __device__ __forceinline__ void gemm_phase(PG8_LAS unsigned char* lds, const Gemm g, const Sched& S, const Epi& E, int wave_s) {
;     ...
;         for (int t = 0; t < nt; t += 2) {
;             const bool last = (t == nt - 2);
;             const char* a1 = cA + (size_t)(t + 1) * kstep;
;             const char* a2 = last ? nA : cA + (size_t)(t + 2) * kstep; const char* b2 = last ? nB : cB + (size_t)(t + 2) * kstep;
;             const char* a3 = a2 + kstep; const char* b3 = b2 + kstep;
;             if (last && has_next) S.a_ready(nxt);
;             if constexpr (SP2) {
;             PG8_LDB(B0, 0, 0); PG8_LDB(B1, 0, 1); PG8_SCHED; PG8_LDA(At, 0, 0); PG8_STAGE(PG8_SA(1, 1), a1 + hstepA, voffA);
;             PG8_WAIT_V(8); PG8_WAIT_L(0); PG8_BAR; PG8_MMA(0, 0, At, B0); PG8_MMA(0, 1, At, B1); PG8_BAR; PG8_SCHED;
;             PG8_LDA(At, 0, 1); PG8_STAGE(PG8_SB(0, 0), b2, voffB); PG8_STAGE(PG8_SB(0, 1), b2 + hstepB, voffB); PG8_STAGE(PG8_SA(0, 0), a2, voffA);
;             PG8_WAIT_V(8); PG8_WAIT_L(0); PG8_BAR; PG8_MMA(1, 0, At, B0); PG8_MMA(1, 1, At, B1); PG8_BAR; PG8_SCHED;
;             PG8_LDB(B0, 1, 0); PG8_LDB(B1, 1, 1); PG8_SCHED; PG8_LDA(At, 1, 0); PG8_STAGE(PG8_SA(0, 1), a2 + hstepA, voffA);
;             PG8_WAIT_V(8); PG8_WAIT_L(0); PG8_BAR; PG8_MMA(0, 0, At, B0); PG8_MMA(0, 1, At, B1); PG8_BAR; PG8_SCHED;
;             PG8_LDA(At, 1, 1); PG8_STAGE(PG8_SB(1, 0), b3, voffB); PG8_STAGE(PG8_SB(1, 1), b3 + hstepB, voffB); PG8_STAGE(PG8_SA(1, 0), a3, voffA);
;             PG8_WAIT_V(8); PG8_WAIT_L(0); PG8_BAR; PG8_MMA(1, 0, At, B0); PG8_MMA(1, 1, At, B1); PG8_BAR; PG8_SCHED;
	s_add_i32 s40, s95, s34
	v_lshl_add_u64 v[210:211], v[210:211], 0, s[60:61]
	s_mov_b32 m0, s40
	ds_read_b128 v[178:181], v148 offset:49152
	ds_read_b128 v[182:185], v148 offset:50176
	ds_read_b128 v[186:189], v148 offset:51200
	ds_read_b128 v[190:193], v148 offset:52224
	ds_read_b128 v[194:197], v148 offset:53248
	ds_read_b128 v[198:201], v148 offset:54272
	ds_read_b128 v[202:205], v148 offset:55296
	ds_read_b128 v[206:209], v148 offset:56320
	global_load_lds_dwordx4 v[210:211], off
	s_add_i32 m0, s40, 0x2000
	s_add_u32 s30, s30, 0x80080
	v_lshl_add_u64 v[210:211], v[212:213], 0, s[60:61]
	s_addc_u32 s31, s31, 0
	s_add_i32 s40, s96, s34
	global_load_lds_dwordx4 v[210:211], off
	v_lshl_add_u64 v[210:211], s[30:31], 0, v[132:133]
	s_mov_b32 m0, s40
	s_nop 0
	global_load_lds_dwordx4 v[210:211], off
	v_lshl_add_u64 v[210:211], s[30:31], 0, v[136:137]
	s_add_i32 m0, s40, 0x2000
	s_nop 0
	global_load_lds_dwordx4 v[210:211], off
	v_lshl_add_u64 v[210:211], v[214:215], 0, s[60:61]
	s_mov_b32 m0, s45
	s_nop 0
	global_load_lds_dwordx4 v[210:211], off
	v_lshl_add_u64 v[210:211], v[216:217], 0, s[60:61]
	s_mov_b32 m0, s46
	s_nop 0
	global_load_lds_dwordx4 v[210:211], off
	s_waitcnt vmcnt(8)
	s_waitcnt lgkmcnt(0)
	s_barrier
	s_waitcnt lgkmcnt(0)
	v_mfma_f32_16x16x32_bf16 v[62:65], v[142:145], v[178:181], v[62:65]
	v_mfma_f32_16x16x32_bf16 v[58:61], v[154:157], v[178:181], v[58:61]
	v_mfma_f32_16x16x32_bf16 v[46:49], v[142:145], v[186:189], v[46:49]
	v_mfma_f32_16x16x32_bf16 v[42:45], v[154:157], v[186:189], v[42:45]
	v_mfma_f32_16x16x32_bf16 v[30:33], v[142:145], v[194:197], v[30:33]
	v_mfma_f32_16x16x32_bf16 v[26:29], v[154:157], v[194:197], v[26:29]
	v_mfma_f32_16x16x32_bf16 v[14:17], v[142:145], v[202:205], v[14:17]
	v_mfma_f32_16x16x32_bf16 v[10:13], v[154:157], v[202:205], v[10:13]
	v_mfma_f32_16x16x32_bf16 v[62:65], v[150:153], v[182:185], v[62:65]
	v_mfma_f32_16x16x32_bf16 v[58:61], v[158:161], v[182:185], v[58:61]
	v_mfma_f32_16x16x32_bf16 v[46:49], v[150:153], v[190:193], v[46:49]
	v_mfma_f32_16x16x32_bf16 v[42:45], v[158:161], v[190:193], v[42:45]
	v_mfma_f32_16x16x32_bf16 v[30:33], v[150:153], v[198:201], v[30:33]
	v_mfma_f32_16x16x32_bf16 v[26:29], v[158:161], v[198:201], v[26:29]
	v_mfma_f32_16x16x32_bf16 v[14:17], v[150:153], v[206:209], v[14:17]
	v_mfma_f32_16x16x32_bf16 v[10:13], v[158:161], v[206:209], v[10:13]
	v_mfma_f32_16x16x32_bf16 v[54:57], v[162:165], v[178:181], v[54:57]
	v_mfma_f32_16x16x32_bf16 v[50:53], v[170:173], v[178:181], v[50:53]
	v_mfma_f32_16x16x32_bf16 v[38:41], v[162:165], v[186:189], v[38:41]
	v_mfma_f32_16x16x32_bf16 v[34:37], v[170:173], v[186:189], v[34:37]
	v_mfma_f32_16x16x32_bf16 v[22:25], v[162:165], v[194:197], v[22:25]
	v_mfma_f32_16x16x32_bf16 v[18:21], v[170:173], v[194:197], v[18:21]
	v_mfma_f32_16x16x32_bf16 v[6:9], v[162:165], v[202:205], v[6:9]
	v_mfma_f32_16x16x32_bf16 v[2:5], v[170:173], v[202:205], v[2:5]
	v_mfma_f32_16x16x32_bf16 v[54:57], v[166:169], v[182:185], v[54:57]
	v_mfma_f32_16x16x32_bf16 v[50:53], v[174:177], v[182:185], v[50:53]
	v_mfma_f32_16x16x32_bf16 v[38:41], v[166:169], v[190:193], v[38:41]
	v_mfma_f32_16x16x32_bf16 v[34:37], v[174:177], v[190:193], v[34:37]
	v_mfma_f32_16x16x32_bf16 v[22:25], v[166:169], v[198:201], v[22:25]
	v_mfma_f32_16x16x32_bf16 v[18:21], v[174:177], v[198:201], v[18:21]
	v_mfma_f32_16x16x32_bf16 v[6:9], v[166:169], v[206:209], v[6:9]
	v_mfma_f32_16x16x32_bf16 v[2:5], v[174:177], v[206:209], v[2:5]
	s_add_i32 s94, s94, 2
	s_add_u32 s4, s4, 0x100
	s_addc_u32 s5, s5, 0
	s_add_u32 s15, s15, 0x100
	s_addc_u32 s21, s21, 0
	s_add_u32 s30, s4, 0xfff80080
	s_addc_u32 s31, s5, -1
	s_add_i32 s95, 0, 0x10000
	s_cmp_eq_u32 s94, 28
	s_cselect_b32 s41, s27, s31
	s_cselect_b32 s40, s26, s30
	s_cselect_b32 s31, s2, s21
	s_cselect_b32 s30, s3, s15
	s_add_i32 vcc_lo, 0, 0x14000
	s_cmp_gt_u32 s94, 29
	s_barrier
.LBB0_412:
	v_add_u32_e32 v149, s95, v147
	ds_read_b128 v[142:145], v149
	ds_read_b128 v[150:153], v149 offset:1024
	ds_read_b128 v[154:157], v149 offset:2048
	ds_read_b128 v[158:161], v149 offset:3072
	v_add_u32_e32 v149, vcc_lo, v147
	ds_read_b128 v[162:165], v149
	ds_read_b128 v[166:169], v149 offset:1024
	ds_read_b128 v[170:173], v149 offset:2048
	ds_read_b128 v[174:177], v149 offset:3072
	v_lshl_add_u64 v[210:211], s[4:5], 0, v[138:139]
	s_add_i32 m0, s35, 0xc000
	ds_read_b128 v[178:181], v148
	ds_read_b128 v[182:185], v148 offset:1024
	ds_read_b128 v[186:189], v148 offset:2048
	ds_read_b128 v[190:193], v148 offset:3072
	ds_read_b128 v[194:197], v148 offset:4096
	ds_read_b128 v[198:201], v148 offset:5120
	ds_read_b128 v[202:205], v148 offset:6144
	ds_read_b128 v[206:209], v148 offset:7168
	global_load_lds_dwordx4 v[210:211], off
	v_lshl_add_u64 v[210:211], s[4:5], 0, v[140:141]
	s_add_i32 m0, s35, 0xe000
	s_nop 0
	global_load_lds_dwordx4 v[210:211], off
	s_waitcnt vmcnt(8)
	s_waitcnt lgkmcnt(0)
	s_barrier
; #define PG8_STAGE(bufoff, gbase, voff) do { _Pragma("unroll") for (int _i = 0; _i < 2; ++_i) \
;         __builtin_amdgcn_global_load_lds((const unsigned*)((const char*)(gbase) + (voff)[_i]), (PG8_LAS unsigned*)(lds + (bufoff) + ldsw + _i * 8192), 16, 0, 0); } while (0)
; #define PG8_LDA(dst, b, h) do { _Pragma("unroll") for (int m = 0; m < 4; ++m) _Pragma("unroll") for (int k = 0; k < 2; ++k) dst[m][k] = *(const PG8_LAS bf16x8*)(lds + PG8_SA(b, h) + aoff + m * 2048 + k * 1024); } while (0)
; #define PG8_LDB(dst, b, h) do { _Pragma("unroll") for (int n = 0; n < 2; ++n) _Pragma("unroll") for (int k = 0; k < 2; ++k) dst[n][k] = *(const PG8_LAS bf16x8*)(lds + PG8_SB(b, h) + boff + n * 2048 + k * 1024); } while (0)
; #define PG8_MMA(ai, bj, At, Bt) do { __builtin_amdgcn_s_setprio(1); _Pragma("unroll") for (int m = 0; m < 4; ++m) _Pragma("unroll") for (int n = 0; n < 2; ++n) _Pragma("unroll") for (int k = 0; k < 2; ++k) \
;         acc[ai][bj][m][n] = __builtin_amdgcn_mfma_f32_16x16x32_bf16(Bt[n][k], At[m][k], acc[ai][bj][m][n], 0, 0, 0); __builtin_amdgcn_s_setprio(0); } while (0)
; #define PG8_WAIT_V(n) asm volatile("s_waitcnt vmcnt(" #n ")" ::: "memory")
; #define PG8_WAIT_L(n) asm volatile("s_waitcnt lgkmcnt(" #n ")" ::: "memory")
; #define PG8_BAR __builtin_amdgcn_s_barrier()
; #define PG8_SCHED __builtin_amdgcn_sched_barrier(0)
; template <class Epi, class Sched, bool ALIGN_EPI = false, bool SP2 = false>
; __device__ __forceinline__ void gemm_phase(PG8_LAS unsigned char* lds, const Gemm g, const Sched& S, const Epi& E, int wave_s) {
;     ...
;             PG8_WAIT_V(8); PG8_WAIT_L(0); PG8_BAR; PG8_MMA(0, 0, At, B0); PG8_MMA(0, 1, At, B1); PG8_BAR; PG8_SCHED;
;             PG8_LDA(At, 0, 1); PG8_STAGE(PG8_SB(0, 0), b2, voffB); PG8_STAGE(PG8_SB(0, 1), b2 + hstepB, voffB); PG8_STAGE(PG8_SA(0, 0), a2, voffA);
;             PG8_WAIT_V(8); PG8_WAIT_L(0); PG8_BAR; PG8_MMA(1, 0, At, B0); PG8_MMA(1, 1, At, B1); PG8_BAR; PG8_SCHED;
;             PG8_LDB(B0, 1, 0); PG8_LDB(B1, 1, 1); PG8_SCHED; PG8_LDA(At, 1, 0); PG8_STAGE(PG8_SA(0, 1), a2 + hstepA, voffA);
;             PG8_WAIT_V(8); PG8_WAIT_L(0); PG8_BAR; PG8_MMA(0, 0, At, B0); PG8_MMA(0, 1, At, B1); PG8_BAR; PG8_SCHED;
	s_waitcnt lgkmcnt(0)
	v_mfma_f32_16x16x32_bf16 v[126:129], v[142:145], v[178:181], v[126:129]
	v_mfma_f32_16x16x32_bf16 v[122:125], v[154:157], v[178:181], v[122:125]
	v_mfma_f32_16x16x32_bf16 v[110:113], v[142:145], v[186:189], v[110:113]
	v_mfma_f32_16x16x32_bf16 v[106:109], v[154:157], v[186:189], v[106:109]
	v_mfma_f32_16x16x32_bf16 v[94:97], v[142:145], v[194:197], v[94:97]
	v_mfma_f32_16x16x32_bf16 v[90:93], v[154:157], v[194:197], v[90:93]
	v_mfma_f32_16x16x32_bf16 v[78:81], v[142:145], v[202:205], v[78:81]
	v_mfma_f32_16x16x32_bf16 v[74:77], v[154:157], v[202:205], v[74:77]
	v_mfma_f32_16x16x32_bf16 v[126:129], v[150:153], v[182:185], v[126:129]
	v_mfma_f32_16x16x32_bf16 v[122:125], v[158:161], v[182:185], v[122:125]
	v_mfma_f32_16x16x32_bf16 v[110:113], v[150:153], v[190:193], v[110:113]
	v_mfma_f32_16x16x32_bf16 v[106:109], v[158:161], v[190:193], v[106:109]
	v_mfma_f32_16x16x32_bf16 v[94:97], v[150:153], v[198:201], v[94:97]
	v_mfma_f32_16x16x32_bf16 v[90:93], v[158:161], v[198:201], v[90:93]
	v_mfma_f32_16x16x32_bf16 v[78:81], v[150:153], v[206:209], v[78:81]
	v_mfma_f32_16x16x32_bf16 v[74:77], v[158:161], v[206:209], v[74:77]
	v_mfma_f32_16x16x32_bf16 v[118:121], v[162:165], v[178:181], v[118:121]
	v_mfma_f32_16x16x32_bf16 v[114:117], v[170:173], v[178:181], v[114:117]
	v_mfma_f32_16x16x32_bf16 v[102:105], v[162:165], v[186:189], v[102:105]
	v_mfma_f32_16x16x32_bf16 v[98:101], v[170:173], v[186:189], v[98:101]
	v_mfma_f32_16x16x32_bf16 v[86:89], v[162:165], v[194:197], v[86:89]
	v_mfma_f32_16x16x32_bf16 v[82:85], v[170:173], v[194:197], v[82:85]
	v_mfma_f32_16x16x32_bf16 v[70:73], v[162:165], v[202:205], v[70:73]
	v_mfma_f32_16x16x32_bf16 v[66:69], v[170:173], v[202:205], v[66:69]
	v_mfma_f32_16x16x32_bf16 v[118:121], v[166:169], v[182:185], v[118:121]
	v_mfma_f32_16x16x32_bf16 v[114:117], v[174:177], v[182:185], v[114:117]
	v_mfma_f32_16x16x32_bf16 v[102:105], v[166:169], v[190:193], v[102:105]
	v_mfma_f32_16x16x32_bf16 v[98:101], v[174:177], v[190:193], v[98:101]
	v_mfma_f32_16x16x32_bf16 v[86:89], v[166:169], v[198:201], v[86:89]
	v_mfma_f32_16x16x32_bf16 v[82:85], v[174:177], v[198:201], v[82:85]
	v_mfma_f32_16x16x32_bf16 v[70:73], v[166:169], v[206:209], v[70:73]
	v_mfma_f32_16x16x32_bf16 v[66:69], v[174:177], v[206:209], v[66:69]
	s_barrier
	s_add_i32 s95, s95, s34
	v_lshl_add_u64 v[210:211], s[30:31], 0, v[132:133]
	s_mov_b32 m0, s95
	ds_read_b128 v[178:181], v148 offset:16384
	ds_read_b128 v[182:185], v148 offset:17408
	ds_read_b128 v[186:189], v148 offset:18432
	ds_read_b128 v[190:193], v148 offset:19456
	ds_read_b128 v[194:197], v148 offset:20480
	ds_read_b128 v[198:201], v148 offset:21504
	ds_read_b128 v[202:205], v148 offset:22528
	ds_read_b128 v[206:209], v148 offset:23552
	global_load_lds_dwordx4 v[210:211], off
	s_add_i32 m0, s95, 0x2000
	s_add_u32 s96, s30, 0x80000
	v_lshl_add_u64 v[212:213], s[30:31], 0, v[136:137]
	s_addc_u32 s97, s31, 0
	s_add_i32 s95, vcc_lo, s34
	global_load_lds_dwordx4 v[212:213], off
	v_lshl_add_u64 v[214:215], s[96:97], 0, v[132:133]
	s_mov_b32 m0, s95
	v_lshl_add_u64 v[216:217], s[40:41], 0, v[134:135]
	global_load_lds_dwordx4 v[214:215], off
	v_lshl_add_u64 v[214:215], s[96:97], 0, v[136:137]
	s_add_i32 m0, s95, 0x2000
	s_nop 0
	global_load_lds_dwordx4 v[214:215], off
	v_lshl_add_u64 v[214:215], s[40:41], 0, v[130:131]
	s_mov_b32 m0, s35
	s_nop 0
	global_load_lds_dwordx4 v[214:215], off
	s_mov_b32 m0, s36
	s_nop 0
	global_load_lds_dwordx4 v[216:217], off
	s_waitcnt vmcnt(8)
	s_waitcnt lgkmcnt(0)
	s_barrier
	s_waitcnt lgkmcnt(0)
	v_mfma_f32_16x16x32_bf16 v[62:65], v[142:145], v[178:181], v[62:65]
	v_mfma_f32_16x16x32_bf16 v[58:61], v[154:157], v[178:181], v[58:61]
	v_mfma_f32_16x16x32_bf16 v[46:49], v[142:145], v[186:189], v[46:49]
	v_mfma_f32_16x16x32_bf16 v[42:45], v[154:157], v[186:189], v[42:45]
	v_mfma_f32_16x16x32_bf16 v[30:33], v[142:145], v[194:197], v[30:33]
	v_mfma_f32_16x16x32_bf16 v[26:29], v[154:157], v[194:197], v[26:29]
	v_mfma_f32_16x16x32_bf16 v[14:17], v[142:145], v[202:205], v[14:17]
	v_mfma_f32_16x16x32_bf16 v[10:13], v[154:157], v[202:205], v[10:13]
	v_mfma_f32_16x16x32_bf16 v[62:65], v[150:153], v[182:185], v[62:65]
	v_mfma_f32_16x16x32_bf16 v[58:61], v[158:161], v[182:185], v[58:61]
	v_mfma_f32_16x16x32_bf16 v[46:49], v[150:153], v[190:193], v[46:49]
	v_mfma_f32_16x16x32_bf16 v[42:45], v[158:161], v[190:193], v[42:45]
	v_mfma_f32_16x16x32_bf16 v[30:33], v[150:153], v[198:201], v[30:33]
	v_mfma_f32_16x16x32_bf16 v[26:29], v[158:161], v[198:201], v[26:29]
	v_mfma_f32_16x16x32_bf16 v[14:17], v[150:153], v[206:209], v[14:17]
	v_mfma_f32_16x16x32_bf16 v[10:13], v[158:161], v[206:209], v[10:13]
	v_mfma_f32_16x16x32_bf16 v[54:57], v[162:165], v[178:181], v[54:57]
	v_mfma_f32_16x16x32_bf16 v[50:53], v[170:173], v[178:181], v[50:53]
	v_mfma_f32_16x16x32_bf16 v[38:41], v[162:165], v[186:189], v[38:41]
	v_mfma_f32_16x16x32_bf16 v[34:37], v[170:173], v[186:189], v[34:37]
	v_mfma_f32_16x16x32_bf16 v[22:25], v[162:165], v[194:197], v[22:25]
	v_mfma_f32_16x16x32_bf16 v[18:21], v[170:173], v[194:197], v[18:21]
	v_mfma_f32_16x16x32_bf16 v[6:9], v[162:165], v[202:205], v[6:9]
	v_mfma_f32_16x16x32_bf16 v[2:5], v[170:173], v[202:205], v[2:5]
	v_mfma_f32_16x16x32_bf16 v[54:57], v[166:169], v[182:185], v[54:57]
	v_mfma_f32_16x16x32_bf16 v[50:53], v[174:177], v[182:185], v[50:53]
	v_mfma_f32_16x16x32_bf16 v[38:41], v[166:169], v[190:193], v[38:41]
	v_mfma_f32_16x16x32_bf16 v[34:37], v[174:177], v[190:193], v[34:37]
	v_mfma_f32_16x16x32_bf16 v[22:25], v[166:169], v[198:201], v[22:25]
	v_mfma_f32_16x16x32_bf16 v[18:21], v[174:177], v[198:201], v[18:21]
	v_mfma_f32_16x16x32_bf16 v[6:9], v[166:169], v[206:209], v[6:9]
	v_mfma_f32_16x16x32_bf16 v[2:5], v[174:177], v[206:209], v[2:5]
	s_barrier
; #define PG8_STAGE(bufoff, gbase, voff) do { _Pragma("unroll") for (int _i = 0; _i < 2; ++_i) \
;         __builtin_amdgcn_global_load_lds((const unsigned*)((const char*)(gbase) + (voff)[_i]), (PG8_LAS unsigned*)(lds + (bufoff) + ldsw + _i * 8192), 16, 0, 0); } while (0)
; #define PG8_LDA(dst, b, h) do { _Pragma("unroll") for (int m = 0; m < 4; ++m) _Pragma("unroll") for (int k = 0; k < 2; ++k) dst[m][k] = *(const PG8_LAS bf16x8*)(lds + PG8_SA(b, h) + aoff + m * 2048 + k * 1024); } while (0)
; #define PG8_LDB(dst, b, h) do { _Pragma("unroll") for (int n = 0; n < 2; ++n) _Pragma("unroll") for (int k = 0; k < 2; ++k) dst[n][k] = *(const PG8_LAS bf16x8*)(lds + PG8_SB(b, h) + boff + n * 2048 + k * 1024); } while (0)
; #define PG8_MMA(ai, bj, At, Bt) do { __builtin_amdgcn_s_setprio(1); _Pragma("unroll") for (int m = 0; m < 4; ++m) _Pragma("unroll") for (int n = 0; n < 2; ++n) _Pragma("unroll") for (int k = 0; k < 2; ++k) \
;         acc[ai][bj][m][n] = __builtin_amdgcn_mfma_f32_16x16x32_bf16(Bt[n][k], At[m][k], acc[ai][bj][m][n], 0, 0, 0); __builtin_amdgcn_s_setprio(0); } while (0)
; #define PG8_WAIT_V(n) asm volatile("s_waitcnt vmcnt(" #n ")" ::: "memory")
; #define PG8_WAIT_L(n) asm volatile("s_waitcnt lgkmcnt(" #n ")" ::: "memory")
; #define PG8_BAR __builtin_amdgcn_s_barrier()
; #define PG8_SCHED __builtin_amdgcn_sched_barrier(0)
; template <class Epi, class Sched, bool ALIGN_EPI = false, bool SP2 = false>
; __device__ __forceinline__ void gemm_phase(PG8_LAS unsigned char* lds, const Gemm g, const Sched& S, const Epi& E, int wave_s) {
;     ...
;             PG8_LDB(B0, 1, 0); PG8_LDB(B1, 1, 1); PG8_SCHED; PG8_LDA(At, 1, 0); PG8_STAGE(PG8_SA(0, 1), a2 + hstepA, voffA);
;             PG8_WAIT_V(8); PG8_WAIT_L(0); PG8_BAR; PG8_MMA(0, 0, At, B0); PG8_MMA(0, 1, At, B1); PG8_BAR; PG8_SCHED;
;             PG8_LDA(At, 1, 1); PG8_STAGE(PG8_SB(1, 0), b3, voffB); PG8_STAGE(PG8_SB(1, 1), b3 + hstepB, voffB); PG8_STAGE(PG8_SA(1, 0), a3, voffA);
	s_add_i32 s95, 0, 0x18000
	v_add_u32_e32 v149, s95, v147
	s_add_i32 s96, 0, 0x1c000
	ds_read_b128 v[142:145], v149
	ds_read_b128 v[150:153], v149 offset:1024
	ds_read_b128 v[154:157], v149 offset:2048
	ds_read_b128 v[158:161], v149 offset:3072
	v_add_u32_e32 v149, s96, v147
	ds_read_b128 v[162:165], v149
	ds_read_b128 v[166:169], v149 offset:1024
	ds_read_b128 v[170:173], v149 offset:2048
	ds_read_b128 v[174:177], v149 offset:3072
	s_add_u32 s40, s40, 0x80000
	s_addc_u32 s41, s41, 0
	s_mov_b32 m0, s37
	v_lshl_add_u64 v[218:219], s[40:41], 0, v[130:131]
	ds_read_b128 v[178:181], v148 offset:32768
	ds_read_b128 v[182:185], v148 offset:33792
	ds_read_b128 v[186:189], v148 offset:34816
	ds_read_b128 v[190:193], v148 offset:35840
	ds_read_b128 v[194:197], v148 offset:36864
	ds_read_b128 v[198:201], v148 offset:37888
	ds_read_b128 v[202:205], v148 offset:38912
	ds_read_b128 v[206:209], v148 offset:39936
	global_load_lds_dwordx4 v[218:219], off
	v_lshl_add_u64 v[218:219], s[40:41], 0, v[134:135]
	s_mov_b32 m0, s42
	s_nop 0
	global_load_lds_dwordx4 v[218:219], off
	s_waitcnt vmcnt(8)
	s_waitcnt lgkmcnt(0)
	s_barrier
	s_waitcnt lgkmcnt(0)
	v_mfma_f32_16x16x32_bf16 v[126:129], v[142:145], v[178:181], v[126:129]
	v_mfma_f32_16x16x32_bf16 v[122:125], v[154:157], v[178:181], v[122:125]
	v_mfma_f32_16x16x32_bf16 v[110:113], v[142:145], v[186:189], v[110:113]
	v_mfma_f32_16x16x32_bf16 v[106:109], v[154:157], v[186:189], v[106:109]
	v_mfma_f32_16x16x32_bf16 v[94:97], v[142:145], v[194:197], v[94:97]
	v_mfma_f32_16x16x32_bf16 v[90:93], v[154:157], v[194:197], v[90:93]
	v_mfma_f32_16x16x32_bf16 v[78:81], v[142:145], v[202:205], v[78:81]
	v_mfma_f32_16x16x32_bf16 v[74:77], v[154:157], v[202:205], v[74:77]
	v_mfma_f32_16x16x32_bf16 v[126:129], v[150:153], v[182:185], v[126:129]
	v_mfma_f32_16x16x32_bf16 v[122:125], v[158:161], v[182:185], v[122:125]
	v_mfma_f32_16x16x32_bf16 v[110:113], v[150:153], v[190:193], v[110:113]
	v_mfma_f32_16x16x32_bf16 v[106:109], v[158:161], v[190:193], v[106:109]
	v_mfma_f32_16x16x32_bf16 v[94:97], v[150:153], v[198:201], v[94:97]
	v_mfma_f32_16x16x32_bf16 v[90:93], v[158:161], v[198:201], v[90:93]
	v_mfma_f32_16x16x32_bf16 v[78:81], v[150:153], v[206:209], v[78:81]
	v_mfma_f32_16x16x32_bf16 v[74:77], v[158:161], v[206:209], v[74:77]
	v_mfma_f32_16x16x32_bf16 v[118:121], v[162:165], v[178:181], v[118:121]
	v_mfma_f32_16x16x32_bf16 v[114:117], v[170:173], v[178:181], v[114:117]
	v_mfma_f32_16x16x32_bf16 v[102:105], v[162:165], v[186:189], v[102:105]
	v_mfma_f32_16x16x32_bf16 v[98:101], v[170:173], v[186:189], v[98:101]
	v_mfma_f32_16x16x32_bf16 v[86:89], v[162:165], v[194:197], v[86:89]
	v_mfma_f32_16x16x32_bf16 v[82:85], v[170:173], v[194:197], v[82:85]
	v_mfma_f32_16x16x32_bf16 v[70:73], v[162:165], v[202:205], v[70:73]
	v_mfma_f32_16x16x32_bf16 v[66:69], v[170:173], v[202:205], v[66:69]
	v_mfma_f32_16x16x32_bf16 v[118:121], v[166:169], v[182:185], v[118:121]
	v_mfma_f32_16x16x32_bf16 v[114:117], v[174:177], v[182:185], v[114:117]
	v_mfma_f32_16x16x32_bf16 v[102:105], v[166:169], v[190:193], v[102:105]
	v_mfma_f32_16x16x32_bf16 v[98:101], v[174:177], v[190:193], v[98:101]
	v_mfma_f32_16x16x32_bf16 v[86:89], v[166:169], v[198:201], v[86:89]
	v_mfma_f32_16x16x32_bf16 v[82:85], v[174:177], v[198:201], v[82:85]
	v_mfma_f32_16x16x32_bf16 v[70:73], v[166:169], v[206:209], v[70:73]
	v_mfma_f32_16x16x32_bf16 v[66:69], v[174:177], v[206:209], v[66:69]
	s_barrier
; #define PG8_STAGE(bufoff, gbase, voff) do { _Pragma("unroll") for (int _i = 0; _i < 2; ++_i) \
;         __builtin_amdgcn_global_load_lds((const unsigned*)((const char*)(gbase) + (voff)[_i]), (PG8_LAS unsigned*)(lds + (bufoff) + ldsw + _i * 8192), 16, 0, 0); } while (0)
; #define PG8_LDA(dst, b, h) do { _Pragma("unroll") for (int m = 0; m < 4; ++m) _Pragma("unroll") for (int k = 0; k < 2; ++k) dst[m][k] = *(const PG8_LAS bf16x8*)(lds + PG8_SA(b, h) + aoff + m * 2048 + k * 1024); } while (0)
; #define PG8_WAIT_V(n) asm volatile("s_waitcnt vmcnt(" #n ")" ::: "memory")
; #define PG8_WAIT_L(n) asm volatile("s_waitcnt lgkmcnt(" #n ")" ::: "memory")
; #define PG8_BAR __builtin_amdgcn_s_barrier()
; template <class Epi, class Sched, bool ALIGN_EPI = false, bool SP2 = false>
; __device__ __forceinline__ void gemm_phase(PG8_LAS unsigned char* lds, const Gemm g, const Sched& S, const Epi& E, int wave_s) {
;     ...
;         for (int t = 0; t < nt; t += 2) {
;             const bool last = (t == nt - 2);
;             const char* a1 = cA + (size_t)(t + 1) * kstep;
;             const char* a2 = last ? nA : cA + (size_t)(t + 2) * kstep; const char* b2 = last ? nB : cB + (size_t)(t + 2) * kstep;
;             const char* a3 = a2 + kstep; const char* b3 = b2 + kstep;
;             if (last && has_next) S.a_ready(nxt);
;             if constexpr (SP2) {
;             PG8_LDB(B0, 0, 0); PG8_LDB(B1, 0, 1); PG8_SCHED; PG8_LDA(At, 0, 0); PG8_STAGE(PG8_SA(1, 1), a1 + hstepA, voffA);
;             PG8_WAIT_V(8); PG8_WAIT_L(0); PG8_BAR; PG8_MMA(0, 0, At, B0); PG8_MMA(0, 1, At, B1); PG8_BAR; PG8_SCHED;
;             PG8_LDA(At, 0, 1); PG8_STAGE(PG8_SB(0, 0), b2, voffB); PG8_STAGE(PG8_SB(0, 1), b2 + hstepB, voffB); PG8_STAGE(PG8_SA(0, 0), a2, voffA);
;             PG8_WAIT_V(8); PG8_WAIT_L(0); PG8_BAR; PG8_MMA(1, 0, At, B0); PG8_MMA(1, 1, At, B1); PG8_BAR; PG8_SCHED;
;             PG8_LDB(B0, 1, 0); PG8_LDB(B1, 1, 1); PG8_SCHED; PG8_LDA(At, 1, 0); PG8_STAGE(PG8_SA(0, 1), a2 + hstepA, voffA);
;             PG8_WAIT_V(8); PG8_WAIT_L(0); PG8_BAR; PG8_MMA(0, 0, At, B0); PG8_MMA(0, 1, At, B1); PG8_BAR; PG8_SCHED;
;             PG8_LDA(At, 1, 1); PG8_STAGE(PG8_SB(1, 0), b3, voffB); PG8_STAGE(PG8_SB(1, 1), b3 + hstepB, voffB); PG8_STAGE(PG8_SA(1, 0), a3, voffA);
;             PG8_WAIT_V(8); PG8_WAIT_L(0); PG8_BAR; PG8_MMA(1, 0, At, B0); PG8_MMA(1, 1, At, B1); PG8_BAR; PG8_SCHED;
	s_add_i32 s40, s95, s34
	v_lshl_add_u64 v[210:211], v[210:211], 0, s[60:61]
	s_mov_b32 m0, s40
	ds_read_b128 v[178:181], v148 offset:49152
	ds_read_b128 v[182:185], v148 offset:50176
	ds_read_b128 v[186:189], v148 offset:51200
	ds_read_b128 v[190:193], v148 offset:52224
	ds_read_b128 v[194:197], v148 offset:53248
	ds_read_b128 v[198:201], v148 offset:54272
	ds_read_b128 v[202:205], v148 offset:55296
	ds_read_b128 v[206:209], v148 offset:56320
	global_load_lds_dwordx4 v[210:211], off
	s_add_i32 m0, s40, 0x2000
	s_add_u32 s30, s30, 0x80080
	v_lshl_add_u64 v[210:211], v[212:213], 0, s[60:61]
	s_addc_u32 s31, s31, 0
	s_add_i32 s40, s96, s34
	global_load_lds_dwordx4 v[210:211], off
	v_lshl_add_u64 v[210:211], s[30:31], 0, v[132:133]
	s_mov_b32 m0, s40
	s_nop 0
	global_load_lds_dwordx4 v[210:211], off
	v_lshl_add_u64 v[210:211], s[30:31], 0, v[136:137]
	s_add_i32 m0, s40, 0x2000
	s_nop 0
	global_load_lds_dwordx4 v[210:211], off
	v_lshl_add_u64 v[210:211], v[214:215], 0, s[60:61]
	s_mov_b32 m0, s45
	s_nop 0
	global_load_lds_dwordx4 v[210:211], off
	v_lshl_add_u64 v[210:211], v[216:217], 0, s[60:61]
	s_mov_b32 m0, s46
	s_nop 0
	global_load_lds_dwordx4 v[210:211], off
	s_waitcnt vmcnt(8)
	s_waitcnt lgkmcnt(0)
	s_barrier
	s_waitcnt lgkmcnt(0)
	v_mfma_f32_16x16x32_bf16 v[62:65], v[142:145], v[178:181], v[62:65]
	v_mfma_f32_16x16x32_bf16 v[58:61], v[154:157], v[178:181], v[58:61]
	v_mfma_f32_16x16x32_bf16 v[46:49], v[142:145], v[186:189], v[46:49]
	v_mfma_f32_16x16x32_bf16 v[42:45], v[154:157], v[186:189], v[42:45]
	v_mfma_f32_16x16x32_bf16 v[30:33], v[142:145], v[194:197], v[30:33]
	v_mfma_f32_16x16x32_bf16 v[26:29], v[154:157], v[194:197], v[26:29]
	v_mfma_f32_16x16x32_bf16 v[14:17], v[142:145], v[202:205], v[14:17]
	v_mfma_f32_16x16x32_bf16 v[10:13], v[154:157], v[202:205], v[10:13]
	v_mfma_f32_16x16x32_bf16 v[62:65], v[150:153], v[182:185], v[62:65]
	v_mfma_f32_16x16x32_bf16 v[58:61], v[158:161], v[182:185], v[58:61]
	v_mfma_f32_16x16x32_bf16 v[46:49], v[150:153], v[190:193], v[46:49]
	v_mfma_f32_16x16x32_bf16 v[42:45], v[158:161], v[190:193], v[42:45]
	v_mfma_f32_16x16x32_bf16 v[30:33], v[150:153], v[198:201], v[30:33]
	v_mfma_f32_16x16x32_bf16 v[26:29], v[158:161], v[198:201], v[26:29]
	v_mfma_f32_16x16x32_bf16 v[14:17], v[150:153], v[206:209], v[14:17]
	v_mfma_f32_16x16x32_bf16 v[10:13], v[158:161], v[206:209], v[10:13]
	v_mfma_f32_16x16x32_bf16 v[54:57], v[162:165], v[178:181], v[54:57]
	v_mfma_f32_16x16x32_bf16 v[50:53], v[170:173], v[178:181], v[50:53]
	v_mfma_f32_16x16x32_bf16 v[38:41], v[162:165], v[186:189], v[38:41]
	v_mfma_f32_16x16x32_bf16 v[34:37], v[170:173], v[186:189], v[34:37]
	v_mfma_f32_16x16x32_bf16 v[22:25], v[162:165], v[194:197], v[22:25]
	v_mfma_f32_16x16x32_bf16 v[18:21], v[170:173], v[194:197], v[18:21]
	v_mfma_f32_16x16x32_bf16 v[6:9], v[162:165], v[202:205], v[6:9]
	v_mfma_f32_16x16x32_bf16 v[2:5], v[170:173], v[202:205], v[2:5]
	v_mfma_f32_16x16x32_bf16 v[54:57], v[166:169], v[182:185], v[54:57]
	v_mfma_f32_16x16x32_bf16 v[50:53], v[174:177], v[182:185], v[50:53]
	v_mfma_f32_16x16x32_bf16 v[38:41], v[166:169], v[190:193], v[38:41]
	v_mfma_f32_16x16x32_bf16 v[34:37], v[174:177], v[190:193], v[34:37]
	v_mfma_f32_16x16x32_bf16 v[22:25], v[166:169], v[198:201], v[22:25]
	v_mfma_f32_16x16x32_bf16 v[18:21], v[174:177], v[198:201], v[18:21]
	v_mfma_f32_16x16x32_bf16 v[6:9], v[166:169], v[206:209], v[6:9]
	v_mfma_f32_16x16x32_bf16 v[2:5], v[174:177], v[206:209], v[2:5]
	s_add_i32 s94, s94, 2
	s_add_u32 s4, s4, 0x100
	s_addc_u32 s5, s5, 0
	s_add_u32 s15, s15, 0x100
	s_addc_u32 s21, s21, 0
	s_add_u32 s30, s4, 0xfff80080
	s_addc_u32 s31, s5, -1
	s_add_i32 s95, 0, 0x10000
	s_cmp_eq_u32 s94, 28
	s_cselect_b32 s41, s27, s31
	s_cselect_b32 s40, s26, s30
	s_cselect_b32 s31, s2, s21
	s_cselect_b32 s30, s3, s15
	s_add_i32 vcc_lo, 0, 0x14000
	s_cmp_gt_u32 s94, 29
	s_barrier
	s_cbranch_scc0 .LBB0_412
	s_and_b64 vcc, exec, s[12:13]
	s_cbranch_vccz .LBB0_415
	s_barrier

; #define PG8_STAGE(bufoff, gbase, voff) do { _Pragma("unroll") for (int _i = 0; _i < 2; ++_i) \
;         __builtin_amdgcn_global_load_lds((const unsigned*)((const char*)(gbase) + (voff)[_i]), (PG8_LAS unsigned*)(lds + (bufoff) + ldsw + _i * 8192), 16, 0, 0); } while (0)
; #define PG8_LDA(dst, b, h) do { _Pragma("unroll") for (int m = 0; m < 4; ++m) _Pragma("unroll") for (int k = 0; k < 2; ++k) dst[m][k] = *(const PG8_LAS bf16x8*)(lds + PG8_SA(b, h) + aoff + m * 2048 + k * 1024); } while (0)
; #define PG8_LDB(dst, b, h) do { _Pragma("unroll") for (int n = 0; n < 2; ++n) _Pragma("unroll") for (int k = 0; k < 2; ++k) dst[n][k] = *(const PG8_LAS bf16x8*)(lds + PG8_SB(b, h) + boff + n * 2048 + k * 1024); } while (0)
; #define PG8_WAIT_V(n) asm volatile("s_waitcnt vmcnt(" #n ")" ::: "memory")
; #define PG8_WAIT_L(n) asm volatile("s_waitcnt lgkmcnt(" #n ")" ::: "memory")
; #define PG8_BAR __builtin_amdgcn_s_barrier()
; template <class Epi, class Sched, bool ALIGN_EPI = false, bool SP2 = false>
; __device__ __forceinline__ void gemm_phase(PG8_LAS unsigned char* lds, const Gemm g, const Sched& S, const Epi& E, int wave_s) {
;     ...
;         const bool has_next = S.next(ui + 1, nxt);
;         const char* nA = has_next ? (const char*)g.A + (size_t)nxt.pm * tstepA + (size_t)(nxt.pn / g.npg) * (size_t)(K * 2) : cA; const char* nB = has_next ? (const char*)g.Bt + (size_t)nxt.pn * tstepB : cB;
;         for (int t = 0; t < nt; t += 2) {
;             const bool last = (t == nt - 2);
;             const char* a1 = cA + (size_t)(t + 1) * kstep;
;             const char* a2 = last ? nA : cA + (size_t)(t + 2) * kstep; const char* b2 = last ? nB : cB + (size_t)(t + 2) * kstep;
;             const char* a3 = a2 + kstep; const char* b3 = b2 + kstep;
;             if (last && has_next) S.a_ready(nxt);
;             if constexpr (SP2) {
;             PG8_LDB(B0, 0, 0); PG8_LDB(B1, 0, 1); PG8_SCHED; PG8_LDA(At, 0, 0); PG8_STAGE(PG8_SA(1, 1), a1 + hstepA, voffA);
;             PG8_WAIT_V(8); PG8_WAIT_L(0); PG8_BAR; PG8_MMA(0, 0, At, B0); PG8_MMA(0, 1, At, B1); PG8_BAR; PG8_SCHED;
;             PG8_LDA(At, 0, 1); PG8_STAGE(PG8_SB(0, 0), b2, voffB); PG8_STAGE(PG8_SB(0, 1), b2 + hstepB, voffB); PG8_STAGE(PG8_SA(0, 0), a2, voffA);
;             PG8_WAIT_V(8); PG8_WAIT_L(0); PG8_BAR; PG8_MMA(1, 0, At, B0); PG8_MMA(1, 1, At, B1); PG8_BAR; PG8_SCHED;
.LBB0_601:
	s_ashr_i32 s21, s20, 31
	s_lshl_b64 s[2:3], s[20:21], 20
	s_add_u32 s88, s22, s2
	s_addc_u32 s89, s23, s3
	s_and_b64 s[2:3], s[4:5], exec
	s_cselect_b32 s2, s89, s31
	s_cselect_b32 s3, s88, s30
	s_add_u32 s4, s40, 0x80080
	s_addc_u32 s5, s41, 0
	s_add_u32 s21, s30, 0x100
	s_addc_u32 s27, s31, 0
	s_mov_b32 s81, -2
	s_add_u32 s30, s4, 0xfff80080
	s_addc_u32 s31, s5, -1
	s_add_i32 s84, 0, 0x10000
	s_cmp_eq_u32 s81, 28
	s_cselect_b32 s41, s29, s31
	s_cselect_b32 s40, s28, s30
	s_cselect_b32 s31, s2, s27
	s_cselect_b32 s30, s3, s21
	s_add_i32 s90, 0, 0x14000
	v_add_u32_e32 v134, s84, v207
	v_add_u32_e32 v158, s90, v207
	ds_read_b128 v[118:121], v134
	ds_read_b128 v[126:129], v134 offset:1024
	ds_read_b128 v[130:133], v134 offset:2048
	ds_read_b128 v[134:137], v134 offset:3072
	ds_read_b128 v[138:141], v158
	ds_read_b128 v[142:145], v158 offset:1024
	ds_read_b128 v[154:157], v158 offset:2048
	ds_read_b128 v[158:161], v158 offset:3072
	v_lshl_add_u64 v[210:211], s[4:5], 0, v[198:199]
	s_add_i32 m0, s35, 0xc000
	ds_read_b128 v[162:165], v208
	ds_read_b128 v[166:169], v208 offset:1024
	ds_read_b128 v[170:173], v208 offset:2048
	ds_read_b128 v[174:177], v208 offset:3072
	ds_read_b128 v[178:181], v208 offset:4096
	ds_read_b128 v[182:185], v208 offset:5120
	ds_read_b128 v[186:189], v208 offset:6144
	ds_read_b128 v[202:205], v208 offset:7168
	global_load_lds_dwordx4 v[210:211], off
	v_lshl_add_u64 v[210:211], s[4:5], 0, v[200:201]
	s_add_i32 m0, s35, 0xe000
	s_nop 0
	global_load_lds_dwordx4 v[210:211], off
	s_waitcnt vmcnt(8)
	s_waitcnt lgkmcnt(0)
	s_barrier
	s_waitcnt lgkmcnt(0)
	v_mfma_f32_16x16x32_bf16 v[150:153], v[118:121], v[162:165], 0
	v_mfma_f32_16x16x32_bf16 v[146:149], v[130:133], v[162:165], 0
	v_mfma_f32_16x16x32_bf16 v[110:113], v[118:121], v[170:173], 0
	v_mfma_f32_16x16x32_bf16 v[106:109], v[130:133], v[170:173], 0
	v_mfma_f32_16x16x32_bf16 v[94:97], v[118:121], v[178:181], 0
	v_mfma_f32_16x16x32_bf16 v[90:93], v[130:133], v[178:181], 0
	v_mfma_f32_16x16x32_bf16 v[78:81], v[118:121], v[186:189], 0
	v_mfma_f32_16x16x32_bf16 v[74:77], v[130:133], v[186:189], 0
	v_mfma_f32_16x16x32_bf16 v[150:153], v[126:129], v[166:169], v[150:153]
	v_mfma_f32_16x16x32_bf16 v[146:149], v[134:137], v[166:169], v[146:149]
	v_mfma_f32_16x16x32_bf16 v[110:113], v[126:129], v[174:177], v[110:113]
	v_mfma_f32_16x16x32_bf16 v[106:109], v[134:137], v[174:177], v[106:109]
	v_mfma_f32_16x16x32_bf16 v[94:97], v[126:129], v[182:185], v[94:97]
	v_mfma_f32_16x16x32_bf16 v[90:93], v[134:137], v[182:185], v[90:93]
	v_mfma_f32_16x16x32_bf16 v[78:81], v[126:129], v[202:205], v[78:81]
	v_mfma_f32_16x16x32_bf16 v[74:77], v[134:137], v[202:205], v[74:77]
	v_mfma_f32_16x16x32_bf16 v[122:125], v[138:141], v[162:165], 0
	v_mfma_f32_16x16x32_bf16 v[114:117], v[154:157], v[162:165], 0
	v_mfma_f32_16x16x32_bf16 v[102:105], v[138:141], v[170:173], 0
	v_mfma_f32_16x16x32_bf16 v[98:101], v[154:157], v[170:173], 0
	v_mfma_f32_16x16x32_bf16 v[86:89], v[138:141], v[178:181], 0
	v_mfma_f32_16x16x32_bf16 v[82:85], v[154:157], v[178:181], 0
	v_mfma_f32_16x16x32_bf16 v[70:73], v[138:141], v[186:189], 0
	v_mfma_f32_16x16x32_bf16 v[66:69], v[154:157], v[186:189], 0
	v_mfma_f32_16x16x32_bf16 v[122:125], v[142:145], v[166:169], v[122:125]
	v_mfma_f32_16x16x32_bf16 v[114:117], v[158:161], v[166:169], v[114:117]
	v_mfma_f32_16x16x32_bf16 v[102:105], v[142:145], v[174:177], v[102:105]
	v_mfma_f32_16x16x32_bf16 v[98:101], v[158:161], v[174:177], v[98:101]
	v_mfma_f32_16x16x32_bf16 v[86:89], v[142:145], v[182:185], v[86:89]
	v_mfma_f32_16x16x32_bf16 v[82:85], v[158:161], v[182:185], v[82:85]
	v_mfma_f32_16x16x32_bf16 v[70:73], v[142:145], v[202:205], v[70:73]
	v_mfma_f32_16x16x32_bf16 v[66:69], v[158:161], v[202:205], v[66:69]
	s_barrier
	s_add_i32 s84, s84, s34
	v_lshl_add_u64 v[210:211], s[30:31], 0, v[194:195]
	s_mov_b32 m0, s84
	ds_read_b128 v[162:165], v208 offset:16384
	ds_read_b128 v[166:169], v208 offset:17408
	ds_read_b128 v[170:173], v208 offset:18432
	ds_read_b128 v[174:177], v208 offset:19456
	ds_read_b128 v[178:181], v208 offset:20480
	ds_read_b128 v[182:185], v208 offset:21504
	ds_read_b128 v[186:189], v208 offset:22528
	ds_read_b128 v[202:205], v208 offset:23552
	global_load_lds_dwordx4 v[210:211], off
	s_add_i32 m0, s84, 0x2000
	s_add_u32 s84, s30, 0x80000
	v_lshl_add_u64 v[212:213], s[30:31], 0, v[190:191]
	s_addc_u32 s85, s31, 0
	s_add_i32 s90, s90, s34
	global_load_lds_dwordx4 v[212:213], off
	v_lshl_add_u64 v[214:215], s[84:85], 0, v[194:195]
	s_mov_b32 m0, s90
	v_lshl_add_u64 v[216:217], s[40:41], 0, v[192:193]
	global_load_lds_dwordx4 v[214:215], off
	v_lshl_add_u64 v[214:215], s[84:85], 0, v[190:191]
	s_add_i32 m0, s90, 0x2000
	s_nop 0
	global_load_lds_dwordx4 v[214:215], off
	v_lshl_add_u64 v[214:215], s[40:41], 0, v[196:197]
	s_mov_b32 m0, s35
	s_nop 0
	global_load_lds_dwordx4 v[214:215], off
	s_mov_b32 m0, s36
	s_nop 0
	global_load_lds_dwordx4 v[216:217], off
	s_waitcnt vmcnt(8)
	s_waitcnt lgkmcnt(0)
	s_barrier
; #define PG8_STAGE(bufoff, gbase, voff) do { _Pragma("unroll") for (int _i = 0; _i < 2; ++_i) \
;         __builtin_amdgcn_global_load_lds((const unsigned*)((const char*)(gbase) + (voff)[_i]), (PG8_LAS unsigned*)(lds + (bufoff) + ldsw + _i * 8192), 16, 0, 0); } while (0)
; #define PG8_LDA(dst, b, h) do { _Pragma("unroll") for (int m = 0; m < 4; ++m) _Pragma("unroll") for (int k = 0; k < 2; ++k) dst[m][k] = *(const PG8_LAS bf16x8*)(lds + PG8_SA(b, h) + aoff + m * 2048 + k * 1024); } while (0)
; #define PG8_LDB(dst, b, h) do { _Pragma("unroll") for (int n = 0; n < 2; ++n) _Pragma("unroll") for (int k = 0; k < 2; ++k) dst[n][k] = *(const PG8_LAS bf16x8*)(lds + PG8_SB(b, h) + boff + n * 2048 + k * 1024); } while (0)
; #define PG8_MMA(ai, bj, At, Bt) do { __builtin_amdgcn_s_setprio(1); _Pragma("unroll") for (int m = 0; m < 4; ++m) _Pragma("unroll") for (int n = 0; n < 2; ++n) _Pragma("unroll") for (int k = 0; k < 2; ++k) \
;         acc[ai][bj][m][n] = __builtin_amdgcn_mfma_f32_16x16x32_bf16(Bt[n][k], At[m][k], acc[ai][bj][m][n], 0, 0, 0); __builtin_amdgcn_s_setprio(0); } while (0)
; #define PG8_WAIT_V(n) asm volatile("s_waitcnt vmcnt(" #n ")" ::: "memory")
; #define PG8_WAIT_L(n) asm volatile("s_waitcnt lgkmcnt(" #n ")" ::: "memory")
; #define PG8_BAR __builtin_amdgcn_s_barrier()
; #define PG8_SCHED __builtin_amdgcn_sched_barrier(0)
; template <class Epi, class Sched, bool ALIGN_EPI = false, bool SP2 = false>
; __device__ __forceinline__ void gemm_phase(PG8_LAS unsigned char* lds, const Gemm g, const Sched& S, const Epi& E, int wave_s) {
;     ...
;             PG8_WAIT_V(8); PG8_WAIT_L(0); PG8_BAR; PG8_MMA(1, 0, At, B0); PG8_MMA(1, 1, At, B1); PG8_BAR; PG8_SCHED;
;             PG8_LDB(B0, 1, 0); PG8_LDB(B1, 1, 1); PG8_SCHED; PG8_LDA(At, 1, 0); PG8_STAGE(PG8_SA(0, 1), a2 + hstepA, voffA);
;             PG8_WAIT_V(8); PG8_WAIT_L(0); PG8_BAR; PG8_MMA(0, 0, At, B0); PG8_MMA(0, 1, At, B1); PG8_BAR; PG8_SCHED;
;             PG8_LDA(At, 1, 1); PG8_STAGE(PG8_SB(1, 0), b3, voffB); PG8_STAGE(PG8_SB(1, 1), b3 + hstepB, voffB); PG8_STAGE(PG8_SA(1, 0), a3, voffA);
	s_waitcnt lgkmcnt(0)
	v_mfma_f32_16x16x32_bf16 v[62:65], v[118:121], v[162:165], 0
	v_mfma_f32_16x16x32_bf16 v[58:61], v[130:133], v[162:165], 0
	v_mfma_f32_16x16x32_bf16 v[46:49], v[118:121], v[170:173], 0
	v_mfma_f32_16x16x32_bf16 v[42:45], v[130:133], v[170:173], 0
	v_mfma_f32_16x16x32_bf16 v[30:33], v[118:121], v[178:181], 0
	v_mfma_f32_16x16x32_bf16 v[26:29], v[130:133], v[178:181], 0
	v_mfma_f32_16x16x32_bf16 v[14:17], v[118:121], v[186:189], 0
	v_mfma_f32_16x16x32_bf16 v[10:13], v[130:133], v[186:189], 0
	v_mfma_f32_16x16x32_bf16 v[62:65], v[126:129], v[166:169], v[62:65]
	v_mfma_f32_16x16x32_bf16 v[58:61], v[134:137], v[166:169], v[58:61]
	v_mfma_f32_16x16x32_bf16 v[46:49], v[126:129], v[174:177], v[46:49]
	v_mfma_f32_16x16x32_bf16 v[42:45], v[134:137], v[174:177], v[42:45]
	v_mfma_f32_16x16x32_bf16 v[30:33], v[126:129], v[182:185], v[30:33]
	v_mfma_f32_16x16x32_bf16 v[26:29], v[134:137], v[182:185], v[26:29]
	v_mfma_f32_16x16x32_bf16 v[14:17], v[126:129], v[202:205], v[14:17]
	v_mfma_f32_16x16x32_bf16 v[10:13], v[134:137], v[202:205], v[10:13]
	v_mfma_f32_16x16x32_bf16 v[54:57], v[138:141], v[162:165], 0
	v_mfma_f32_16x16x32_bf16 v[50:53], v[154:157], v[162:165], 0
	v_mfma_f32_16x16x32_bf16 v[38:41], v[138:141], v[170:173], 0
	v_mfma_f32_16x16x32_bf16 v[34:37], v[154:157], v[170:173], 0
	v_mfma_f32_16x16x32_bf16 v[22:25], v[138:141], v[178:181], 0
	v_mfma_f32_16x16x32_bf16 v[18:21], v[154:157], v[178:181], 0
	v_mfma_f32_16x16x32_bf16 v[6:9], v[138:141], v[186:189], 0
	v_mfma_f32_16x16x32_bf16 v[2:5], v[154:157], v[186:189], 0
	v_mfma_f32_16x16x32_bf16 v[54:57], v[142:145], v[166:169], v[54:57]
	v_mfma_f32_16x16x32_bf16 v[50:53], v[158:161], v[166:169], v[50:53]
	v_mfma_f32_16x16x32_bf16 v[38:41], v[142:145], v[174:177], v[38:41]
	v_mfma_f32_16x16x32_bf16 v[34:37], v[158:161], v[174:177], v[34:37]
	v_mfma_f32_16x16x32_bf16 v[22:25], v[142:145], v[182:185], v[22:25]
	v_mfma_f32_16x16x32_bf16 v[18:21], v[158:161], v[182:185], v[18:21]
	v_mfma_f32_16x16x32_bf16 v[6:9], v[142:145], v[202:205], v[6:9]
	v_mfma_f32_16x16x32_bf16 v[2:5], v[158:161], v[202:205], v[2:5]
	s_barrier
	s_add_i32 s84, 0, 0x18000
	s_add_i32 s85, 0, 0x1c000
	v_add_u32_e32 v134, s84, v207
	v_add_u32_e32 v158, s85, v207
	ds_read_b128 v[118:121], v134
	ds_read_b128 v[126:129], v134 offset:1024
	ds_read_b128 v[130:133], v134 offset:2048
	ds_read_b128 v[134:137], v134 offset:3072
	ds_read_b128 v[138:141], v158
	ds_read_b128 v[142:145], v158 offset:1024
	ds_read_b128 v[154:157], v158 offset:2048
	ds_read_b128 v[158:161], v158 offset:3072
	s_add_u32 s40, s40, 0x80000
	s_addc_u32 s41, s41, 0
	s_mov_b32 m0, s37
	v_lshl_add_u64 v[218:219], s[40:41], 0, v[196:197]
	ds_read_b128 v[162:165], v208 offset:32768
	ds_read_b128 v[166:169], v208 offset:33792
	ds_read_b128 v[170:173], v208 offset:34816
	ds_read_b128 v[174:177], v208 offset:35840
	ds_read_b128 v[178:181], v208 offset:36864
	ds_read_b128 v[182:185], v208 offset:37888
	ds_read_b128 v[186:189], v208 offset:38912
	ds_read_b128 v[202:205], v208 offset:39936
	global_load_lds_dwordx4 v[218:219], off
	v_lshl_add_u64 v[218:219], s[40:41], 0, v[192:193]
	s_mov_b32 m0, s42
	s_nop 0
	global_load_lds_dwordx4 v[218:219], off
	s_waitcnt vmcnt(8)
	s_waitcnt lgkmcnt(0)
	s_barrier
	s_waitcnt lgkmcnt(0)
	v_mfma_f32_16x16x32_bf16 v[150:153], v[118:121], v[162:165], v[150:153]
	v_mfma_f32_16x16x32_bf16 v[146:149], v[130:133], v[162:165], v[146:149]
	v_mfma_f32_16x16x32_bf16 v[110:113], v[118:121], v[170:173], v[110:113]
	v_mfma_f32_16x16x32_bf16 v[106:109], v[130:133], v[170:173], v[106:109]
	v_mfma_f32_16x16x32_bf16 v[94:97], v[118:121], v[178:181], v[94:97]
	v_mfma_f32_16x16x32_bf16 v[90:93], v[130:133], v[178:181], v[90:93]
	v_mfma_f32_16x16x32_bf16 v[78:81], v[118:121], v[186:189], v[78:81]
	v_mfma_f32_16x16x32_bf16 v[74:77], v[130:133], v[186:189], v[74:77]
	v_mfma_f32_16x16x32_bf16 v[150:153], v[126:129], v[166:169], v[150:153]
	v_mfma_f32_16x16x32_bf16 v[146:149], v[134:137], v[166:169], v[146:149]
	v_mfma_f32_16x16x32_bf16 v[110:113], v[126:129], v[174:177], v[110:113]
	v_mfma_f32_16x16x32_bf16 v[106:109], v[134:137], v[174:177], v[106:109]
	v_mfma_f32_16x16x32_bf16 v[94:97], v[126:129], v[182:185], v[94:97]
	v_mfma_f32_16x16x32_bf16 v[90:93], v[134:137], v[182:185], v[90:93]
	v_mfma_f32_16x16x32_bf16 v[78:81], v[126:129], v[202:205], v[78:81]
	v_mfma_f32_16x16x32_bf16 v[74:77], v[134:137], v[202:205], v[74:77]
	v_mfma_f32_16x16x32_bf16 v[122:125], v[138:141], v[162:165], v[122:125]
	v_mfma_f32_16x16x32_bf16 v[114:117], v[154:157], v[162:165], v[114:117]
	v_mfma_f32_16x16x32_bf16 v[102:105], v[138:141], v[170:173], v[102:105]
	v_mfma_f32_16x16x32_bf16 v[98:101], v[154:157], v[170:173], v[98:101]
	v_mfma_f32_16x16x32_bf16 v[86:89], v[138:141], v[178:181], v[86:89]
	v_mfma_f32_16x16x32_bf16 v[82:85], v[154:157], v[178:181], v[82:85]
	v_mfma_f32_16x16x32_bf16 v[70:73], v[138:141], v[186:189], v[70:73]
	v_mfma_f32_16x16x32_bf16 v[66:69], v[154:157], v[186:189], v[66:69]
	v_mfma_f32_16x16x32_bf16 v[122:125], v[142:145], v[166:169], v[122:125]
	v_mfma_f32_16x16x32_bf16 v[114:117], v[158:161], v[166:169], v[114:117]
	v_mfma_f32_16x16x32_bf16 v[102:105], v[142:145], v[174:177], v[102:105]
	v_mfma_f32_16x16x32_bf16 v[98:101], v[158:161], v[174:177], v[98:101]
	v_mfma_f32_16x16x32_bf16 v[86:89], v[142:145], v[182:185], v[86:89]
	v_mfma_f32_16x16x32_bf16 v[82:85], v[158:161], v[182:185], v[82:85]
	v_mfma_f32_16x16x32_bf16 v[70:73], v[142:145], v[202:205], v[70:73]
	v_mfma_f32_16x16x32_bf16 v[66:69], v[158:161], v[202:205], v[66:69]
	s_barrier
; #define PG8_STAGE(bufoff, gbase, voff) do { _Pragma("unroll") for (int _i = 0; _i < 2; ++_i) \
;         __builtin_amdgcn_global_load_lds((const unsigned*)((const char*)(gbase) + (voff)[_i]), (PG8_LAS unsigned*)(lds + (bufoff) + ldsw + _i * 8192), 16, 0, 0); } while (0)
; #define PG8_LDA(dst, b, h) do { _Pragma("unroll") for (int m = 0; m < 4; ++m) _Pragma("unroll") for (int k = 0; k < 2; ++k) dst[m][k] = *(const PG8_LAS bf16x8*)(lds + PG8_SA(b, h) + aoff + m * 2048 + k * 1024); } while (0)
; #define PG8_WAIT_V(n) asm volatile("s_waitcnt vmcnt(" #n ")" ::: "memory")
; #define PG8_WAIT_L(n) asm volatile("s_waitcnt lgkmcnt(" #n ")" ::: "memory")
; #define PG8_BAR __builtin_amdgcn_s_barrier()
; template <class Epi, class Sched, bool ALIGN_EPI = false, bool SP2 = false>
; __device__ __forceinline__ void gemm_phase(PG8_LAS unsigned char* lds, const Gemm g, const Sched& S, const Epi& E, int wave_s) {
;     ...
;         for (int t = 0; t < nt; t += 2) {
;             const bool last = (t == nt - 2);
;             const char* a1 = cA + (size_t)(t + 1) * kstep;
;             const char* a2 = last ? nA : cA + (size_t)(t + 2) * kstep; const char* b2 = last ? nB : cB + (size_t)(t + 2) * kstep;
;             const char* a3 = a2 + kstep; const char* b3 = b2 + kstep;
;             if (last && has_next) S.a_ready(nxt);
;             if constexpr (SP2) {
;             PG8_LDB(B0, 0, 0); PG8_LDB(B1, 0, 1); PG8_SCHED; PG8_LDA(At, 0, 0); PG8_STAGE(PG8_SA(1, 1), a1 + hstepA, voffA);
;             PG8_WAIT_V(8); PG8_WAIT_L(0); PG8_BAR; PG8_MMA(0, 0, At, B0); PG8_MMA(0, 1, At, B1); PG8_BAR; PG8_SCHED;
;             PG8_LDA(At, 0, 1); PG8_STAGE(PG8_SB(0, 0), b2, voffB); PG8_STAGE(PG8_SB(0, 1), b2 + hstepB, voffB); PG8_STAGE(PG8_SA(0, 0), a2, voffA);
;             PG8_WAIT_V(8); PG8_WAIT_L(0); PG8_BAR; PG8_MMA(1, 0, At, B0); PG8_MMA(1, 1, At, B1); PG8_BAR; PG8_SCHED;
;             PG8_LDB(B0, 1, 0); PG8_LDB(B1, 1, 1); PG8_SCHED; PG8_LDA(At, 1, 0); PG8_STAGE(PG8_SA(0, 1), a2 + hstepA, voffA);
;             PG8_WAIT_V(8); PG8_WAIT_L(0); PG8_BAR; PG8_MMA(0, 0, At, B0); PG8_MMA(0, 1, At, B1); PG8_BAR; PG8_SCHED;
;             PG8_LDA(At, 1, 1); PG8_STAGE(PG8_SB(1, 0), b3, voffB); PG8_STAGE(PG8_SB(1, 1), b3 + hstepB, voffB); PG8_STAGE(PG8_SA(1, 0), a3, voffA);
;             PG8_WAIT_V(8); PG8_WAIT_L(0); PG8_BAR; PG8_MMA(1, 0, At, B0); PG8_MMA(1, 1, At, B1); PG8_BAR; PG8_SCHED;
	s_add_i32 s40, s84, s34
	v_lshl_add_u64 v[210:211], v[210:211], 0, s[60:61]
	s_mov_b32 m0, s40
	ds_read_b128 v[162:165], v208 offset:49152
	ds_read_b128 v[166:169], v208 offset:50176
	ds_read_b128 v[170:173], v208 offset:51200
	ds_read_b128 v[174:177], v208 offset:52224
	ds_read_b128 v[178:181], v208 offset:53248
	ds_read_b128 v[182:185], v208 offset:54272
	ds_read_b128 v[186:189], v208 offset:55296
	ds_read_b128 v[202:205], v208 offset:56320
	global_load_lds_dwordx4 v[210:211], off
	s_add_i32 m0, s40, 0x2000
	s_add_u32 s30, s30, 0x80080
	v_lshl_add_u64 v[210:211], v[212:213], 0, s[60:61]
	s_addc_u32 s31, s31, 0
	s_add_i32 s40, s85, s34
	global_load_lds_dwordx4 v[210:211], off
	v_lshl_add_u64 v[210:211], s[30:31], 0, v[194:195]
	s_mov_b32 m0, s40
	s_nop 0
	global_load_lds_dwordx4 v[210:211], off
	v_lshl_add_u64 v[210:211], s[30:31], 0, v[190:191]
	s_add_i32 m0, s40, 0x2000
	s_nop 0
	global_load_lds_dwordx4 v[210:211], off
	v_lshl_add_u64 v[210:211], v[214:215], 0, s[60:61]
	s_mov_b32 m0, s46
	s_nop 0
	global_load_lds_dwordx4 v[210:211], off
	v_lshl_add_u64 v[210:211], v[216:217], 0, s[60:61]
	s_mov_b32 m0, s47
	s_nop 0
	global_load_lds_dwordx4 v[210:211], off
	s_waitcnt vmcnt(8)
	s_waitcnt lgkmcnt(0)
	s_barrier
	s_waitcnt lgkmcnt(0)
	v_mfma_f32_16x16x32_bf16 v[62:65], v[118:121], v[162:165], v[62:65]
	v_mfma_f32_16x16x32_bf16 v[58:61], v[130:133], v[162:165], v[58:61]
	v_mfma_f32_16x16x32_bf16 v[46:49], v[118:121], v[170:173], v[46:49]
	v_mfma_f32_16x16x32_bf16 v[42:45], v[130:133], v[170:173], v[42:45]
	v_mfma_f32_16x16x32_bf16 v[30:33], v[118:121], v[178:181], v[30:33]
	v_mfma_f32_16x16x32_bf16 v[26:29], v[130:133], v[178:181], v[26:29]
	v_mfma_f32_16x16x32_bf16 v[14:17], v[118:121], v[186:189], v[14:17]
	v_mfma_f32_16x16x32_bf16 v[10:13], v[130:133], v[186:189], v[10:13]
	v_mfma_f32_16x16x32_bf16 v[62:65], v[126:129], v[166:169], v[62:65]
	v_mfma_f32_16x16x32_bf16 v[58:61], v[134:137], v[166:169], v[58:61]
	v_mfma_f32_16x16x32_bf16 v[46:49], v[126:129], v[174:177], v[46:49]
	v_mfma_f32_16x16x32_bf16 v[42:45], v[134:137], v[174:177], v[42:45]
	v_mfma_f32_16x16x32_bf16 v[30:33], v[126:129], v[182:185], v[30:33]
	v_mfma_f32_16x16x32_bf16 v[26:29], v[134:137], v[182:185], v[26:29]
	v_mfma_f32_16x16x32_bf16 v[14:17], v[126:129], v[202:205], v[14:17]
	v_mfma_f32_16x16x32_bf16 v[10:13], v[134:137], v[202:205], v[10:13]
	v_mfma_f32_16x16x32_bf16 v[54:57], v[138:141], v[162:165], v[54:57]
	v_mfma_f32_16x16x32_bf16 v[50:53], v[154:157], v[162:165], v[50:53]
	v_mfma_f32_16x16x32_bf16 v[38:41], v[138:141], v[170:173], v[38:41]
	v_mfma_f32_16x16x32_bf16 v[34:37], v[154:157], v[170:173], v[34:37]
	v_mfma_f32_16x16x32_bf16 v[22:25], v[138:141], v[178:181], v[22:25]
	v_mfma_f32_16x16x32_bf16 v[18:21], v[154:157], v[178:181], v[18:21]
	v_mfma_f32_16x16x32_bf16 v[6:9], v[138:141], v[186:189], v[6:9]
	v_mfma_f32_16x16x32_bf16 v[2:5], v[154:157], v[186:189], v[2:5]
	v_mfma_f32_16x16x32_bf16 v[54:57], v[142:145], v[166:169], v[54:57]
	v_mfma_f32_16x16x32_bf16 v[50:53], v[158:161], v[166:169], v[50:53]
	v_mfma_f32_16x16x32_bf16 v[38:41], v[142:145], v[174:177], v[38:41]
	v_mfma_f32_16x16x32_bf16 v[34:37], v[158:161], v[174:177], v[34:37]
	v_mfma_f32_16x16x32_bf16 v[22:25], v[142:145], v[182:185], v[22:25]
	v_mfma_f32_16x16x32_bf16 v[18:21], v[158:161], v[182:185], v[18:21]
	v_mfma_f32_16x16x32_bf16 v[6:9], v[142:145], v[202:205], v[6:9]
	v_mfma_f32_16x16x32_bf16 v[2:5], v[158:161], v[202:205], v[2:5]
	s_add_i32 s81, s81, 2
	s_add_u32 s4, s4, 0x100
	s_addc_u32 s5, s5, 0
	s_add_u32 s21, s21, 0x100
	s_addc_u32 s27, s27, 0
	s_add_u32 s30, s4, 0xfff80080
	s_addc_u32 s31, s5, -1
	s_add_i32 s84, 0, 0x10000
	s_cmp_eq_u32 s81, 28
	s_cselect_b32 s41, s29, s31
	s_cselect_b32 s40, s28, s30
	s_cselect_b32 s31, s2, s27
	s_cselect_b32 s30, s3, s21
	s_add_i32 s90, 0, 0x14000
	s_cmp_gt_u32 s81, 29
	s_barrier
.LBB0_602:
	v_add_u32_e32 v134, s84, v207
	v_add_u32_e32 v158, s90, v207
	ds_read_b128 v[118:121], v134
	ds_read_b128 v[126:129], v134 offset:1024
	ds_read_b128 v[130:133], v134 offset:2048
	ds_read_b128 v[134:137], v134 offset:3072
	ds_read_b128 v[138:141], v158
	ds_read_b128 v[142:145], v158 offset:1024
	ds_read_b128 v[154:157], v158 offset:2048
	ds_read_b128 v[158:161], v158 offset:3072
	v_lshl_add_u64 v[210:211], s[4:5], 0, v[198:199]
	s_add_i32 m0, s35, 0xc000
	ds_read_b128 v[162:165], v208
	ds_read_b128 v[166:169], v208 offset:1024
	ds_read_b128 v[170:173], v208 offset:2048
	ds_read_b128 v[174:177], v208 offset:3072
	ds_read_b128 v[178:181], v208 offset:4096
	ds_read_b128 v[182:185], v208 offset:5120
	ds_read_b128 v[186:189], v208 offset:6144
	ds_read_b128 v[202:205], v208 offset:7168
	global_load_lds_dwordx4 v[210:211], off
	v_lshl_add_u64 v[210:211], s[4:5], 0, v[200:201]
	s_add_i32 m0, s35, 0xe000
	s_nop 0
	global_load_lds_dwordx4 v[210:211], off
	s_waitcnt vmcnt(8)
	s_waitcnt lgkmcnt(0)
	s_barrier
; #define PG8_STAGE(bufoff, gbase, voff) do { _Pragma("unroll") for (int _i = 0; _i < 2; ++_i) \
;         __builtin_amdgcn_global_load_lds((const unsigned*)((const char*)(gbase) + (voff)[_i]), (PG8_LAS unsigned*)(lds + (bufoff) + ldsw + _i * 8192), 16, 0, 0); } while (0)
; #define PG8_LDA(dst, b, h) do { _Pragma("unroll") for (int m = 0; m < 4; ++m) _Pragma("unroll") for (int k = 0; k < 2; ++k) dst[m][k] = *(const PG8_LAS bf16x8*)(lds + PG8_SA(b, h) + aoff + m * 2048 + k * 1024); } while (0)
; #define PG8_LDB(dst, b, h) do { _Pragma("unroll") for (int n = 0; n < 2; ++n) _Pragma("unroll") for (int k = 0; k < 2; ++k) dst[n][k] = *(const PG8_LAS bf16x8*)(lds + PG8_SB(b, h) + boff + n * 2048 + k * 1024); } while (0)
; #define PG8_MMA(ai, bj, At, Bt) do { __builtin_amdgcn_s_setprio(1); _Pragma("unroll") for (int m = 0; m < 4; ++m) _Pragma("unroll") for (int n = 0; n < 2; ++n) _Pragma("unroll") for (int k = 0; k < 2; ++k) \
;         acc[ai][bj][m][n] = __builtin_amdgcn_mfma_f32_16x16x32_bf16(Bt[n][k], At[m][k], acc[ai][bj][m][n], 0, 0, 0); __builtin_amdgcn_s_setprio(0); } while (0)
; #define PG8_WAIT_V(n) asm volatile("s_waitcnt vmcnt(" #n ")" ::: "memory")
; #define PG8_WAIT_L(n) asm volatile("s_waitcnt lgkmcnt(" #n ")" ::: "memory")
; #define PG8_BAR __builtin_amdgcn_s_barrier()
; #define PG8_SCHED __builtin_amdgcn_sched_barrier(0)
; template <class Epi, class Sched, bool ALIGN_EPI = false, bool SP2 = false>
; __device__ __forceinline__ void gemm_phase(PG8_LAS unsigned char* lds, const Gemm g, const Sched& S, const Epi& E, int wave_s) {
;     ...
;             PG8_LDB(B0, 0, 0); PG8_LDB(B1, 0, 1); PG8_SCHED; PG8_LDA(At, 0, 0); PG8_STAGE(PG8_SA(1, 1), a1 + hstepA, voffA);
;             PG8_WAIT_V(8); PG8_WAIT_L(0); PG8_BAR; PG8_MMA(0, 0, At, B0); PG8_MMA(0, 1, At, B1); PG8_BAR; PG8_SCHED;
;             PG8_LDA(At, 0, 1); PG8_STAGE(PG8_SB(0, 0), b2, voffB); PG8_STAGE(PG8_SB(0, 1), b2 + hstepB, voffB); PG8_STAGE(PG8_SA(0, 0), a2, voffA);
;             PG8_WAIT_V(8); PG8_WAIT_L(0); PG8_BAR; PG8_MMA(1, 0, At, B0); PG8_MMA(1, 1, At, B1); PG8_BAR; PG8_SCHED;
	s_waitcnt lgkmcnt(0)
	v_mfma_f32_16x16x32_bf16 v[150:153], v[118:121], v[162:165], v[150:153]
	v_mfma_f32_16x16x32_bf16 v[146:149], v[130:133], v[162:165], v[146:149]
	v_mfma_f32_16x16x32_bf16 v[110:113], v[118:121], v[170:173], v[110:113]
	v_mfma_f32_16x16x32_bf16 v[106:109], v[130:133], v[170:173], v[106:109]
	v_mfma_f32_16x16x32_bf16 v[94:97], v[118:121], v[178:181], v[94:97]
	v_mfma_f32_16x16x32_bf16 v[90:93], v[130:133], v[178:181], v[90:93]
	v_mfma_f32_16x16x32_bf16 v[78:81], v[118:121], v[186:189], v[78:81]
	v_mfma_f32_16x16x32_bf16 v[74:77], v[130:133], v[186:189], v[74:77]
	v_mfma_f32_16x16x32_bf16 v[150:153], v[126:129], v[166:169], v[150:153]
	v_mfma_f32_16x16x32_bf16 v[146:149], v[134:137], v[166:169], v[146:149]
	v_mfma_f32_16x16x32_bf16 v[110:113], v[126:129], v[174:177], v[110:113]
	v_mfma_f32_16x16x32_bf16 v[106:109], v[134:137], v[174:177], v[106:109]
	v_mfma_f32_16x16x32_bf16 v[94:97], v[126:129], v[182:185], v[94:97]
	v_mfma_f32_16x16x32_bf16 v[90:93], v[134:137], v[182:185], v[90:93]
	v_mfma_f32_16x16x32_bf16 v[78:81], v[126:129], v[202:205], v[78:81]
	v_mfma_f32_16x16x32_bf16 v[74:77], v[134:137], v[202:205], v[74:77]
	v_mfma_f32_16x16x32_bf16 v[122:125], v[138:141], v[162:165], v[122:125]
	v_mfma_f32_16x16x32_bf16 v[114:117], v[154:157], v[162:165], v[114:117]
	v_mfma_f32_16x16x32_bf16 v[102:105], v[138:141], v[170:173], v[102:105]
	v_mfma_f32_16x16x32_bf16 v[98:101], v[154:157], v[170:173], v[98:101]
	v_mfma_f32_16x16x32_bf16 v[86:89], v[138:141], v[178:181], v[86:89]
	v_mfma_f32_16x16x32_bf16 v[82:85], v[154:157], v[178:181], v[82:85]
	v_mfma_f32_16x16x32_bf16 v[70:73], v[138:141], v[186:189], v[70:73]
	v_mfma_f32_16x16x32_bf16 v[66:69], v[154:157], v[186:189], v[66:69]
	v_mfma_f32_16x16x32_bf16 v[122:125], v[142:145], v[166:169], v[122:125]
	v_mfma_f32_16x16x32_bf16 v[114:117], v[158:161], v[166:169], v[114:117]
	v_mfma_f32_16x16x32_bf16 v[102:105], v[142:145], v[174:177], v[102:105]
	v_mfma_f32_16x16x32_bf16 v[98:101], v[158:161], v[174:177], v[98:101]
	v_mfma_f32_16x16x32_bf16 v[86:89], v[142:145], v[182:185], v[86:89]
	v_mfma_f32_16x16x32_bf16 v[82:85], v[158:161], v[182:185], v[82:85]
	v_mfma_f32_16x16x32_bf16 v[70:73], v[142:145], v[202:205], v[70:73]
	v_mfma_f32_16x16x32_bf16 v[66:69], v[158:161], v[202:205], v[66:69]
	s_barrier
	s_add_i32 s84, s84, s34
	v_lshl_add_u64 v[210:211], s[30:31], 0, v[194:195]
	s_mov_b32 m0, s84
	ds_read_b128 v[162:165], v208 offset:16384
	ds_read_b128 v[166:169], v208 offset:17408
	ds_read_b128 v[170:173], v208 offset:18432
	ds_read_b128 v[174:177], v208 offset:19456
	ds_read_b128 v[178:181], v208 offset:20480
	ds_read_b128 v[182:185], v208 offset:21504
	ds_read_b128 v[186:189], v208 offset:22528
	ds_read_b128 v[202:205], v208 offset:23552
	global_load_lds_dwordx4 v[210:211], off
	s_add_i32 m0, s84, 0x2000
	s_add_u32 s84, s30, 0x80000
	v_lshl_add_u64 v[212:213], s[30:31], 0, v[190:191]
	s_addc_u32 s85, s31, 0
	s_add_i32 s90, s90, s34
	global_load_lds_dwordx4 v[212:213], off
	v_lshl_add_u64 v[214:215], s[84:85], 0, v[194:195]
	s_mov_b32 m0, s90
	v_lshl_add_u64 v[216:217], s[40:41], 0, v[192:193]
	global_load_lds_dwordx4 v[214:215], off
	v_lshl_add_u64 v[214:215], s[84:85], 0, v[190:191]
	s_add_i32 m0, s90, 0x2000
	s_nop 0
	global_load_lds_dwordx4 v[214:215], off
	v_lshl_add_u64 v[214:215], s[40:41], 0, v[196:197]
	s_mov_b32 m0, s35
	s_nop 0
	global_load_lds_dwordx4 v[214:215], off
	s_mov_b32 m0, s36
	s_nop 0
	global_load_lds_dwordx4 v[216:217], off
	s_waitcnt vmcnt(8)
	s_waitcnt lgkmcnt(0)
	s_barrier
	s_waitcnt lgkmcnt(0)
	v_mfma_f32_16x16x32_bf16 v[62:65], v[118:121], v[162:165], v[62:65]
	v_mfma_f32_16x16x32_bf16 v[58:61], v[130:133], v[162:165], v[58:61]
	v_mfma_f32_16x16x32_bf16 v[46:49], v[118:121], v[170:173], v[46:49]
	v_mfma_f32_16x16x32_bf16 v[42:45], v[130:133], v[170:173], v[42:45]
	v_mfma_f32_16x16x32_bf16 v[30:33], v[118:121], v[178:181], v[30:33]
	v_mfma_f32_16x16x32_bf16 v[26:29], v[130:133], v[178:181], v[26:29]
	v_mfma_f32_16x16x32_bf16 v[14:17], v[118:121], v[186:189], v[14:17]
	v_mfma_f32_16x16x32_bf16 v[10:13], v[130:133], v[186:189], v[10:13]
	v_mfma_f32_16x16x32_bf16 v[62:65], v[126:129], v[166:169], v[62:65]
	v_mfma_f32_16x16x32_bf16 v[58:61], v[134:137], v[166:169], v[58:61]
	v_mfma_f32_16x16x32_bf16 v[46:49], v[126:129], v[174:177], v[46:49]
	v_mfma_f32_16x16x32_bf16 v[42:45], v[134:137], v[174:177], v[42:45]
	v_mfma_f32_16x16x32_bf16 v[30:33], v[126:129], v[182:185], v[30:33]
	v_mfma_f32_16x16x32_bf16 v[26:29], v[134:137], v[182:185], v[26:29]
	v_mfma_f32_16x16x32_bf16 v[14:17], v[126:129], v[202:205], v[14:17]
	v_mfma_f32_16x16x32_bf16 v[10:13], v[134:137], v[202:205], v[10:13]
	v_mfma_f32_16x16x32_bf16 v[54:57], v[138:141], v[162:165], v[54:57]
	v_mfma_f32_16x16x32_bf16 v[50:53], v[154:157], v[162:165], v[50:53]
	v_mfma_f32_16x16x32_bf16 v[38:41], v[138:141], v[170:173], v[38:41]
	v_mfma_f32_16x16x32_bf16 v[34:37], v[154:157], v[170:173], v[34:37]
	v_mfma_f32_16x16x32_bf16 v[22:25], v[138:141], v[178:181], v[22:25]
	v_mfma_f32_16x16x32_bf16 v[18:21], v[154:157], v[178:181], v[18:21]
	v_mfma_f32_16x16x32_bf16 v[6:9], v[138:141], v[186:189], v[6:9]
	v_mfma_f32_16x16x32_bf16 v[2:5], v[154:157], v[186:189], v[2:5]
	v_mfma_f32_16x16x32_bf16 v[54:57], v[142:145], v[166:169], v[54:57]
	v_mfma_f32_16x16x32_bf16 v[50:53], v[158:161], v[166:169], v[50:53]
	v_mfma_f32_16x16x32_bf16 v[38:41], v[142:145], v[174:177], v[38:41]
	v_mfma_f32_16x16x32_bf16 v[34:37], v[158:161], v[174:177], v[34:37]
	v_mfma_f32_16x16x32_bf16 v[22:25], v[142:145], v[182:185], v[22:25]
	v_mfma_f32_16x16x32_bf16 v[18:21], v[158:161], v[182:185], v[18:21]
	v_mfma_f32_16x16x32_bf16 v[6:9], v[142:145], v[202:205], v[6:9]
	v_mfma_f32_16x16x32_bf16 v[2:5], v[158:161], v[202:205], v[2:5]
	s_barrier
; #define PG8_STAGE(bufoff, gbase, voff) do { _Pragma("unroll") for (int _i = 0; _i < 2; ++_i) \
;         __builtin_amdgcn_global_load_lds((const unsigned*)((const char*)(gbase) + (voff)[_i]), (PG8_LAS unsigned*)(lds + (bufoff) + ldsw + _i * 8192), 16, 0, 0); } while (0)
; #define PG8_LDA(dst, b, h) do { _Pragma("unroll") for (int m = 0; m < 4; ++m) _Pragma("unroll") for (int k = 0; k < 2; ++k) dst[m][k] = *(const PG8_LAS bf16x8*)(lds + PG8_SA(b, h) + aoff + m * 2048 + k * 1024); } while (0)
; #define PG8_LDB(dst, b, h) do { _Pragma("unroll") for (int n = 0; n < 2; ++n) _Pragma("unroll") for (int k = 0; k < 2; ++k) dst[n][k] = *(const PG8_LAS bf16x8*)(lds + PG8_SB(b, h) + boff + n * 2048 + k * 1024); } while (0)
; #define PG8_MMA(ai, bj, At, Bt) do { __builtin_amdgcn_s_setprio(1); _Pragma("unroll") for (int m = 0; m < 4; ++m) _Pragma("unroll") for (int n = 0; n < 2; ++n) _Pragma("unroll") for (int k = 0; k < 2; ++k) \
;         acc[ai][bj][m][n] = __builtin_amdgcn_mfma_f32_16x16x32_bf16(Bt[n][k], At[m][k], acc[ai][bj][m][n], 0, 0, 0); __builtin_amdgcn_s_setprio(0); } while (0)
; #define PG8_WAIT_V(n) asm volatile("s_waitcnt vmcnt(" #n ")" ::: "memory")
; #define PG8_WAIT_L(n) asm volatile("s_waitcnt lgkmcnt(" #n ")" ::: "memory")
; #define PG8_BAR __builtin_amdgcn_s_barrier()
; #define PG8_SCHED __builtin_amdgcn_sched_barrier(0)
; template <class Epi, class Sched, bool ALIGN_EPI = false, bool SP2 = false>
; __device__ __forceinline__ void gemm_phase(PG8_LAS unsigned char* lds, const Gemm g, const Sched& S, const Epi& E, int wave_s) {
;     ...
;             PG8_LDB(B0, 1, 0); PG8_LDB(B1, 1, 1); PG8_SCHED; PG8_LDA(At, 1, 0); PG8_STAGE(PG8_SA(0, 1), a2 + hstepA, voffA);
;             PG8_WAIT_V(8); PG8_WAIT_L(0); PG8_BAR; PG8_MMA(0, 0, At, B0); PG8_MMA(0, 1, At, B1); PG8_BAR; PG8_SCHED;
	s_add_i32 s84, 0, 0x18000
	s_add_i32 s85, 0, 0x1c000
	v_add_u32_e32 v134, s84, v207
	v_add_u32_e32 v158, s85, v207
	ds_read_b128 v[118:121], v134
	ds_read_b128 v[126:129], v134 offset:1024
	ds_read_b128 v[130:133], v134 offset:2048
	ds_read_b128 v[134:137], v134 offset:3072
	ds_read_b128 v[138:141], v158
	ds_read_b128 v[142:145], v158 offset:1024
	ds_read_b128 v[154:157], v158 offset:2048
	ds_read_b128 v[158:161], v158 offset:3072
	s_add_u32 s40, s40, 0x80000
	s_addc_u32 s41, s41, 0
	s_mov_b32 m0, s37
	v_lshl_add_u64 v[218:219], s[40:41], 0, v[196:197]
	ds_read_b128 v[162:165], v208 offset:32768
	ds_read_b128 v[166:169], v208 offset:33792
	ds_read_b128 v[170:173], v208 offset:34816
	ds_read_b128 v[174:177], v208 offset:35840
	ds_read_b128 v[178:181], v208 offset:36864
	ds_read_b128 v[182:185], v208 offset:37888
	ds_read_b128 v[186:189], v208 offset:38912
	ds_read_b128 v[202:205], v208 offset:39936
	global_load_lds_dwordx4 v[218:219], off
	v_lshl_add_u64 v[218:219], s[40:41], 0, v[192:193]
	s_mov_b32 m0, s42
	s_nop 0
	global_load_lds_dwordx4 v[218:219], off
	s_waitcnt vmcnt(8)
	s_waitcnt lgkmcnt(0)
	s_barrier
	s_waitcnt lgkmcnt(0)
	v_mfma_f32_16x16x32_bf16 v[150:153], v[118:121], v[162:165], v[150:153]
	v_mfma_f32_16x16x32_bf16 v[146:149], v[130:133], v[162:165], v[146:149]
	v_mfma_f32_16x16x32_bf16 v[110:113], v[118:121], v[170:173], v[110:113]
	v_mfma_f32_16x16x32_bf16 v[106:109], v[130:133], v[170:173], v[106:109]
	v_mfma_f32_16x16x32_bf16 v[94:97], v[118:121], v[178:181], v[94:97]
	v_mfma_f32_16x16x32_bf16 v[90:93], v[130:133], v[178:181], v[90:93]
	v_mfma_f32_16x16x32_bf16 v[78:81], v[118:121], v[186:189], v[78:81]
	v_mfma_f32_16x16x32_bf16 v[74:77], v[130:133], v[186:189], v[74:77]
	v_mfma_f32_16x16x32_bf16 v[150:153], v[126:129], v[166:169], v[150:153]
	v_mfma_f32_16x16x32_bf16 v[146:149], v[134:137], v[166:169], v[146:149]
	v_mfma_f32_16x16x32_bf16 v[110:113], v[126:129], v[174:177], v[110:113]
	v_mfma_f32_16x16x32_bf16 v[106:109], v[134:137], v[174:177], v[106:109]
	v_mfma_f32_16x16x32_bf16 v[94:97], v[126:129], v[182:185], v[94:97]
	v_mfma_f32_16x16x32_bf16 v[90:93], v[134:137], v[182:185], v[90:93]
	v_mfma_f32_16x16x32_bf16 v[78:81], v[126:129], v[202:205], v[78:81]
	v_mfma_f32_16x16x32_bf16 v[74:77], v[134:137], v[202:205], v[74:77]
	v_mfma_f32_16x16x32_bf16 v[122:125], v[138:141], v[162:165], v[122:125]
	v_mfma_f32_16x16x32_bf16 v[114:117], v[154:157], v[162:165], v[114:117]
	v_mfma_f32_16x16x32_bf16 v[102:105], v[138:141], v[170:173], v[102:105]
	v_mfma_f32_16x16x32_bf16 v[98:101], v[154:157], v[170:173], v[98:101]
	v_mfma_f32_16x16x32_bf16 v[86:89], v[138:141], v[178:181], v[86:89]
	v_mfma_f32_16x16x32_bf16 v[82:85], v[154:157], v[178:181], v[82:85]
	v_mfma_f32_16x16x32_bf16 v[70:73], v[138:141], v[186:189], v[70:73]
	v_mfma_f32_16x16x32_bf16 v[66:69], v[154:157], v[186:189], v[66:69]
	v_mfma_f32_16x16x32_bf16 v[122:125], v[142:145], v[166:169], v[122:125]
	v_mfma_f32_16x16x32_bf16 v[114:117], v[158:161], v[166:169], v[114:117]
	v_mfma_f32_16x16x32_bf16 v[102:105], v[142:145], v[174:177], v[102:105]
	v_mfma_f32_16x16x32_bf16 v[98:101], v[158:161], v[174:177], v[98:101]
	v_mfma_f32_16x16x32_bf16 v[86:89], v[142:145], v[182:185], v[86:89]
	v_mfma_f32_16x16x32_bf16 v[82:85], v[158:161], v[182:185], v[82:85]
	v_mfma_f32_16x16x32_bf16 v[70:73], v[142:145], v[202:205], v[70:73]
	v_mfma_f32_16x16x32_bf16 v[66:69], v[158:161], v[202:205], v[66:69]
	s_barrier
; #define PG8_STAGE(bufoff, gbase, voff) do { _Pragma("unroll") for (int _i = 0; _i < 2; ++_i) \
;         __builtin_amdgcn_global_load_lds((const unsigned*)((const char*)(gbase) + (voff)[_i]), (PG8_LAS unsigned*)(lds + (bufoff) + ldsw + _i * 8192), 16, 0, 0); } while (0)
; #define PG8_LDA(dst, b, h) do { _Pragma("unroll") for (int m = 0; m < 4; ++m) _Pragma("unroll") for (int k = 0; k < 2; ++k) dst[m][k] = *(const PG8_LAS bf16x8*)(lds + PG8_SA(b, h) + aoff + m * 2048 + k * 1024); } while (0)
; #define PG8_WAIT_V(n) asm volatile("s_waitcnt vmcnt(" #n ")" ::: "memory")
; #define PG8_WAIT_L(n) asm volatile("s_waitcnt lgkmcnt(" #n ")" ::: "memory")
; template <class Epi, class Sched, bool ALIGN_EPI = false, bool SP2 = false>
; __device__ __forceinline__ void gemm_phase(PG8_LAS unsigned char* lds, const Gemm g, const Sched& S, const Epi& E, int wave_s) {
;     ...
;         for (int t = 0; t < nt; t += 2) {
;             const bool last = (t == nt - 2);
;             const char* a1 = cA + (size_t)(t + 1) * kstep;
;             const char* a2 = last ? nA : cA + (size_t)(t + 2) * kstep; const char* b2 = last ? nB : cB + (size_t)(t + 2) * kstep;
;             const char* a3 = a2 + kstep; const char* b3 = b2 + kstep;
;             if (last && has_next) S.a_ready(nxt);
;             if constexpr (SP2) {
;             PG8_LDB(B0, 0, 0); PG8_LDB(B1, 0, 1); PG8_SCHED; PG8_LDA(At, 0, 0); PG8_STAGE(PG8_SA(1, 1), a1 + hstepA, voffA);
;             PG8_WAIT_V(8); PG8_WAIT_L(0); PG8_BAR; PG8_MMA(0, 0, At, B0); PG8_MMA(0, 1, At, B1); PG8_BAR; PG8_SCHED;
;             PG8_LDA(At, 0, 1); PG8_STAGE(PG8_SB(0, 0), b2, voffB); PG8_STAGE(PG8_SB(0, 1), b2 + hstepB, voffB); PG8_STAGE(PG8_SA(0, 0), a2, voffA);
;             PG8_WAIT_V(8); PG8_WAIT_L(0); PG8_BAR; PG8_MMA(1, 0, At, B0); PG8_MMA(1, 1, At, B1); PG8_BAR; PG8_SCHED;
;             PG8_LDB(B0, 1, 0); PG8_LDB(B1, 1, 1); PG8_SCHED; PG8_LDA(At, 1, 0); PG8_STAGE(PG8_SA(0, 1), a2 + hstepA, voffA);
;             PG8_WAIT_V(8); PG8_WAIT_L(0); PG8_BAR; PG8_MMA(0, 0, At, B0); PG8_MMA(0, 1, At, B1); PG8_BAR; PG8_SCHED;
;             PG8_LDA(At, 1, 1); PG8_STAGE(PG8_SB(1, 0), b3, voffB); PG8_STAGE(PG8_SB(1, 1), b3 + hstepB, voffB); PG8_STAGE(PG8_SA(1, 0), a3, voffA);
;             PG8_WAIT_V(8); PG8_WAIT_L(0); PG8_BAR; PG8_MMA(1, 0, At, B0); PG8_MMA(1, 1, At, B1); PG8_BAR; PG8_SCHED;
;     ...
;         if constexpr (ALIGN_EPI) { if (wr == 0) PG8_BAR; }
	s_add_i32 s40, s84, s34
	v_lshl_add_u64 v[210:211], v[210:211], 0, s[60:61]
	s_mov_b32 m0, s40
	ds_read_b128 v[162:165], v208 offset:49152
	ds_read_b128 v[166:169], v208 offset:50176
	ds_read_b128 v[170:173], v208 offset:51200
	ds_read_b128 v[174:177], v208 offset:52224
	ds_read_b128 v[178:181], v208 offset:53248
	ds_read_b128 v[182:185], v208 offset:54272
	ds_read_b128 v[186:189], v208 offset:55296
	ds_read_b128 v[202:205], v208 offset:56320
	global_load_lds_dwordx4 v[210:211], off
	s_add_i32 m0, s40, 0x2000
	s_add_u32 s30, s30, 0x80080
	v_lshl_add_u64 v[210:211], v[212:213], 0, s[60:61]
	s_addc_u32 s31, s31, 0
	s_add_i32 s40, s85, s34
	global_load_lds_dwordx4 v[210:211], off
	v_lshl_add_u64 v[210:211], s[30:31], 0, v[194:195]
	s_mov_b32 m0, s40
	s_nop 0
	global_load_lds_dwordx4 v[210:211], off
	v_lshl_add_u64 v[210:211], s[30:31], 0, v[190:191]
	s_add_i32 m0, s40, 0x2000
	s_nop 0
	global_load_lds_dwordx4 v[210:211], off
	v_lshl_add_u64 v[210:211], v[214:215], 0, s[60:61]
	s_mov_b32 m0, s46
	s_nop 0
	global_load_lds_dwordx4 v[210:211], off
	v_lshl_add_u64 v[210:211], v[216:217], 0, s[60:61]
	s_mov_b32 m0, s47
	s_nop 0
	global_load_lds_dwordx4 v[210:211], off
	s_waitcnt vmcnt(8)
	s_waitcnt lgkmcnt(0)
	s_barrier
	s_waitcnt lgkmcnt(0)
	v_mfma_f32_16x16x32_bf16 v[62:65], v[118:121], v[162:165], v[62:65]
	v_mfma_f32_16x16x32_bf16 v[58:61], v[130:133], v[162:165], v[58:61]
	v_mfma_f32_16x16x32_bf16 v[46:49], v[118:121], v[170:173], v[46:49]
	v_mfma_f32_16x16x32_bf16 v[42:45], v[130:133], v[170:173], v[42:45]
	v_mfma_f32_16x16x32_bf16 v[30:33], v[118:121], v[178:181], v[30:33]
	v_mfma_f32_16x16x32_bf16 v[26:29], v[130:133], v[178:181], v[26:29]
	v_mfma_f32_16x16x32_bf16 v[14:17], v[118:121], v[186:189], v[14:17]
	v_mfma_f32_16x16x32_bf16 v[10:13], v[130:133], v[186:189], v[10:13]
	v_mfma_f32_16x16x32_bf16 v[62:65], v[126:129], v[166:169], v[62:65]
	v_mfma_f32_16x16x32_bf16 v[58:61], v[134:137], v[166:169], v[58:61]
	v_mfma_f32_16x16x32_bf16 v[46:49], v[126:129], v[174:177], v[46:49]
	v_mfma_f32_16x16x32_bf16 v[42:45], v[134:137], v[174:177], v[42:45]
	v_mfma_f32_16x16x32_bf16 v[30:33], v[126:129], v[182:185], v[30:33]
	v_mfma_f32_16x16x32_bf16 v[26:29], v[134:137], v[182:185], v[26:29]
	v_mfma_f32_16x16x32_bf16 v[14:17], v[126:129], v[202:205], v[14:17]
	v_mfma_f32_16x16x32_bf16 v[10:13], v[134:137], v[202:205], v[10:13]
	v_mfma_f32_16x16x32_bf16 v[54:57], v[138:141], v[162:165], v[54:57]
	v_mfma_f32_16x16x32_bf16 v[50:53], v[154:157], v[162:165], v[50:53]
	v_mfma_f32_16x16x32_bf16 v[38:41], v[138:141], v[170:173], v[38:41]
	v_mfma_f32_16x16x32_bf16 v[34:37], v[154:157], v[170:173], v[34:37]
	v_mfma_f32_16x16x32_bf16 v[22:25], v[138:141], v[178:181], v[22:25]
	v_mfma_f32_16x16x32_bf16 v[18:21], v[154:157], v[178:181], v[18:21]
	v_mfma_f32_16x16x32_bf16 v[6:9], v[138:141], v[186:189], v[6:9]
	v_mfma_f32_16x16x32_bf16 v[2:5], v[154:157], v[186:189], v[2:5]
	v_mfma_f32_16x16x32_bf16 v[54:57], v[142:145], v[166:169], v[54:57]
	v_mfma_f32_16x16x32_bf16 v[50:53], v[158:161], v[166:169], v[50:53]
	v_mfma_f32_16x16x32_bf16 v[38:41], v[142:145], v[174:177], v[38:41]
	v_mfma_f32_16x16x32_bf16 v[34:37], v[158:161], v[174:177], v[34:37]
	v_mfma_f32_16x16x32_bf16 v[22:25], v[142:145], v[182:185], v[22:25]
	v_mfma_f32_16x16x32_bf16 v[18:21], v[158:161], v[182:185], v[18:21]
	v_mfma_f32_16x16x32_bf16 v[6:9], v[142:145], v[202:205], v[6:9]
	v_mfma_f32_16x16x32_bf16 v[2:5], v[158:161], v[202:205], v[2:5]
	s_add_i32 s81, s81, 2
	s_add_u32 s4, s4, 0x100
	s_addc_u32 s5, s5, 0
	s_add_u32 s21, s21, 0x100
	s_addc_u32 s27, s27, 0
	s_add_u32 s30, s4, 0xfff80080
	s_addc_u32 s31, s5, -1
	s_add_i32 s84, 0, 0x10000
	s_cmp_eq_u32 s81, 28
	s_cselect_b32 s41, s29, s31
	s_cselect_b32 s40, s28, s30
	s_cselect_b32 s31, s2, s27
	s_cselect_b32 s30, s3, s21
	s_add_i32 s90, 0, 0x14000
	s_cmp_gt_u32 s81, 29
	s_barrier
	s_cbranch_scc0 .LBB0_602
	s_and_b64 vcc, exec, s[14:15]
	s_cbranch_vccz .LBB0_605
	s_barrier

; #define PG8_STAGE(bufoff, gbase, voff) do { _Pragma("unroll") for (int _i = 0; _i < 2; ++_i) \
;         __builtin_amdgcn_global_load_lds((const unsigned*)((const char*)(gbase) + (voff)[_i]), (PG8_LAS unsigned*)(lds + (bufoff) + ldsw + _i * 8192), 16, 0, 0); } while (0)
; #define PG8_LDA(dst, b, h) do { _Pragma("unroll") for (int m = 0; m < 4; ++m) _Pragma("unroll") for (int k = 0; k < 2; ++k) dst[m][k] = *(const PG8_LAS bf16x8*)(lds + PG8_SA(b, h) + aoff + m * 2048 + k * 1024); } while (0)
; #define PG8_LDB(dst, b, h) do { _Pragma("unroll") for (int n = 0; n < 2; ++n) _Pragma("unroll") for (int k = 0; k < 2; ++k) dst[n][k] = *(const PG8_LAS bf16x8*)(lds + PG8_SB(b, h) + boff + n * 2048 + k * 1024); } while (0)
; #define PG8_WAIT_V(n) asm volatile("s_waitcnt vmcnt(" #n ")" ::: "memory")
; #define PG8_WAIT_L(n) asm volatile("s_waitcnt lgkmcnt(" #n ")" ::: "memory")
; #define PG8_BAR __builtin_amdgcn_s_barrier()
; template <class Epi, class Sched, bool ALIGN_EPI = false, bool SP2 = false>
; __device__ __forceinline__ void gemm_phase(PG8_LAS unsigned char* lds, const Gemm g, const Sched& S, const Epi& E, int wave_s) {
;     ...
;         const bool has_next = S.next(ui + 1, nxt);
;         const char* nA = has_next ? (const char*)g.A + (size_t)nxt.pm * tstepA + (size_t)(nxt.pn / g.npg) * (size_t)(K * 2) : cA; const char* nB = has_next ? (const char*)g.Bt + (size_t)nxt.pn * tstepB : cB;
;         for (int t = 0; t < nt; t += 2) {
;             const bool last = (t == nt - 2);
;             const char* a1 = cA + (size_t)(t + 1) * kstep;
;             const char* a2 = last ? nA : cA + (size_t)(t + 2) * kstep; const char* b2 = last ? nB : cB + (size_t)(t + 2) * kstep;
;             const char* a3 = a2 + kstep; const char* b3 = b2 + kstep;
;             if (last && has_next) S.a_ready(nxt);
;             if constexpr (SP2) {
;             PG8_LDB(B0, 0, 0); PG8_LDB(B1, 0, 1); PG8_SCHED; PG8_LDA(At, 0, 0); PG8_STAGE(PG8_SA(1, 1), a1 + hstepA, voffA);
;             PG8_WAIT_V(8); PG8_WAIT_L(0); PG8_BAR; PG8_MMA(0, 0, At, B0); PG8_MMA(0, 1, At, B1); PG8_BAR; PG8_SCHED;
;             PG8_LDA(At, 0, 1); PG8_STAGE(PG8_SB(0, 0), b2, voffB); PG8_STAGE(PG8_SB(0, 1), b2 + hstepB, voffB); PG8_STAGE(PG8_SA(0, 0), a2, voffA);
;             PG8_WAIT_V(8); PG8_WAIT_L(0); PG8_BAR; PG8_MMA(1, 0, At, B0); PG8_MMA(1, 1, At, B1); PG8_BAR; PG8_SCHED;
.LBB0_690:
	s_ashr_i32 s89, s88, 31
	s_lshl_b64 s[2:3], s[88:89], 20
	s_add_u32 s28, s22, s2
	s_addc_u32 s29, s23, s3
	s_and_b64 s[2:3], s[4:5], exec
	s_cselect_b32 s2, s29, s41
	s_cselect_b32 s3, s28, s40
	s_add_u32 s89, s40, 0x100
	s_addc_u32 s91, s41, 0
	s_mov_b32 vcc_lo, -2
	s_add_u32 s4, s30, 0x100
	s_addc_u32 s5, s31, 0
	s_add_i32 vcc_hi, 0, 0x10000
	s_cmp_eq_u32 vcc_lo, 28
	s_cselect_b32 s41, s21, s5
	s_cselect_b32 s40, s20, s4
	s_cselect_b32 s7, s2, s91
	s_cselect_b32 s6, s3, s89
	s_add_i32 s86, 0, 0x14000
	v_add_u32_e32 v142, vcc_hi, v251
	v_add_u32_e32 v158, s86, v251
	ds_read_b128 v[126:129], v142
	ds_read_b128 v[134:137], v142 offset:1024
	ds_read_b128 v[138:141], v142 offset:2048
	ds_read_b128 v[142:145], v142 offset:3072
	ds_read_b128 v[146:149], v158
	ds_read_b128 v[150:153], v158 offset:1024
	ds_read_b128 v[154:157], v158 offset:2048
	ds_read_b128 v[158:161], v158 offset:3072
	v_lshl_add_u64 v[194:195], s[30:31], 0, v[244:245]
	s_add_i32 m0, s36, 0xc000
	ds_read_b128 v[162:165], v252
	ds_read_b128 v[166:169], v252 offset:1024
	ds_read_b128 v[170:173], v252 offset:2048
	ds_read_b128 v[174:177], v252 offset:3072
	ds_read_b128 v[178:181], v252 offset:4096
	ds_read_b128 v[182:185], v252 offset:5120
	ds_read_b128 v[186:189], v252 offset:6144
	ds_read_b128 v[190:193], v252 offset:7168
	global_load_lds_dwordx4 v[194:195], off
	v_lshl_add_u64 v[194:195], s[30:31], 0, v[246:247]
	s_add_i32 m0, s36, 0xe000
	s_nop 0
	global_load_lds_dwordx4 v[194:195], off
	s_waitcnt vmcnt(8)
	s_waitcnt lgkmcnt(0)
	s_barrier
	s_waitcnt lgkmcnt(0)
	v_mfma_f32_16x16x32_bf16 v[130:133], v[126:129], v[162:165], 0
	v_mfma_f32_16x16x32_bf16 v[118:121], v[138:141], v[162:165], 0
	v_mfma_f32_16x16x32_bf16 v[110:113], v[126:129], v[170:173], 0
	v_mfma_f32_16x16x32_bf16 v[98:101], v[138:141], v[170:173], 0
	v_mfma_f32_16x16x32_bf16 v[62:65], v[126:129], v[178:181], 0
	v_mfma_f32_16x16x32_bf16 v[58:61], v[138:141], v[178:181], 0
	v_mfma_f32_16x16x32_bf16 v[46:49], v[126:129], v[186:189], 0
	v_mfma_f32_16x16x32_bf16 v[42:45], v[138:141], v[186:189], 0
	v_mfma_f32_16x16x32_bf16 v[130:133], v[134:137], v[166:169], v[130:133]
	v_mfma_f32_16x16x32_bf16 v[118:121], v[142:145], v[166:169], v[118:121]
	v_mfma_f32_16x16x32_bf16 v[110:113], v[134:137], v[174:177], v[110:113]
	v_mfma_f32_16x16x32_bf16 v[98:101], v[142:145], v[174:177], v[98:101]
	v_mfma_f32_16x16x32_bf16 v[62:65], v[134:137], v[182:185], v[62:65]
	v_mfma_f32_16x16x32_bf16 v[58:61], v[142:145], v[182:185], v[58:61]
	v_mfma_f32_16x16x32_bf16 v[46:49], v[134:137], v[190:193], v[46:49]
	v_mfma_f32_16x16x32_bf16 v[42:45], v[142:145], v[190:193], v[42:45]
	v_mfma_f32_16x16x32_bf16 v[102:105], v[146:149], v[162:165], 0
	v_mfma_f32_16x16x32_bf16 v[74:77], v[154:157], v[162:165], 0
	v_mfma_f32_16x16x32_bf16 v[78:81], v[146:149], v[170:173], 0
	v_mfma_f32_16x16x32_bf16 v[90:93], v[154:157], v[170:173], 0
	v_mfma_f32_16x16x32_bf16 v[34:37], v[146:149], v[178:181], 0
	v_mfma_f32_16x16x32_bf16 v[26:29], v[154:157], v[178:181], 0
	v_mfma_f32_16x16x32_bf16 v[14:17], v[146:149], v[186:189], 0
	v_mfma_f32_16x16x32_bf16 v[2:5], v[154:157], v[186:189], 0
	v_mfma_f32_16x16x32_bf16 v[102:105], v[150:153], v[166:169], v[102:105]
	v_mfma_f32_16x16x32_bf16 v[74:77], v[158:161], v[166:169], v[74:77]
	v_mfma_f32_16x16x32_bf16 v[78:81], v[150:153], v[174:177], v[78:81]
	v_mfma_f32_16x16x32_bf16 v[90:93], v[158:161], v[174:177], v[90:93]
	v_mfma_f32_16x16x32_bf16 v[34:37], v[150:153], v[182:185], v[34:37]
	v_mfma_f32_16x16x32_bf16 v[26:29], v[158:161], v[182:185], v[26:29]
	v_mfma_f32_16x16x32_bf16 v[14:17], v[150:153], v[190:193], v[14:17]
	v_mfma_f32_16x16x32_bf16 v[2:5], v[158:161], v[190:193], v[2:5]
	s_barrier
	s_add_i32 s30, vcc_hi, s35
	v_lshl_add_u64 v[194:195], s[6:7], 0, v[238:239]
	s_mov_b32 m0, s30
	ds_read_b128 v[162:165], v252 offset:16384
	ds_read_b128 v[166:169], v252 offset:17408
	ds_read_b128 v[170:173], v252 offset:18432
	ds_read_b128 v[174:177], v252 offset:19456
	ds_read_b128 v[178:181], v252 offset:20480
	ds_read_b128 v[182:185], v252 offset:21504
	ds_read_b128 v[186:189], v252 offset:22528
	ds_read_b128 v[190:193], v252 offset:23552
	global_load_lds_dwordx4 v[194:195], off
	s_add_i32 m0, s30, 0x2000
	s_add_u32 s30, s6, 0x80000
	v_lshl_add_u64 v[196:197], s[6:7], 0, v[242:243]
	s_addc_u32 s31, s7, 0
	s_add_i32 s86, s86, s35
	global_load_lds_dwordx4 v[196:197], off
	v_lshl_add_u64 v[198:199], s[30:31], 0, v[238:239]
	s_mov_b32 m0, s86
	v_lshl_add_u64 v[200:201], s[40:41], 0, v[240:241]
	global_load_lds_dwordx4 v[198:199], off
	v_lshl_add_u64 v[198:199], s[30:31], 0, v[242:243]
	s_add_i32 m0, s86, 0x2000
	s_nop 0
	global_load_lds_dwordx4 v[198:199], off
	v_lshl_add_u64 v[198:199], s[40:41], 0, v[236:237]
	s_mov_b32 m0, s36
	s_nop 0
	global_load_lds_dwordx4 v[198:199], off
	s_mov_b32 m0, s37
	s_nop 0
	global_load_lds_dwordx4 v[200:201], off
	s_waitcnt vmcnt(8)
	s_waitcnt lgkmcnt(0)
	s_barrier
; #define PG8_STAGE(bufoff, gbase, voff) do { _Pragma("unroll") for (int _i = 0; _i < 2; ++_i) \
;         __builtin_amdgcn_global_load_lds((const unsigned*)((const char*)(gbase) + (voff)[_i]), (PG8_LAS unsigned*)(lds + (bufoff) + ldsw + _i * 8192), 16, 0, 0); } while (0)
; #define PG8_LDA(dst, b, h) do { _Pragma("unroll") for (int m = 0; m < 4; ++m) _Pragma("unroll") for (int k = 0; k < 2; ++k) dst[m][k] = *(const PG8_LAS bf16x8*)(lds + PG8_SA(b, h) + aoff + m * 2048 + k * 1024); } while (0)
; #define PG8_LDB(dst, b, h) do { _Pragma("unroll") for (int n = 0; n < 2; ++n) _Pragma("unroll") for (int k = 0; k < 2; ++k) dst[n][k] = *(const PG8_LAS bf16x8*)(lds + PG8_SB(b, h) + boff + n * 2048 + k * 1024); } while (0)
; #define PG8_MMA(ai, bj, At, Bt) do { __builtin_amdgcn_s_setprio(1); _Pragma("unroll") for (int m = 0; m < 4; ++m) _Pragma("unroll") for (int n = 0; n < 2; ++n) _Pragma("unroll") for (int k = 0; k < 2; ++k) \
;         acc[ai][bj][m][n] = __builtin_amdgcn_mfma_f32_16x16x32_bf16(Bt[n][k], At[m][k], acc[ai][bj][m][n], 0, 0, 0); __builtin_amdgcn_s_setprio(0); } while (0)
; #define PG8_WAIT_V(n) asm volatile("s_waitcnt vmcnt(" #n ")" ::: "memory")
; #define PG8_WAIT_L(n) asm volatile("s_waitcnt lgkmcnt(" #n ")" ::: "memory")
; #define PG8_BAR __builtin_amdgcn_s_barrier()
; #define PG8_SCHED __builtin_amdgcn_sched_barrier(0)
; template <class Epi, class Sched, bool ALIGN_EPI = false, bool SP2 = false>
; __device__ __forceinline__ void gemm_phase(PG8_LAS unsigned char* lds, const Gemm g, const Sched& S, const Epi& E, int wave_s) {
;     ...
;             PG8_WAIT_V(8); PG8_WAIT_L(0); PG8_BAR; PG8_MMA(1, 0, At, B0); PG8_MMA(1, 1, At, B1); PG8_BAR; PG8_SCHED;
;             PG8_LDB(B0, 1, 0); PG8_LDB(B1, 1, 1); PG8_SCHED; PG8_LDA(At, 1, 0); PG8_STAGE(PG8_SA(0, 1), a2 + hstepA, voffA);
;             PG8_WAIT_V(8); PG8_WAIT_L(0); PG8_BAR; PG8_MMA(0, 0, At, B0); PG8_MMA(0, 1, At, B1); PG8_BAR; PG8_SCHED;
;             PG8_LDA(At, 1, 1); PG8_STAGE(PG8_SB(1, 0), b3, voffB); PG8_STAGE(PG8_SB(1, 1), b3 + hstepB, voffB); PG8_STAGE(PG8_SA(1, 0), a3, voffA);
	s_waitcnt lgkmcnt(0)
	v_mfma_f32_16x16x32_bf16 v[54:57], v[126:129], v[162:165], 0
	v_mfma_f32_16x16x32_bf16 v[50:53], v[138:141], v[162:165], 0
	v_mfma_f32_16x16x32_bf16 v[38:41], v[126:129], v[170:173], 0
	v_mfma_f32_16x16x32_bf16 v[30:33], v[138:141], v[170:173], 0
	v_mfma_f32_16x16x32_bf16 v[86:89], v[126:129], v[178:181], 0
	v_mfma_f32_16x16x32_bf16 v[122:125], v[138:141], v[178:181], 0
	v_mfma_f32_16x16x32_bf16 v[114:117], v[126:129], v[186:189], 0
	v_mfma_f32_16x16x32_bf16 v[106:109], v[138:141], v[186:189], 0
	v_mfma_f32_16x16x32_bf16 v[54:57], v[134:137], v[166:169], v[54:57]
	v_mfma_f32_16x16x32_bf16 v[50:53], v[142:145], v[166:169], v[50:53]
	v_mfma_f32_16x16x32_bf16 v[38:41], v[134:137], v[174:177], v[38:41]
	v_mfma_f32_16x16x32_bf16 v[30:33], v[142:145], v[174:177], v[30:33]
	v_mfma_f32_16x16x32_bf16 v[86:89], v[134:137], v[182:185], v[86:89]
	v_mfma_f32_16x16x32_bf16 v[122:125], v[142:145], v[182:185], v[122:125]
	v_mfma_f32_16x16x32_bf16 v[114:117], v[134:137], v[190:193], v[114:117]
	v_mfma_f32_16x16x32_bf16 v[106:109], v[142:145], v[190:193], v[106:109]
	v_mfma_f32_16x16x32_bf16 v[22:25], v[146:149], v[162:165], 0
	v_mfma_f32_16x16x32_bf16 v[18:21], v[154:157], v[162:165], 0
	v_mfma_f32_16x16x32_bf16 v[10:13], v[146:149], v[170:173], 0
	v_mfma_f32_16x16x32_bf16 v[6:9], v[154:157], v[170:173], 0
	v_mfma_f32_16x16x32_bf16 v[82:85], v[146:149], v[178:181], 0
	v_mfma_f32_16x16x32_bf16 v[94:97], v[154:157], v[178:181], 0
	v_mfma_f32_16x16x32_bf16 v[70:73], v[146:149], v[186:189], 0
	v_mfma_f32_16x16x32_bf16 v[66:69], v[154:157], v[186:189], 0
	v_mfma_f32_16x16x32_bf16 v[22:25], v[150:153], v[166:169], v[22:25]
	v_mfma_f32_16x16x32_bf16 v[18:21], v[158:161], v[166:169], v[18:21]
	v_mfma_f32_16x16x32_bf16 v[10:13], v[150:153], v[174:177], v[10:13]
	v_mfma_f32_16x16x32_bf16 v[6:9], v[158:161], v[174:177], v[6:9]
	v_mfma_f32_16x16x32_bf16 v[82:85], v[150:153], v[182:185], v[82:85]
	v_mfma_f32_16x16x32_bf16 v[94:97], v[158:161], v[182:185], v[94:97]
	v_mfma_f32_16x16x32_bf16 v[70:73], v[150:153], v[190:193], v[70:73]
	v_mfma_f32_16x16x32_bf16 v[66:69], v[158:161], v[190:193], v[66:69]
	s_barrier
	s_add_i32 s86, 0, 0x18000
	s_add_i32 s87, 0, 0x1c000
	v_add_u32_e32 v142, s86, v251
	v_add_u32_e32 v158, s87, v251
	ds_read_b128 v[126:129], v142
	ds_read_b128 v[134:137], v142 offset:1024
	ds_read_b128 v[138:141], v142 offset:2048
	ds_read_b128 v[142:145], v142 offset:3072
	ds_read_b128 v[146:149], v158
	ds_read_b128 v[150:153], v158 offset:1024
	ds_read_b128 v[154:157], v158 offset:2048
	ds_read_b128 v[158:161], v158 offset:3072
	s_add_u32 s30, s40, 0x4000
	s_addc_u32 s31, s41, 0
	s_mov_b32 m0, s42
	v_lshl_add_u64 v[202:203], s[30:31], 0, v[236:237]
	ds_read_b128 v[162:165], v252 offset:32768
	ds_read_b128 v[166:169], v252 offset:33792
	ds_read_b128 v[170:173], v252 offset:34816
	ds_read_b128 v[174:177], v252 offset:35840
	ds_read_b128 v[178:181], v252 offset:36864
	ds_read_b128 v[182:185], v252 offset:37888
	ds_read_b128 v[186:189], v252 offset:38912
	ds_read_b128 v[190:193], v252 offset:39936
	global_load_lds_dwordx4 v[202:203], off
	v_lshl_add_u64 v[202:203], s[30:31], 0, v[240:241]
	s_mov_b32 m0, s43
	s_nop 0
	global_load_lds_dwordx4 v[202:203], off
	s_waitcnt vmcnt(8)
	s_waitcnt lgkmcnt(0)
	s_barrier
	s_waitcnt lgkmcnt(0)
	v_mfma_f32_16x16x32_bf16 v[130:133], v[126:129], v[162:165], v[130:133]
	v_mfma_f32_16x16x32_bf16 v[118:121], v[138:141], v[162:165], v[118:121]
	v_mfma_f32_16x16x32_bf16 v[110:113], v[126:129], v[170:173], v[110:113]
	v_mfma_f32_16x16x32_bf16 v[98:101], v[138:141], v[170:173], v[98:101]
	v_mfma_f32_16x16x32_bf16 v[62:65], v[126:129], v[178:181], v[62:65]
	v_mfma_f32_16x16x32_bf16 v[58:61], v[138:141], v[178:181], v[58:61]
	v_mfma_f32_16x16x32_bf16 v[46:49], v[126:129], v[186:189], v[46:49]
	v_mfma_f32_16x16x32_bf16 v[42:45], v[138:141], v[186:189], v[42:45]
	v_mfma_f32_16x16x32_bf16 v[130:133], v[134:137], v[166:169], v[130:133]
	v_mfma_f32_16x16x32_bf16 v[118:121], v[142:145], v[166:169], v[118:121]
	v_mfma_f32_16x16x32_bf16 v[110:113], v[134:137], v[174:177], v[110:113]
	v_mfma_f32_16x16x32_bf16 v[98:101], v[142:145], v[174:177], v[98:101]
	v_mfma_f32_16x16x32_bf16 v[62:65], v[134:137], v[182:185], v[62:65]
	v_mfma_f32_16x16x32_bf16 v[58:61], v[142:145], v[182:185], v[58:61]
	v_mfma_f32_16x16x32_bf16 v[46:49], v[134:137], v[190:193], v[46:49]
	v_mfma_f32_16x16x32_bf16 v[42:45], v[142:145], v[190:193], v[42:45]
	v_mfma_f32_16x16x32_bf16 v[102:105], v[146:149], v[162:165], v[102:105]
	v_mfma_f32_16x16x32_bf16 v[74:77], v[154:157], v[162:165], v[74:77]
	v_mfma_f32_16x16x32_bf16 v[78:81], v[146:149], v[170:173], v[78:81]
	v_mfma_f32_16x16x32_bf16 v[90:93], v[154:157], v[170:173], v[90:93]
	v_mfma_f32_16x16x32_bf16 v[34:37], v[146:149], v[178:181], v[34:37]
	v_mfma_f32_16x16x32_bf16 v[26:29], v[154:157], v[178:181], v[26:29]
	v_mfma_f32_16x16x32_bf16 v[14:17], v[146:149], v[186:189], v[14:17]
	v_mfma_f32_16x16x32_bf16 v[2:5], v[154:157], v[186:189], v[2:5]
	v_mfma_f32_16x16x32_bf16 v[102:105], v[150:153], v[166:169], v[102:105]
	v_mfma_f32_16x16x32_bf16 v[74:77], v[158:161], v[166:169], v[74:77]
	v_mfma_f32_16x16x32_bf16 v[78:81], v[150:153], v[174:177], v[78:81]
	v_mfma_f32_16x16x32_bf16 v[90:93], v[158:161], v[174:177], v[90:93]
	v_mfma_f32_16x16x32_bf16 v[34:37], v[150:153], v[182:185], v[34:37]
	v_mfma_f32_16x16x32_bf16 v[26:29], v[158:161], v[182:185], v[26:29]
	v_mfma_f32_16x16x32_bf16 v[14:17], v[150:153], v[190:193], v[14:17]
	v_mfma_f32_16x16x32_bf16 v[2:5], v[158:161], v[190:193], v[2:5]
	s_barrier
; #define PG8_STAGE(bufoff, gbase, voff) do { _Pragma("unroll") for (int _i = 0; _i < 2; ++_i) \
;         __builtin_amdgcn_global_load_lds((const unsigned*)((const char*)(gbase) + (voff)[_i]), (PG8_LAS unsigned*)(lds + (bufoff) + ldsw + _i * 8192), 16, 0, 0); } while (0)
; #define PG8_LDA(dst, b, h) do { _Pragma("unroll") for (int m = 0; m < 4; ++m) _Pragma("unroll") for (int k = 0; k < 2; ++k) dst[m][k] = *(const PG8_LAS bf16x8*)(lds + PG8_SA(b, h) + aoff + m * 2048 + k * 1024); } while (0)
; #define PG8_WAIT_V(n) asm volatile("s_waitcnt vmcnt(" #n ")" ::: "memory")
; #define PG8_WAIT_L(n) asm volatile("s_waitcnt lgkmcnt(" #n ")" ::: "memory")
; #define PG8_BAR __builtin_amdgcn_s_barrier()
; template <class Epi, class Sched, bool ALIGN_EPI = false, bool SP2 = false>
; __device__ __forceinline__ void gemm_phase(PG8_LAS unsigned char* lds, const Gemm g, const Sched& S, const Epi& E, int wave_s) {
;     ...
;         for (int t = 0; t < nt; t += 2) {
;             const bool last = (t == nt - 2);
;             const char* a1 = cA + (size_t)(t + 1) * kstep;
;             const char* a2 = last ? nA : cA + (size_t)(t + 2) * kstep; const char* b2 = last ? nB : cB + (size_t)(t + 2) * kstep;
;             const char* a3 = a2 + kstep; const char* b3 = b2 + kstep;
;             if (last && has_next) S.a_ready(nxt);
;             if constexpr (SP2) {
;             PG8_LDB(B0, 0, 0); PG8_LDB(B1, 0, 1); PG8_SCHED; PG8_LDA(At, 0, 0); PG8_STAGE(PG8_SA(1, 1), a1 + hstepA, voffA);
;             PG8_WAIT_V(8); PG8_WAIT_L(0); PG8_BAR; PG8_MMA(0, 0, At, B0); PG8_MMA(0, 1, At, B1); PG8_BAR; PG8_SCHED;
;             PG8_LDA(At, 0, 1); PG8_STAGE(PG8_SB(0, 0), b2, voffB); PG8_STAGE(PG8_SB(0, 1), b2 + hstepB, voffB); PG8_STAGE(PG8_SA(0, 0), a2, voffA);
;             PG8_WAIT_V(8); PG8_WAIT_L(0); PG8_BAR; PG8_MMA(1, 0, At, B0); PG8_MMA(1, 1, At, B1); PG8_BAR; PG8_SCHED;
;             PG8_LDB(B0, 1, 0); PG8_LDB(B1, 1, 1); PG8_SCHED; PG8_LDA(At, 1, 0); PG8_STAGE(PG8_SA(0, 1), a2 + hstepA, voffA);
;             PG8_WAIT_V(8); PG8_WAIT_L(0); PG8_BAR; PG8_MMA(0, 0, At, B0); PG8_MMA(0, 1, At, B1); PG8_BAR; PG8_SCHED;
;             PG8_LDA(At, 1, 1); PG8_STAGE(PG8_SB(1, 0), b3, voffB); PG8_STAGE(PG8_SB(1, 1), b3 + hstepB, voffB); PG8_STAGE(PG8_SA(1, 0), a3, voffA);
;             PG8_WAIT_V(8); PG8_WAIT_L(0); PG8_BAR; PG8_MMA(1, 0, At, B0); PG8_MMA(1, 1, At, B1); PG8_BAR; PG8_SCHED;
	s_add_i32 s30, s86, s35
	v_lshl_add_u64 v[194:195], v[194:195], 0, s[60:61]
	s_mov_b32 m0, s30
	ds_read_b128 v[162:165], v252 offset:49152
	ds_read_b128 v[166:169], v252 offset:50176
	ds_read_b128 v[170:173], v252 offset:51200
	ds_read_b128 v[174:177], v252 offset:52224
	ds_read_b128 v[178:181], v252 offset:53248
	ds_read_b128 v[182:185], v252 offset:54272
	ds_read_b128 v[186:189], v252 offset:55296
	ds_read_b128 v[190:193], v252 offset:56320
	global_load_lds_dwordx4 v[194:195], off
	s_add_i32 m0, s30, 0x2000
	s_add_u32 s6, s6, 0x80080
	v_lshl_add_u64 v[194:195], v[196:197], 0, s[60:61]
	s_addc_u32 s7, s7, 0
	s_add_i32 s30, s87, s35
	global_load_lds_dwordx4 v[194:195], off
	v_lshl_add_u64 v[194:195], s[6:7], 0, v[238:239]
	s_mov_b32 m0, s30
	s_nop 0
	global_load_lds_dwordx4 v[194:195], off
	v_lshl_add_u64 v[194:195], s[6:7], 0, v[242:243]
	s_add_i32 m0, s30, 0x2000
	s_nop 0
	global_load_lds_dwordx4 v[194:195], off
	v_lshl_add_u64 v[194:195], v[198:199], 0, s[60:61]
	s_mov_b32 m0, s77
	s_nop 0
	global_load_lds_dwordx4 v[194:195], off
	v_lshl_add_u64 v[194:195], v[200:201], 0, s[60:61]
	s_mov_b32 m0, s94
	s_nop 0
	global_load_lds_dwordx4 v[194:195], off
	s_waitcnt vmcnt(8)
	s_waitcnt lgkmcnt(0)
	s_barrier
	s_waitcnt lgkmcnt(0)
	v_mfma_f32_16x16x32_bf16 v[54:57], v[126:129], v[162:165], v[54:57]
	v_mfma_f32_16x16x32_bf16 v[50:53], v[138:141], v[162:165], v[50:53]
	v_mfma_f32_16x16x32_bf16 v[38:41], v[126:129], v[170:173], v[38:41]
	v_mfma_f32_16x16x32_bf16 v[30:33], v[138:141], v[170:173], v[30:33]
	v_mfma_f32_16x16x32_bf16 v[86:89], v[126:129], v[178:181], v[86:89]
	v_mfma_f32_16x16x32_bf16 v[122:125], v[138:141], v[178:181], v[122:125]
	v_mfma_f32_16x16x32_bf16 v[114:117], v[126:129], v[186:189], v[114:117]
	v_mfma_f32_16x16x32_bf16 v[106:109], v[138:141], v[186:189], v[106:109]
	v_mfma_f32_16x16x32_bf16 v[54:57], v[134:137], v[166:169], v[54:57]
	v_mfma_f32_16x16x32_bf16 v[50:53], v[142:145], v[166:169], v[50:53]
	v_mfma_f32_16x16x32_bf16 v[38:41], v[134:137], v[174:177], v[38:41]
	v_mfma_f32_16x16x32_bf16 v[30:33], v[142:145], v[174:177], v[30:33]
	v_mfma_f32_16x16x32_bf16 v[86:89], v[134:137], v[182:185], v[86:89]
	v_mfma_f32_16x16x32_bf16 v[122:125], v[142:145], v[182:185], v[122:125]
	v_mfma_f32_16x16x32_bf16 v[114:117], v[134:137], v[190:193], v[114:117]
	v_mfma_f32_16x16x32_bf16 v[106:109], v[142:145], v[190:193], v[106:109]
	v_mfma_f32_16x16x32_bf16 v[22:25], v[146:149], v[162:165], v[22:25]
	v_mfma_f32_16x16x32_bf16 v[18:21], v[154:157], v[162:165], v[18:21]
	v_mfma_f32_16x16x32_bf16 v[10:13], v[146:149], v[170:173], v[10:13]
	v_mfma_f32_16x16x32_bf16 v[6:9], v[154:157], v[170:173], v[6:9]
	v_mfma_f32_16x16x32_bf16 v[82:85], v[146:149], v[178:181], v[82:85]
	v_mfma_f32_16x16x32_bf16 v[94:97], v[154:157], v[178:181], v[94:97]
	v_mfma_f32_16x16x32_bf16 v[70:73], v[146:149], v[186:189], v[70:73]
	v_mfma_f32_16x16x32_bf16 v[66:69], v[154:157], v[186:189], v[66:69]
	v_mfma_f32_16x16x32_bf16 v[22:25], v[150:153], v[166:169], v[22:25]
	v_mfma_f32_16x16x32_bf16 v[18:21], v[158:161], v[166:169], v[18:21]
	v_mfma_f32_16x16x32_bf16 v[10:13], v[150:153], v[174:177], v[10:13]
	v_mfma_f32_16x16x32_bf16 v[6:9], v[158:161], v[174:177], v[6:9]
	v_mfma_f32_16x16x32_bf16 v[82:85], v[150:153], v[182:185], v[82:85]
	v_mfma_f32_16x16x32_bf16 v[94:97], v[158:161], v[182:185], v[94:97]
	v_mfma_f32_16x16x32_bf16 v[70:73], v[150:153], v[190:193], v[70:73]
	v_mfma_f32_16x16x32_bf16 v[66:69], v[158:161], v[190:193], v[66:69]
	s_add_i32 vcc_lo, vcc_lo, 2
	s_add_u32 s89, s89, 0x100
	s_addc_u32 s91, s91, 0
	s_mov_b64 s[30:31], s[4:5]
	s_add_u32 s4, s30, 0x100
	s_addc_u32 s5, s31, 0
	s_add_i32 vcc_hi, 0, 0x10000
	s_cmp_eq_u32 vcc_lo, 28
	s_cselect_b32 s41, s21, s5
	s_cselect_b32 s40, s20, s4
	s_cselect_b32 s7, s2, s91
	s_cselect_b32 s6, s3, s89
	s_add_i32 s86, 0, 0x14000
	s_cmp_gt_u32 vcc_lo, 29
	s_barrier
.LBB0_691:
	v_add_u32_e32 v142, vcc_hi, v251
	v_add_u32_e32 v158, s86, v251
	ds_read_b128 v[126:129], v142
	ds_read_b128 v[134:137], v142 offset:1024
	ds_read_b128 v[138:141], v142 offset:2048
	ds_read_b128 v[142:145], v142 offset:3072
	ds_read_b128 v[146:149], v158
	ds_read_b128 v[150:153], v158 offset:1024
	ds_read_b128 v[154:157], v158 offset:2048
	ds_read_b128 v[158:161], v158 offset:3072
	v_lshl_add_u64 v[194:195], s[30:31], 0, v[244:245]
	s_add_i32 m0, s36, 0xc000
	ds_read_b128 v[162:165], v252
	ds_read_b128 v[166:169], v252 offset:1024
	ds_read_b128 v[170:173], v252 offset:2048
	ds_read_b128 v[174:177], v252 offset:3072
	ds_read_b128 v[178:181], v252 offset:4096
	ds_read_b128 v[182:185], v252 offset:5120
	ds_read_b128 v[186:189], v252 offset:6144
	ds_read_b128 v[190:193], v252 offset:7168
	global_load_lds_dwordx4 v[194:195], off
	v_lshl_add_u64 v[194:195], s[30:31], 0, v[246:247]
	s_add_i32 m0, s36, 0xe000
	s_nop 0
	global_load_lds_dwordx4 v[194:195], off
	s_waitcnt vmcnt(8)
	s_waitcnt lgkmcnt(0)
	s_barrier
; #define PG8_STAGE(bufoff, gbase, voff) do { _Pragma("unroll") for (int _i = 0; _i < 2; ++_i) \
;         __builtin_amdgcn_global_load_lds((const unsigned*)((const char*)(gbase) + (voff)[_i]), (PG8_LAS unsigned*)(lds + (bufoff) + ldsw + _i * 8192), 16, 0, 0); } while (0)
; #define PG8_LDA(dst, b, h) do { _Pragma("unroll") for (int m = 0; m < 4; ++m) _Pragma("unroll") for (int k = 0; k < 2; ++k) dst[m][k] = *(const PG8_LAS bf16x8*)(lds + PG8_SA(b, h) + aoff + m * 2048 + k * 1024); } while (0)
; #define PG8_MMA(ai, bj, At, Bt) do { __builtin_amdgcn_s_setprio(1); _Pragma("unroll") for (int m = 0; m < 4; ++m) _Pragma("unroll") for (int n = 0; n < 2; ++n) _Pragma("unroll") for (int k = 0; k < 2; ++k) \
;         acc[ai][bj][m][n] = __builtin_amdgcn_mfma_f32_16x16x32_bf16(Bt[n][k], At[m][k], acc[ai][bj][m][n], 0, 0, 0); __builtin_amdgcn_s_setprio(0); } while (0)
; #define PG8_WAIT_V(n) asm volatile("s_waitcnt vmcnt(" #n ")" ::: "memory")
; #define PG8_WAIT_L(n) asm volatile("s_waitcnt lgkmcnt(" #n ")" ::: "memory")
; #define PG8_BAR __builtin_amdgcn_s_barrier()
; #define PG8_SCHED __builtin_amdgcn_sched_barrier(0)
; template <class Epi, class Sched, bool ALIGN_EPI = false, bool SP2 = false>
; __device__ __forceinline__ void gemm_phase(PG8_LAS unsigned char* lds, const Gemm g, const Sched& S, const Epi& E, int wave_s) {
;     ...
;             PG8_WAIT_V(8); PG8_WAIT_L(0); PG8_BAR; PG8_MMA(0, 0, At, B0); PG8_MMA(0, 1, At, B1); PG8_BAR; PG8_SCHED;
;             PG8_LDA(At, 0, 1); PG8_STAGE(PG8_SB(0, 0), b2, voffB); PG8_STAGE(PG8_SB(0, 1), b2 + hstepB, voffB); PG8_STAGE(PG8_SA(0, 0), a2, voffA);
;             PG8_WAIT_V(8); PG8_WAIT_L(0); PG8_BAR; PG8_MMA(1, 0, At, B0); PG8_MMA(1, 1, At, B1); PG8_BAR; PG8_SCHED;
	s_waitcnt lgkmcnt(0)
	v_mfma_f32_16x16x32_bf16 v[130:133], v[126:129], v[162:165], v[130:133]
	v_mfma_f32_16x16x32_bf16 v[118:121], v[138:141], v[162:165], v[118:121]
	v_mfma_f32_16x16x32_bf16 v[110:113], v[126:129], v[170:173], v[110:113]
	v_mfma_f32_16x16x32_bf16 v[98:101], v[138:141], v[170:173], v[98:101]
	v_mfma_f32_16x16x32_bf16 v[62:65], v[126:129], v[178:181], v[62:65]
	v_mfma_f32_16x16x32_bf16 v[58:61], v[138:141], v[178:181], v[58:61]
	v_mfma_f32_16x16x32_bf16 v[46:49], v[126:129], v[186:189], v[46:49]
	v_mfma_f32_16x16x32_bf16 v[42:45], v[138:141], v[186:189], v[42:45]
	v_mfma_f32_16x16x32_bf16 v[130:133], v[134:137], v[166:169], v[130:133]
	v_mfma_f32_16x16x32_bf16 v[118:121], v[142:145], v[166:169], v[118:121]
	v_mfma_f32_16x16x32_bf16 v[110:113], v[134:137], v[174:177], v[110:113]
	v_mfma_f32_16x16x32_bf16 v[98:101], v[142:145], v[174:177], v[98:101]
	v_mfma_f32_16x16x32_bf16 v[62:65], v[134:137], v[182:185], v[62:65]
	v_mfma_f32_16x16x32_bf16 v[58:61], v[142:145], v[182:185], v[58:61]
	v_mfma_f32_16x16x32_bf16 v[46:49], v[134:137], v[190:193], v[46:49]
	v_mfma_f32_16x16x32_bf16 v[42:45], v[142:145], v[190:193], v[42:45]
	v_mfma_f32_16x16x32_bf16 v[102:105], v[146:149], v[162:165], v[102:105]
	v_mfma_f32_16x16x32_bf16 v[74:77], v[154:157], v[162:165], v[74:77]
	v_mfma_f32_16x16x32_bf16 v[78:81], v[146:149], v[170:173], v[78:81]
	v_mfma_f32_16x16x32_bf16 v[90:93], v[154:157], v[170:173], v[90:93]
	v_mfma_f32_16x16x32_bf16 v[34:37], v[146:149], v[178:181], v[34:37]
	v_mfma_f32_16x16x32_bf16 v[26:29], v[154:157], v[178:181], v[26:29]
	v_mfma_f32_16x16x32_bf16 v[14:17], v[146:149], v[186:189], v[14:17]
	v_mfma_f32_16x16x32_bf16 v[2:5], v[154:157], v[186:189], v[2:5]
	v_mfma_f32_16x16x32_bf16 v[102:105], v[150:153], v[166:169], v[102:105]
	v_mfma_f32_16x16x32_bf16 v[74:77], v[158:161], v[166:169], v[74:77]
	v_mfma_f32_16x16x32_bf16 v[78:81], v[150:153], v[174:177], v[78:81]
	v_mfma_f32_16x16x32_bf16 v[90:93], v[158:161], v[174:177], v[90:93]
	v_mfma_f32_16x16x32_bf16 v[34:37], v[150:153], v[182:185], v[34:37]
	v_mfma_f32_16x16x32_bf16 v[26:29], v[158:161], v[182:185], v[26:29]
	v_mfma_f32_16x16x32_bf16 v[14:17], v[150:153], v[190:193], v[14:17]
	v_mfma_f32_16x16x32_bf16 v[2:5], v[158:161], v[190:193], v[2:5]
	s_barrier
	s_add_i32 s30, vcc_hi, s35
	v_lshl_add_u64 v[194:195], s[6:7], 0, v[238:239]
	s_mov_b32 m0, s30
	ds_read_b128 v[162:165], v252 offset:16384
	ds_read_b128 v[166:169], v252 offset:17408
	ds_read_b128 v[170:173], v252 offset:18432
	ds_read_b128 v[174:177], v252 offset:19456
	ds_read_b128 v[178:181], v252 offset:20480
	ds_read_b128 v[182:185], v252 offset:21504
	ds_read_b128 v[186:189], v252 offset:22528
	ds_read_b128 v[190:193], v252 offset:23552
	global_load_lds_dwordx4 v[194:195], off
	s_add_i32 m0, s30, 0x2000
	s_add_u32 s30, s6, 0x80000
	v_lshl_add_u64 v[196:197], s[6:7], 0, v[242:243]
	s_addc_u32 s31, s7, 0
	s_add_i32 s86, s86, s35
	global_load_lds_dwordx4 v[196:197], off
	v_lshl_add_u64 v[198:199], s[30:31], 0, v[238:239]
	s_mov_b32 m0, s86
	v_lshl_add_u64 v[200:201], s[40:41], 0, v[240:241]
	global_load_lds_dwordx4 v[198:199], off
	v_lshl_add_u64 v[198:199], s[30:31], 0, v[242:243]
	s_add_i32 m0, s86, 0x2000
	s_nop 0
	global_load_lds_dwordx4 v[198:199], off
	v_lshl_add_u64 v[198:199], s[40:41], 0, v[236:237]
	s_mov_b32 m0, s36
	s_nop 0
	global_load_lds_dwordx4 v[198:199], off
	s_mov_b32 m0, s37
	s_nop 0
	global_load_lds_dwordx4 v[200:201], off
	s_waitcnt vmcnt(8)
	s_waitcnt lgkmcnt(0)
	s_barrier
	s_waitcnt lgkmcnt(0)
	v_mfma_f32_16x16x32_bf16 v[54:57], v[126:129], v[162:165], v[54:57]
	v_mfma_f32_16x16x32_bf16 v[50:53], v[138:141], v[162:165], v[50:53]
	v_mfma_f32_16x16x32_bf16 v[38:41], v[126:129], v[170:173], v[38:41]
	v_mfma_f32_16x16x32_bf16 v[30:33], v[138:141], v[170:173], v[30:33]
	v_mfma_f32_16x16x32_bf16 v[86:89], v[126:129], v[178:181], v[86:89]
	v_mfma_f32_16x16x32_bf16 v[122:125], v[138:141], v[178:181], v[122:125]
	v_mfma_f32_16x16x32_bf16 v[114:117], v[126:129], v[186:189], v[114:117]
	v_mfma_f32_16x16x32_bf16 v[106:109], v[138:141], v[186:189], v[106:109]
	v_mfma_f32_16x16x32_bf16 v[54:57], v[134:137], v[166:169], v[54:57]
	v_mfma_f32_16x16x32_bf16 v[50:53], v[142:145], v[166:169], v[50:53]
	v_mfma_f32_16x16x32_bf16 v[38:41], v[134:137], v[174:177], v[38:41]
	v_mfma_f32_16x16x32_bf16 v[30:33], v[142:145], v[174:177], v[30:33]
	v_mfma_f32_16x16x32_bf16 v[86:89], v[134:137], v[182:185], v[86:89]
	v_mfma_f32_16x16x32_bf16 v[122:125], v[142:145], v[182:185], v[122:125]
	v_mfma_f32_16x16x32_bf16 v[114:117], v[134:137], v[190:193], v[114:117]
	v_mfma_f32_16x16x32_bf16 v[106:109], v[142:145], v[190:193], v[106:109]
	v_mfma_f32_16x16x32_bf16 v[22:25], v[146:149], v[162:165], v[22:25]
	v_mfma_f32_16x16x32_bf16 v[18:21], v[154:157], v[162:165], v[18:21]
	v_mfma_f32_16x16x32_bf16 v[10:13], v[146:149], v[170:173], v[10:13]
	v_mfma_f32_16x16x32_bf16 v[6:9], v[154:157], v[170:173], v[6:9]
	v_mfma_f32_16x16x32_bf16 v[82:85], v[146:149], v[178:181], v[82:85]
	v_mfma_f32_16x16x32_bf16 v[94:97], v[154:157], v[178:181], v[94:97]
	v_mfma_f32_16x16x32_bf16 v[70:73], v[146:149], v[186:189], v[70:73]
	v_mfma_f32_16x16x32_bf16 v[66:69], v[154:157], v[186:189], v[66:69]
	v_mfma_f32_16x16x32_bf16 v[22:25], v[150:153], v[166:169], v[22:25]
	v_mfma_f32_16x16x32_bf16 v[18:21], v[158:161], v[166:169], v[18:21]
	v_mfma_f32_16x16x32_bf16 v[10:13], v[150:153], v[174:177], v[10:13]
	v_mfma_f32_16x16x32_bf16 v[6:9], v[158:161], v[174:177], v[6:9]
	v_mfma_f32_16x16x32_bf16 v[82:85], v[150:153], v[182:185], v[82:85]
	v_mfma_f32_16x16x32_bf16 v[94:97], v[158:161], v[182:185], v[94:97]
	v_mfma_f32_16x16x32_bf16 v[70:73], v[150:153], v[190:193], v[70:73]
	v_mfma_f32_16x16x32_bf16 v[66:69], v[158:161], v[190:193], v[66:69]
	s_barrier
; #define PG8_STAGE(bufoff, gbase, voff) do { _Pragma("unroll") for (int _i = 0; _i < 2; ++_i) \
;         __builtin_amdgcn_global_load_lds((const unsigned*)((const char*)(gbase) + (voff)[_i]), (PG8_LAS unsigned*)(lds + (bufoff) + ldsw + _i * 8192), 16, 0, 0); } while (0)
; #define PG8_LDA(dst, b, h) do { _Pragma("unroll") for (int m = 0; m < 4; ++m) _Pragma("unroll") for (int k = 0; k < 2; ++k) dst[m][k] = *(const PG8_LAS bf16x8*)(lds + PG8_SA(b, h) + aoff + m * 2048 + k * 1024); } while (0)
; #define PG8_LDB(dst, b, h) do { _Pragma("unroll") for (int n = 0; n < 2; ++n) _Pragma("unroll") for (int k = 0; k < 2; ++k) dst[n][k] = *(const PG8_LAS bf16x8*)(lds + PG8_SB(b, h) + boff + n * 2048 + k * 1024); } while (0)
; #define PG8_MMA(ai, bj, At, Bt) do { __builtin_amdgcn_s_setprio(1); _Pragma("unroll") for (int m = 0; m < 4; ++m) _Pragma("unroll") for (int n = 0; n < 2; ++n) _Pragma("unroll") for (int k = 0; k < 2; ++k) \
;         acc[ai][bj][m][n] = __builtin_amdgcn_mfma_f32_16x16x32_bf16(Bt[n][k], At[m][k], acc[ai][bj][m][n], 0, 0, 0); __builtin_amdgcn_s_setprio(0); } while (0)
; #define PG8_WAIT_V(n) asm volatile("s_waitcnt vmcnt(" #n ")" ::: "memory")
; #define PG8_WAIT_L(n) asm volatile("s_waitcnt lgkmcnt(" #n ")" ::: "memory")
; #define PG8_BAR __builtin_amdgcn_s_barrier()
; #define PG8_SCHED __builtin_amdgcn_sched_barrier(0)
; template <class Epi, class Sched, bool ALIGN_EPI = false, bool SP2 = false>
; __device__ __forceinline__ void gemm_phase(PG8_LAS unsigned char* lds, const Gemm g, const Sched& S, const Epi& E, int wave_s) {
;     ...
;             PG8_LDB(B0, 1, 0); PG8_LDB(B1, 1, 1); PG8_SCHED; PG8_LDA(At, 1, 0); PG8_STAGE(PG8_SA(0, 1), a2 + hstepA, voffA);
;             PG8_WAIT_V(8); PG8_WAIT_L(0); PG8_BAR; PG8_MMA(0, 0, At, B0); PG8_MMA(0, 1, At, B1); PG8_BAR; PG8_SCHED;
	s_add_i32 s86, 0, 0x18000
	s_add_i32 s87, 0, 0x1c000
	v_add_u32_e32 v142, s86, v251
	v_add_u32_e32 v158, s87, v251
	ds_read_b128 v[126:129], v142
	ds_read_b128 v[134:137], v142 offset:1024
	ds_read_b128 v[138:141], v142 offset:2048
	ds_read_b128 v[142:145], v142 offset:3072
	ds_read_b128 v[146:149], v158
	ds_read_b128 v[150:153], v158 offset:1024
	ds_read_b128 v[154:157], v158 offset:2048
	ds_read_b128 v[158:161], v158 offset:3072
	s_add_u32 s30, s40, 0x4000
	s_addc_u32 s31, s41, 0
	s_mov_b32 m0, s42
	v_lshl_add_u64 v[202:203], s[30:31], 0, v[236:237]
	ds_read_b128 v[162:165], v252 offset:32768
	ds_read_b128 v[166:169], v252 offset:33792
	ds_read_b128 v[170:173], v252 offset:34816
	ds_read_b128 v[174:177], v252 offset:35840
	ds_read_b128 v[178:181], v252 offset:36864
	ds_read_b128 v[182:185], v252 offset:37888
	ds_read_b128 v[186:189], v252 offset:38912
	ds_read_b128 v[190:193], v252 offset:39936
	global_load_lds_dwordx4 v[202:203], off
	v_lshl_add_u64 v[202:203], s[30:31], 0, v[240:241]
	s_mov_b32 m0, s43
	s_nop 0
	global_load_lds_dwordx4 v[202:203], off
	s_waitcnt vmcnt(8)
	s_waitcnt lgkmcnt(0)
	s_barrier
	s_waitcnt lgkmcnt(0)
	v_mfma_f32_16x16x32_bf16 v[130:133], v[126:129], v[162:165], v[130:133]
	v_mfma_f32_16x16x32_bf16 v[118:121], v[138:141], v[162:165], v[118:121]
	v_mfma_f32_16x16x32_bf16 v[110:113], v[126:129], v[170:173], v[110:113]
	v_mfma_f32_16x16x32_bf16 v[98:101], v[138:141], v[170:173], v[98:101]
	v_mfma_f32_16x16x32_bf16 v[62:65], v[126:129], v[178:181], v[62:65]
	v_mfma_f32_16x16x32_bf16 v[58:61], v[138:141], v[178:181], v[58:61]
	v_mfma_f32_16x16x32_bf16 v[46:49], v[126:129], v[186:189], v[46:49]
	v_mfma_f32_16x16x32_bf16 v[42:45], v[138:141], v[186:189], v[42:45]
	v_mfma_f32_16x16x32_bf16 v[130:133], v[134:137], v[166:169], v[130:133]
	v_mfma_f32_16x16x32_bf16 v[118:121], v[142:145], v[166:169], v[118:121]
	v_mfma_f32_16x16x32_bf16 v[110:113], v[134:137], v[174:177], v[110:113]
	v_mfma_f32_16x16x32_bf16 v[98:101], v[142:145], v[174:177], v[98:101]
	v_mfma_f32_16x16x32_bf16 v[62:65], v[134:137], v[182:185], v[62:65]
	v_mfma_f32_16x16x32_bf16 v[58:61], v[142:145], v[182:185], v[58:61]
	v_mfma_f32_16x16x32_bf16 v[46:49], v[134:137], v[190:193], v[46:49]
	v_mfma_f32_16x16x32_bf16 v[42:45], v[142:145], v[190:193], v[42:45]
	v_mfma_f32_16x16x32_bf16 v[102:105], v[146:149], v[162:165], v[102:105]
	v_mfma_f32_16x16x32_bf16 v[74:77], v[154:157], v[162:165], v[74:77]
	v_mfma_f32_16x16x32_bf16 v[78:81], v[146:149], v[170:173], v[78:81]
	v_mfma_f32_16x16x32_bf16 v[90:93], v[154:157], v[170:173], v[90:93]
	v_mfma_f32_16x16x32_bf16 v[34:37], v[146:149], v[178:181], v[34:37]
	v_mfma_f32_16x16x32_bf16 v[26:29], v[154:157], v[178:181], v[26:29]
	v_mfma_f32_16x16x32_bf16 v[14:17], v[146:149], v[186:189], v[14:17]
	v_mfma_f32_16x16x32_bf16 v[2:5], v[154:157], v[186:189], v[2:5]
	v_mfma_f32_16x16x32_bf16 v[102:105], v[150:153], v[166:169], v[102:105]
	v_mfma_f32_16x16x32_bf16 v[74:77], v[158:161], v[166:169], v[74:77]
	v_mfma_f32_16x16x32_bf16 v[78:81], v[150:153], v[174:177], v[78:81]
	v_mfma_f32_16x16x32_bf16 v[90:93], v[158:161], v[174:177], v[90:93]
	v_mfma_f32_16x16x32_bf16 v[34:37], v[150:153], v[182:185], v[34:37]
	v_mfma_f32_16x16x32_bf16 v[26:29], v[158:161], v[182:185], v[26:29]
	v_mfma_f32_16x16x32_bf16 v[14:17], v[150:153], v[190:193], v[14:17]
	v_mfma_f32_16x16x32_bf16 v[2:5], v[158:161], v[190:193], v[2:5]
	s_barrier
; #define PG8_STAGE(bufoff, gbase, voff) do { _Pragma("unroll") for (int _i = 0; _i < 2; ++_i) \
;         __builtin_amdgcn_global_load_lds((const unsigned*)((const char*)(gbase) + (voff)[_i]), (PG8_LAS unsigned*)(lds + (bufoff) + ldsw + _i * 8192), 16, 0, 0); } while (0)
; #define PG8_LDA(dst, b, h) do { _Pragma("unroll") for (int m = 0; m < 4; ++m) _Pragma("unroll") for (int k = 0; k < 2; ++k) dst[m][k] = *(const PG8_LAS bf16x8*)(lds + PG8_SA(b, h) + aoff + m * 2048 + k * 1024); } while (0)
; #define PG8_MMA(ai, bj, At, Bt) do { __builtin_amdgcn_s_setprio(1); _Pragma("unroll") for (int m = 0; m < 4; ++m) _Pragma("unroll") for (int n = 0; n < 2; ++n) _Pragma("unroll") for (int k = 0; k < 2; ++k) \
;         acc[ai][bj][m][n] = __builtin_amdgcn_mfma_f32_16x16x32_bf16(Bt[n][k], At[m][k], acc[ai][bj][m][n], 0, 0, 0); __builtin_amdgcn_s_setprio(0); } while (0)
; #define PG8_WAIT_V(n) asm volatile("s_waitcnt vmcnt(" #n ")" ::: "memory")
; #define PG8_WAIT_L(n) asm volatile("s_waitcnt lgkmcnt(" #n ")" ::: "memory")
; #define PG8_BAR __builtin_amdgcn_s_barrier()
; #define PG8_SCHED __builtin_amdgcn_sched_barrier(0)
; template <class Epi, class Sched, bool ALIGN_EPI = false, bool SP2 = false>
; __device__ __forceinline__ void gemm_phase(PG8_LAS unsigned char* lds, const Gemm g, const Sched& S, const Epi& E, int wave_s) {
;     ...
;             PG8_LDA(At, 1, 1); PG8_STAGE(PG8_SB(1, 0), b3, voffB); PG8_STAGE(PG8_SB(1, 1), b3 + hstepB, voffB); PG8_STAGE(PG8_SA(1, 0), a3, voffA);
;             PG8_WAIT_V(8); PG8_WAIT_L(0); PG8_BAR; PG8_MMA(1, 0, At, B0); PG8_MMA(1, 1, At, B1); PG8_BAR; PG8_SCHED;
;     ...
;         if constexpr (ALIGN_EPI) { if (wr == 0) PG8_BAR; }
	s_add_i32 s30, s86, s35
	v_lshl_add_u64 v[194:195], v[194:195], 0, s[60:61]
	s_mov_b32 m0, s30
	ds_read_b128 v[162:165], v252 offset:49152
	ds_read_b128 v[166:169], v252 offset:50176
	ds_read_b128 v[170:173], v252 offset:51200
	ds_read_b128 v[174:177], v252 offset:52224
	ds_read_b128 v[178:181], v252 offset:53248
	ds_read_b128 v[182:185], v252 offset:54272
	ds_read_b128 v[186:189], v252 offset:55296
	ds_read_b128 v[190:193], v252 offset:56320
	global_load_lds_dwordx4 v[194:195], off
	s_add_i32 m0, s30, 0x2000
	s_add_u32 s6, s6, 0x80080
	v_lshl_add_u64 v[194:195], v[196:197], 0, s[60:61]
	s_addc_u32 s7, s7, 0
	s_add_i32 s30, s87, s35
	global_load_lds_dwordx4 v[194:195], off
	v_lshl_add_u64 v[194:195], s[6:7], 0, v[238:239]
	s_mov_b32 m0, s30
	s_nop 0
	global_load_lds_dwordx4 v[194:195], off
	v_lshl_add_u64 v[194:195], s[6:7], 0, v[242:243]
	s_add_i32 m0, s30, 0x2000
	s_nop 0
	global_load_lds_dwordx4 v[194:195], off
	v_lshl_add_u64 v[194:195], v[198:199], 0, s[60:61]
	s_mov_b32 m0, s77
	s_nop 0
	global_load_lds_dwordx4 v[194:195], off
	v_lshl_add_u64 v[194:195], v[200:201], 0, s[60:61]
	s_mov_b32 m0, s94
	s_nop 0
	global_load_lds_dwordx4 v[194:195], off
	s_waitcnt vmcnt(8)
	s_waitcnt lgkmcnt(0)
	s_barrier
	s_waitcnt lgkmcnt(0)
	v_mfma_f32_16x16x32_bf16 v[54:57], v[126:129], v[162:165], v[54:57]
	v_mfma_f32_16x16x32_bf16 v[50:53], v[138:141], v[162:165], v[50:53]
	v_mfma_f32_16x16x32_bf16 v[38:41], v[126:129], v[170:173], v[38:41]
	v_mfma_f32_16x16x32_bf16 v[30:33], v[138:141], v[170:173], v[30:33]
	v_mfma_f32_16x16x32_bf16 v[86:89], v[126:129], v[178:181], v[86:89]
	v_mfma_f32_16x16x32_bf16 v[122:125], v[138:141], v[178:181], v[122:125]
	v_mfma_f32_16x16x32_bf16 v[114:117], v[126:129], v[186:189], v[114:117]
	v_mfma_f32_16x16x32_bf16 v[106:109], v[138:141], v[186:189], v[106:109]
	v_mfma_f32_16x16x32_bf16 v[54:57], v[134:137], v[166:169], v[54:57]
	v_mfma_f32_16x16x32_bf16 v[50:53], v[142:145], v[166:169], v[50:53]
	v_mfma_f32_16x16x32_bf16 v[38:41], v[134:137], v[174:177], v[38:41]
	v_mfma_f32_16x16x32_bf16 v[30:33], v[142:145], v[174:177], v[30:33]
	v_mfma_f32_16x16x32_bf16 v[86:89], v[134:137], v[182:185], v[86:89]
	v_mfma_f32_16x16x32_bf16 v[122:125], v[142:145], v[182:185], v[122:125]
	v_mfma_f32_16x16x32_bf16 v[114:117], v[134:137], v[190:193], v[114:117]
	v_mfma_f32_16x16x32_bf16 v[106:109], v[142:145], v[190:193], v[106:109]
	v_mfma_f32_16x16x32_bf16 v[22:25], v[146:149], v[162:165], v[22:25]
	v_mfma_f32_16x16x32_bf16 v[18:21], v[154:157], v[162:165], v[18:21]
	v_mfma_f32_16x16x32_bf16 v[10:13], v[146:149], v[170:173], v[10:13]
	v_mfma_f32_16x16x32_bf16 v[6:9], v[154:157], v[170:173], v[6:9]
	v_mfma_f32_16x16x32_bf16 v[82:85], v[146:149], v[178:181], v[82:85]
	v_mfma_f32_16x16x32_bf16 v[94:97], v[154:157], v[178:181], v[94:97]
	v_mfma_f32_16x16x32_bf16 v[70:73], v[146:149], v[186:189], v[70:73]
	v_mfma_f32_16x16x32_bf16 v[66:69], v[154:157], v[186:189], v[66:69]
	v_mfma_f32_16x16x32_bf16 v[22:25], v[150:153], v[166:169], v[22:25]
	v_mfma_f32_16x16x32_bf16 v[18:21], v[158:161], v[166:169], v[18:21]
	v_mfma_f32_16x16x32_bf16 v[10:13], v[150:153], v[174:177], v[10:13]
	v_mfma_f32_16x16x32_bf16 v[6:9], v[158:161], v[174:177], v[6:9]
	v_mfma_f32_16x16x32_bf16 v[82:85], v[150:153], v[182:185], v[82:85]
	v_mfma_f32_16x16x32_bf16 v[94:97], v[158:161], v[182:185], v[94:97]
	v_mfma_f32_16x16x32_bf16 v[70:73], v[150:153], v[190:193], v[70:73]
	v_mfma_f32_16x16x32_bf16 v[66:69], v[158:161], v[190:193], v[66:69]
	s_add_i32 vcc_lo, vcc_lo, 2
	s_add_u32 s89, s89, 0x100
	s_addc_u32 s91, s91, 0
	s_mov_b64 s[30:31], s[4:5]
	s_add_u32 s4, s30, 0x100
	s_addc_u32 s5, s31, 0
	s_add_i32 vcc_hi, 0, 0x10000
	s_cmp_eq_u32 vcc_lo, 28
	s_cselect_b32 s41, s21, s5
	s_cselect_b32 s40, s20, s4
	s_cselect_b32 s7, s2, s91
	s_cselect_b32 s6, s3, s89
	s_add_i32 s86, 0, 0x14000
	s_cmp_gt_u32 vcc_lo, 29
	s_barrier
	s_cbranch_scc0 .LBB0_691
	s_and_b64 vcc, exec, s[26:27]
	s_cbranch_vccz .LBB0_694
	s_barrier

; #define PG8_STAGE(bufoff, gbase, voff) do { _Pragma("unroll") for (int _i = 0; _i < 2; ++_i) \
;         __builtin_amdgcn_global_load_lds((const unsigned*)((const char*)(gbase) + (voff)[_i]), (PG8_LAS unsigned*)(lds + (bufoff) + ldsw + _i * 8192), 16, 0, 0); } while (0)
; #define PG8_LDA(dst, b, h) do { _Pragma("unroll") for (int m = 0; m < 4; ++m) _Pragma("unroll") for (int k = 0; k < 2; ++k) dst[m][k] = *(const PG8_LAS bf16x8*)(lds + PG8_SA(b, h) + aoff + m * 2048 + k * 1024); } while (0)
; #define PG8_LDB(dst, b, h) do { _Pragma("unroll") for (int n = 0; n < 2; ++n) _Pragma("unroll") for (int k = 0; k < 2; ++k) dst[n][k] = *(const PG8_LAS bf16x8*)(lds + PG8_SB(b, h) + boff + n * 2048 + k * 1024); } while (0)
; template <class Epi, class Sched, bool ALIGN_EPI = false, bool SP2 = false>
; __device__ __forceinline__ void gemm_phase(PG8_LAS unsigned char* lds, const Gemm g, const Sched& S, const Epi& E, int wave_s) {
;     ...
;         const bool has_next = S.next(ui + 1, nxt);
;         const char* nA = has_next ? (const char*)g.A + (size_t)nxt.pm * tstepA + (size_t)(nxt.pn / g.npg) * (size_t)(K * 2) : cA; const char* nB = has_next ? (const char*)g.Bt + (size_t)nxt.pn * tstepB : cB;
;         for (int t = 0; t < nt; t += 2) {
;             const bool last = (t == nt - 2);
;             const char* a1 = cA + (size_t)(t + 1) * kstep;
;             const char* a2 = last ? nA : cA + (size_t)(t + 2) * kstep; const char* b2 = last ? nB : cB + (size_t)(t + 2) * kstep;
;             const char* a3 = a2 + kstep; const char* b3 = b2 + kstep;
;             if (last && has_next) S.a_ready(nxt);
;             if constexpr (SP2) {
;             PG8_LDB(B0, 0, 0); PG8_LDB(B1, 0, 1); PG8_SCHED; PG8_LDA(At, 0, 0); PG8_STAGE(PG8_SA(1, 1), a1 + hstepA, voffA);
;             PG8_WAIT_V(8); PG8_WAIT_L(0); PG8_BAR; PG8_MMA(0, 0, At, B0); PG8_MMA(0, 1, At, B1); PG8_BAR; PG8_SCHED;
;             PG8_LDA(At, 0, 1); PG8_STAGE(PG8_SB(0, 0), b2, voffB); PG8_STAGE(PG8_SB(0, 1), b2 + hstepB, voffB); PG8_STAGE(PG8_SA(0, 0), a2, voffA);
;             PG8_WAIT_V(8); PG8_WAIT_L(0); PG8_BAR; PG8_MMA(1, 0, At, B0); PG8_MMA(1, 1, At, B1); PG8_BAR; PG8_SCHED;
;             PG8_LDB(B0, 1, 0); PG8_LDB(B1, 1, 1); PG8_SCHED; PG8_LDA(At, 1, 0); PG8_STAGE(PG8_SA(0, 1), a2 + hstepA, voffA);
;             PG8_WAIT_V(8); PG8_WAIT_L(0); PG8_BAR; PG8_MMA(0, 0, At, B0); PG8_MMA(0, 1, At, B1); PG8_BAR; PG8_SCHED;
.LBB0_785:
	s_add_u32 s2, s30, 0x100
	s_addc_u32 s3, s31, 0
	s_mov_b32 s81, -2
	s_add_u32 s4, s8, 0x100
	s_addc_u32 s5, s9, 0
	s_add_i32 s84, 0, 0x10000
	s_cmpk_eq_i32 s81, 0x54
	s_cselect_b32 s31, s95, s5
	s_cselect_b32 s30, s94, s4
	s_cselect_b32 s7, s97, s3
	s_cselect_b32 s6, s96, s2
	s_add_i32 s85, 0, 0x14000
	v_add_u32_e32 v110, s84, v211
	v_add_u32_e32 v150, s85, v211
	ds_read_b128 v[78:81], v110
	ds_read_b128 v[86:89], v110 offset:1024
	ds_read_b128 v[102:105], v110 offset:2048
	ds_read_b128 v[110:113], v110 offset:3072
	ds_read_b128 v[122:125], v150
	ds_read_b128 v[134:137], v150 offset:1024
	ds_read_b128 v[146:149], v150 offset:2048
	ds_read_b128 v[150:153], v150 offset:3072
	v_lshl_add_u64 v[206:207], s[8:9], 0, v[198:199]
	s_add_i32 m0, s35, 0xc000
	ds_read_b128 v[162:165], v212
	ds_read_b128 v[166:169], v212 offset:1024
	ds_read_b128 v[170:173], v212 offset:2048
	ds_read_b128 v[174:177], v212 offset:3072
	ds_read_b128 v[178:181], v212 offset:4096
	ds_read_b128 v[182:185], v212 offset:5120
	ds_read_b128 v[186:189], v212 offset:6144
	ds_read_b128 v[202:205], v212 offset:7168
	global_load_lds_dwordx4 v[206:207], off
	v_lshl_add_u64 v[206:207], s[8:9], 0, v[200:201]
	s_add_i32 m0, s35, 0xe000
	s_nop 0
	global_load_lds_dwordx4 v[206:207], off
	s_waitcnt vmcnt(8)
	s_waitcnt lgkmcnt(0)
	s_barrier
	s_waitcnt lgkmcnt(0)
	v_mfma_f32_16x16x32_bf16 v[158:161], v[78:81], v[162:165], 0
	v_mfma_f32_16x16x32_bf16 v[154:157], v[102:105], v[162:165], 0
	v_mfma_f32_16x16x32_bf16 v[130:133], v[78:81], v[170:173], 0
	v_mfma_f32_16x16x32_bf16 v[126:129], v[102:105], v[170:173], 0
	v_mfma_f32_16x16x32_bf16 v[106:109], v[78:81], v[178:181], 0
	v_mfma_f32_16x16x32_bf16 v[98:101], v[102:105], v[178:181], 0
	v_mfma_f32_16x16x32_bf16 v[82:85], v[78:81], v[186:189], 0
	v_mfma_f32_16x16x32_bf16 v[74:77], v[102:105], v[186:189], 0
	v_mfma_f32_16x16x32_bf16 v[158:161], v[86:89], v[166:169], v[158:161]
	v_mfma_f32_16x16x32_bf16 v[154:157], v[110:113], v[166:169], v[154:157]
	v_mfma_f32_16x16x32_bf16 v[130:133], v[86:89], v[174:177], v[130:133]
	v_mfma_f32_16x16x32_bf16 v[126:129], v[110:113], v[174:177], v[126:129]
	v_mfma_f32_16x16x32_bf16 v[106:109], v[86:89], v[182:185], v[106:109]
	v_mfma_f32_16x16x32_bf16 v[98:101], v[110:113], v[182:185], v[98:101]
	v_mfma_f32_16x16x32_bf16 v[82:85], v[86:89], v[202:205], v[82:85]
	v_mfma_f32_16x16x32_bf16 v[74:77], v[110:113], v[202:205], v[74:77]
	v_mfma_f32_16x16x32_bf16 v[142:145], v[122:125], v[162:165], 0
	v_mfma_f32_16x16x32_bf16 v[138:141], v[146:149], v[162:165], 0
	v_mfma_f32_16x16x32_bf16 v[118:121], v[122:125], v[170:173], 0
	v_mfma_f32_16x16x32_bf16 v[114:117], v[146:149], v[170:173], 0
	v_mfma_f32_16x16x32_bf16 v[94:97], v[122:125], v[178:181], 0
	v_mfma_f32_16x16x32_bf16 v[90:93], v[146:149], v[178:181], 0
	v_mfma_f32_16x16x32_bf16 v[70:73], v[122:125], v[186:189], 0
	v_mfma_f32_16x16x32_bf16 v[66:69], v[146:149], v[186:189], 0
	v_mfma_f32_16x16x32_bf16 v[142:145], v[134:137], v[166:169], v[142:145]
	v_mfma_f32_16x16x32_bf16 v[138:141], v[150:153], v[166:169], v[138:141]
	v_mfma_f32_16x16x32_bf16 v[118:121], v[134:137], v[174:177], v[118:121]
	v_mfma_f32_16x16x32_bf16 v[114:117], v[150:153], v[174:177], v[114:117]
	v_mfma_f32_16x16x32_bf16 v[94:97], v[134:137], v[182:185], v[94:97]
	v_mfma_f32_16x16x32_bf16 v[90:93], v[150:153], v[182:185], v[90:93]
	v_mfma_f32_16x16x32_bf16 v[70:73], v[134:137], v[202:205], v[70:73]
	v_mfma_f32_16x16x32_bf16 v[66:69], v[150:153], v[202:205], v[66:69]
	s_barrier
	s_add_i32 s8, s84, s22
	v_lshl_add_u64 v[206:207], s[6:7], 0, v[194:195]
	s_mov_b32 m0, s8
	ds_read_b128 v[162:165], v212 offset:16384
	ds_read_b128 v[166:169], v212 offset:17408
	ds_read_b128 v[170:173], v212 offset:18432
	ds_read_b128 v[174:177], v212 offset:19456
	ds_read_b128 v[178:181], v212 offset:20480
	ds_read_b128 v[182:185], v212 offset:21504
	ds_read_b128 v[186:189], v212 offset:22528
	ds_read_b128 v[202:205], v212 offset:23552
	global_load_lds_dwordx4 v[206:207], off
	s_add_i32 m0, s8, 0x2000
	s_add_u32 s8, s6, 0x160000
	v_lshl_add_u64 v[208:209], s[6:7], 0, v[190:191]
	s_addc_u32 s9, s7, 0
	s_add_i32 s84, s85, s22
	global_load_lds_dwordx4 v[208:209], off
	v_lshl_add_u64 v[214:215], s[8:9], 0, v[194:195]
	s_mov_b32 m0, s84
	v_lshl_add_u64 v[216:217], s[30:31], 0, v[192:193]
	global_load_lds_dwordx4 v[214:215], off
	v_lshl_add_u64 v[214:215], s[8:9], 0, v[190:191]
	s_add_i32 m0, s84, 0x2000
	s_nop 0
	global_load_lds_dwordx4 v[214:215], off
	v_lshl_add_u64 v[214:215], s[30:31], 0, v[196:197]
	s_mov_b32 m0, s35
	s_nop 0
	global_load_lds_dwordx4 v[214:215], off
	s_mov_b32 m0, s36
	s_nop 0
	global_load_lds_dwordx4 v[216:217], off
	s_waitcnt vmcnt(8)
	s_waitcnt lgkmcnt(0)
	s_barrier
; #define PG8_STAGE(bufoff, gbase, voff) do { _Pragma("unroll") for (int _i = 0; _i < 2; ++_i) \
;         __builtin_amdgcn_global_load_lds((const unsigned*)((const char*)(gbase) + (voff)[_i]), (PG8_LAS unsigned*)(lds + (bufoff) + ldsw + _i * 8192), 16, 0, 0); } while (0)
; #define PG8_LDA(dst, b, h) do { _Pragma("unroll") for (int m = 0; m < 4; ++m) _Pragma("unroll") for (int k = 0; k < 2; ++k) dst[m][k] = *(const PG8_LAS bf16x8*)(lds + PG8_SA(b, h) + aoff + m * 2048 + k * 1024); } while (0)
; #define PG8_LDB(dst, b, h) do { _Pragma("unroll") for (int n = 0; n < 2; ++n) _Pragma("unroll") for (int k = 0; k < 2; ++k) dst[n][k] = *(const PG8_LAS bf16x8*)(lds + PG8_SB(b, h) + boff + n * 2048 + k * 1024); } while (0)
; #define PG8_MMA(ai, bj, At, Bt) do { __builtin_amdgcn_s_setprio(1); _Pragma("unroll") for (int m = 0; m < 4; ++m) _Pragma("unroll") for (int n = 0; n < 2; ++n) _Pragma("unroll") for (int k = 0; k < 2; ++k) \
;         acc[ai][bj][m][n] = __builtin_amdgcn_mfma_f32_16x16x32_bf16(Bt[n][k], At[m][k], acc[ai][bj][m][n], 0, 0, 0); __builtin_amdgcn_s_setprio(0); } while (0)
; #define PG8_WAIT_V(n) asm volatile("s_waitcnt vmcnt(" #n ")" ::: "memory")
; #define PG8_WAIT_L(n) asm volatile("s_waitcnt lgkmcnt(" #n ")" ::: "memory")
; #define PG8_BAR __builtin_amdgcn_s_barrier()
; #define PG8_SCHED __builtin_amdgcn_sched_barrier(0)
; template <class Epi, class Sched, bool ALIGN_EPI = false, bool SP2 = false>
; __device__ __forceinline__ void gemm_phase(PG8_LAS unsigned char* lds, const Gemm g, const Sched& S, const Epi& E, int wave_s) {
;     ...
;             PG8_WAIT_V(8); PG8_WAIT_L(0); PG8_BAR; PG8_MMA(1, 0, At, B0); PG8_MMA(1, 1, At, B1); PG8_BAR; PG8_SCHED;
;             PG8_LDB(B0, 1, 0); PG8_LDB(B1, 1, 1); PG8_SCHED; PG8_LDA(At, 1, 0); PG8_STAGE(PG8_SA(0, 1), a2 + hstepA, voffA);
;             PG8_WAIT_V(8); PG8_WAIT_L(0); PG8_BAR; PG8_MMA(0, 0, At, B0); PG8_MMA(0, 1, At, B1); PG8_BAR; PG8_SCHED;
	s_waitcnt lgkmcnt(0)
	v_mfma_f32_16x16x32_bf16 v[62:65], v[78:81], v[162:165], 0
	v_mfma_f32_16x16x32_bf16 v[58:61], v[102:105], v[162:165], 0
	v_mfma_f32_16x16x32_bf16 v[46:49], v[78:81], v[170:173], 0
	v_mfma_f32_16x16x32_bf16 v[42:45], v[102:105], v[170:173], 0
	v_mfma_f32_16x16x32_bf16 v[30:33], v[78:81], v[178:181], 0
	v_mfma_f32_16x16x32_bf16 v[26:29], v[102:105], v[178:181], 0
	v_mfma_f32_16x16x32_bf16 v[14:17], v[78:81], v[186:189], 0
	v_mfma_f32_16x16x32_bf16 v[10:13], v[102:105], v[186:189], 0
	v_mfma_f32_16x16x32_bf16 v[62:65], v[86:89], v[166:169], v[62:65]
	v_mfma_f32_16x16x32_bf16 v[58:61], v[110:113], v[166:169], v[58:61]
	v_mfma_f32_16x16x32_bf16 v[46:49], v[86:89], v[174:177], v[46:49]
	v_mfma_f32_16x16x32_bf16 v[42:45], v[110:113], v[174:177], v[42:45]
	v_mfma_f32_16x16x32_bf16 v[30:33], v[86:89], v[182:185], v[30:33]
	v_mfma_f32_16x16x32_bf16 v[26:29], v[110:113], v[182:185], v[26:29]
	v_mfma_f32_16x16x32_bf16 v[14:17], v[86:89], v[202:205], v[14:17]
	v_mfma_f32_16x16x32_bf16 v[10:13], v[110:113], v[202:205], v[10:13]
	v_mfma_f32_16x16x32_bf16 v[54:57], v[122:125], v[162:165], 0
	v_mfma_f32_16x16x32_bf16 v[50:53], v[146:149], v[162:165], 0
	v_mfma_f32_16x16x32_bf16 v[38:41], v[122:125], v[170:173], 0
	v_mfma_f32_16x16x32_bf16 v[34:37], v[146:149], v[170:173], 0
	v_mfma_f32_16x16x32_bf16 v[22:25], v[122:125], v[178:181], 0
	v_mfma_f32_16x16x32_bf16 v[18:21], v[146:149], v[178:181], 0
	v_mfma_f32_16x16x32_bf16 v[6:9], v[122:125], v[186:189], 0
	v_mfma_f32_16x16x32_bf16 v[2:5], v[146:149], v[186:189], 0
	v_mfma_f32_16x16x32_bf16 v[54:57], v[134:137], v[166:169], v[54:57]
	v_mfma_f32_16x16x32_bf16 v[50:53], v[150:153], v[166:169], v[50:53]
	v_mfma_f32_16x16x32_bf16 v[38:41], v[134:137], v[174:177], v[38:41]
	v_mfma_f32_16x16x32_bf16 v[34:37], v[150:153], v[174:177], v[34:37]
	v_mfma_f32_16x16x32_bf16 v[22:25], v[134:137], v[182:185], v[22:25]
	v_mfma_f32_16x16x32_bf16 v[18:21], v[150:153], v[182:185], v[18:21]
	v_mfma_f32_16x16x32_bf16 v[6:9], v[134:137], v[202:205], v[6:9]
	v_mfma_f32_16x16x32_bf16 v[2:5], v[150:153], v[202:205], v[2:5]
	s_barrier
	s_add_i32 s84, 0, 0x18000
	s_add_i32 s85, 0, 0x1c000
	v_add_u32_e32 v110, s84, v211
	v_add_u32_e32 v150, s85, v211
	ds_read_b128 v[78:81], v110
	ds_read_b128 v[86:89], v110 offset:1024
	ds_read_b128 v[102:105], v110 offset:2048
	ds_read_b128 v[110:113], v110 offset:3072
	ds_read_b128 v[122:125], v150
	ds_read_b128 v[134:137], v150 offset:1024
	ds_read_b128 v[146:149], v150 offset:2048
	ds_read_b128 v[150:153], v150 offset:3072
	s_add_u32 s8, s30, 0x160000
	s_addc_u32 s9, s31, 0
	s_mov_b32 m0, s37
	v_lshl_add_u64 v[218:219], s[8:9], 0, v[196:197]
	ds_read_b128 v[162:165], v212 offset:32768
	ds_read_b128 v[166:169], v212 offset:33792
	ds_read_b128 v[170:173], v212 offset:34816
	ds_read_b128 v[174:177], v212 offset:35840
	ds_read_b128 v[178:181], v212 offset:36864
	ds_read_b128 v[182:185], v212 offset:37888
	ds_read_b128 v[186:189], v212 offset:38912
	ds_read_b128 v[202:205], v212 offset:39936
	global_load_lds_dwordx4 v[218:219], off
	v_lshl_add_u64 v[218:219], s[8:9], 0, v[192:193]
	s_mov_b32 m0, s40
	s_nop 0
	global_load_lds_dwordx4 v[218:219], off
	s_waitcnt vmcnt(8)
	s_waitcnt lgkmcnt(0)
	s_barrier
	s_waitcnt lgkmcnt(0)
	v_mfma_f32_16x16x32_bf16 v[158:161], v[78:81], v[162:165], v[158:161]
	v_mfma_f32_16x16x32_bf16 v[154:157], v[102:105], v[162:165], v[154:157]
	v_mfma_f32_16x16x32_bf16 v[130:133], v[78:81], v[170:173], v[130:133]
	v_mfma_f32_16x16x32_bf16 v[126:129], v[102:105], v[170:173], v[126:129]
	v_mfma_f32_16x16x32_bf16 v[106:109], v[78:81], v[178:181], v[106:109]
	v_mfma_f32_16x16x32_bf16 v[98:101], v[102:105], v[178:181], v[98:101]
	v_mfma_f32_16x16x32_bf16 v[82:85], v[78:81], v[186:189], v[82:85]
	v_mfma_f32_16x16x32_bf16 v[74:77], v[102:105], v[186:189], v[74:77]
	v_mfma_f32_16x16x32_bf16 v[158:161], v[86:89], v[166:169], v[158:161]
	v_mfma_f32_16x16x32_bf16 v[154:157], v[110:113], v[166:169], v[154:157]
	v_mfma_f32_16x16x32_bf16 v[130:133], v[86:89], v[174:177], v[130:133]
	v_mfma_f32_16x16x32_bf16 v[126:129], v[110:113], v[174:177], v[126:129]
	v_mfma_f32_16x16x32_bf16 v[106:109], v[86:89], v[182:185], v[106:109]
	v_mfma_f32_16x16x32_bf16 v[98:101], v[110:113], v[182:185], v[98:101]
	v_mfma_f32_16x16x32_bf16 v[82:85], v[86:89], v[202:205], v[82:85]
	v_mfma_f32_16x16x32_bf16 v[74:77], v[110:113], v[202:205], v[74:77]
	v_mfma_f32_16x16x32_bf16 v[142:145], v[122:125], v[162:165], v[142:145]
	v_mfma_f32_16x16x32_bf16 v[138:141], v[146:149], v[162:165], v[138:141]
	v_mfma_f32_16x16x32_bf16 v[118:121], v[122:125], v[170:173], v[118:121]
	v_mfma_f32_16x16x32_bf16 v[114:117], v[146:149], v[170:173], v[114:117]
	v_mfma_f32_16x16x32_bf16 v[94:97], v[122:125], v[178:181], v[94:97]
	v_mfma_f32_16x16x32_bf16 v[90:93], v[146:149], v[178:181], v[90:93]
	v_mfma_f32_16x16x32_bf16 v[70:73], v[122:125], v[186:189], v[70:73]
	v_mfma_f32_16x16x32_bf16 v[66:69], v[146:149], v[186:189], v[66:69]
	v_mfma_f32_16x16x32_bf16 v[142:145], v[134:137], v[166:169], v[142:145]
	v_mfma_f32_16x16x32_bf16 v[138:141], v[150:153], v[166:169], v[138:141]
	v_mfma_f32_16x16x32_bf16 v[118:121], v[134:137], v[174:177], v[118:121]
	v_mfma_f32_16x16x32_bf16 v[114:117], v[150:153], v[174:177], v[114:117]
	v_mfma_f32_16x16x32_bf16 v[94:97], v[134:137], v[182:185], v[94:97]
	v_mfma_f32_16x16x32_bf16 v[90:93], v[150:153], v[182:185], v[90:93]
	v_mfma_f32_16x16x32_bf16 v[70:73], v[134:137], v[202:205], v[70:73]
	v_mfma_f32_16x16x32_bf16 v[66:69], v[150:153], v[202:205], v[66:69]
	s_barrier
; #define PG8_STAGE(bufoff, gbase, voff) do { _Pragma("unroll") for (int _i = 0; _i < 2; ++_i) \
;         __builtin_amdgcn_global_load_lds((const unsigned*)((const char*)(gbase) + (voff)[_i]), (PG8_LAS unsigned*)(lds + (bufoff) + ldsw + _i * 8192), 16, 0, 0); } while (0)
; #define PG8_LDA(dst, b, h) do { _Pragma("unroll") for (int m = 0; m < 4; ++m) _Pragma("unroll") for (int k = 0; k < 2; ++k) dst[m][k] = *(const PG8_LAS bf16x8*)(lds + PG8_SA(b, h) + aoff + m * 2048 + k * 1024); } while (0)
; #define PG8_LDB(dst, b, h) do { _Pragma("unroll") for (int n = 0; n < 2; ++n) _Pragma("unroll") for (int k = 0; k < 2; ++k) dst[n][k] = *(const PG8_LAS bf16x8*)(lds + PG8_SB(b, h) + boff + n * 2048 + k * 1024); } while (0)
; #define PG8_MMA(ai, bj, At, Bt) do { __builtin_amdgcn_s_setprio(1); _Pragma("unroll") for (int m = 0; m < 4; ++m) _Pragma("unroll") for (int n = 0; n < 2; ++n) _Pragma("unroll") for (int k = 0; k < 2; ++k) \
;         acc[ai][bj][m][n] = __builtin_amdgcn_mfma_f32_16x16x32_bf16(Bt[n][k], At[m][k], acc[ai][bj][m][n], 0, 0, 0); __builtin_amdgcn_s_setprio(0); } while (0)
; #define PG8_WAIT_V(n) asm volatile("s_waitcnt vmcnt(" #n ")" ::: "memory")
; #define PG8_WAIT_L(n) asm volatile("s_waitcnt lgkmcnt(" #n ")" ::: "memory")
; #define PG8_BAR __builtin_amdgcn_s_barrier()
; #define PG8_SCHED __builtin_amdgcn_sched_barrier(0)
; template <class Epi, class Sched, bool ALIGN_EPI = false, bool SP2 = false>
; __device__ __forceinline__ void gemm_phase(PG8_LAS unsigned char* lds, const Gemm g, const Sched& S, const Epi& E, int wave_s) {
;     ...
;             PG8_LDB(B0, 0, 0); PG8_LDB(B1, 0, 1); PG8_SCHED; PG8_LDA(At, 0, 0); PG8_STAGE(PG8_SA(1, 1), a1 + hstepA, voffA);
;     ...
;             PG8_LDA(At, 1, 1); PG8_STAGE(PG8_SB(1, 0), b3, voffB); PG8_STAGE(PG8_SB(1, 1), b3 + hstepB, voffB); PG8_STAGE(PG8_SA(1, 0), a3, voffA);
;             PG8_WAIT_V(8); PG8_WAIT_L(0); PG8_BAR; PG8_MMA(1, 0, At, B0); PG8_MMA(1, 1, At, B1); PG8_BAR; PG8_SCHED;
	s_add_i32 s8, s84, s22
	v_lshl_add_u64 v[206:207], v[206:207], 0, s[60:61]
	s_mov_b32 m0, s8
	ds_read_b128 v[162:165], v212 offset:49152
	ds_read_b128 v[166:169], v212 offset:50176
	ds_read_b128 v[170:173], v212 offset:51200
	ds_read_b128 v[174:177], v212 offset:52224
	ds_read_b128 v[178:181], v212 offset:53248
	ds_read_b128 v[182:185], v212 offset:54272
	ds_read_b128 v[186:189], v212 offset:55296
	ds_read_b128 v[202:205], v212 offset:56320
	global_load_lds_dwordx4 v[206:207], off
	s_add_i32 m0, s8, 0x2000
	s_add_u32 s6, s6, 0x160080
	v_lshl_add_u64 v[206:207], v[208:209], 0, s[60:61]
	s_addc_u32 s7, s7, 0
	s_add_i32 s8, s85, s22
	global_load_lds_dwordx4 v[206:207], off
	v_lshl_add_u64 v[206:207], s[6:7], 0, v[194:195]
	s_mov_b32 m0, s8
	s_nop 0
	global_load_lds_dwordx4 v[206:207], off
	v_lshl_add_u64 v[206:207], s[6:7], 0, v[190:191]
	s_add_i32 m0, s8, 0x2000
	s_nop 0
	global_load_lds_dwordx4 v[206:207], off
	v_lshl_add_u64 v[206:207], v[214:215], 0, s[60:61]
	s_mov_b32 m0, s44
	s_nop 0
	global_load_lds_dwordx4 v[206:207], off
	v_lshl_add_u64 v[206:207], v[216:217], 0, s[60:61]
	s_mov_b32 m0, s45
	s_nop 0
	global_load_lds_dwordx4 v[206:207], off
	s_waitcnt vmcnt(8)
	s_waitcnt lgkmcnt(0)
	s_barrier
	s_waitcnt lgkmcnt(0)
	v_mfma_f32_16x16x32_bf16 v[62:65], v[78:81], v[162:165], v[62:65]
	v_mfma_f32_16x16x32_bf16 v[58:61], v[102:105], v[162:165], v[58:61]
	v_mfma_f32_16x16x32_bf16 v[46:49], v[78:81], v[170:173], v[46:49]
	v_mfma_f32_16x16x32_bf16 v[42:45], v[102:105], v[170:173], v[42:45]
	v_mfma_f32_16x16x32_bf16 v[30:33], v[78:81], v[178:181], v[30:33]
	v_mfma_f32_16x16x32_bf16 v[26:29], v[102:105], v[178:181], v[26:29]
	v_mfma_f32_16x16x32_bf16 v[14:17], v[78:81], v[186:189], v[14:17]
	v_mfma_f32_16x16x32_bf16 v[10:13], v[102:105], v[186:189], v[10:13]
	v_mfma_f32_16x16x32_bf16 v[62:65], v[86:89], v[166:169], v[62:65]
	v_mfma_f32_16x16x32_bf16 v[58:61], v[110:113], v[166:169], v[58:61]
	v_mfma_f32_16x16x32_bf16 v[46:49], v[86:89], v[174:177], v[46:49]
	v_mfma_f32_16x16x32_bf16 v[42:45], v[110:113], v[174:177], v[42:45]
	v_mfma_f32_16x16x32_bf16 v[30:33], v[86:89], v[182:185], v[30:33]
	v_mfma_f32_16x16x32_bf16 v[26:29], v[110:113], v[182:185], v[26:29]
	v_mfma_f32_16x16x32_bf16 v[14:17], v[86:89], v[202:205], v[14:17]
	v_mfma_f32_16x16x32_bf16 v[10:13], v[110:113], v[202:205], v[10:13]
	v_mfma_f32_16x16x32_bf16 v[54:57], v[122:125], v[162:165], v[54:57]
	v_mfma_f32_16x16x32_bf16 v[50:53], v[146:149], v[162:165], v[50:53]
	v_mfma_f32_16x16x32_bf16 v[38:41], v[122:125], v[170:173], v[38:41]
	v_mfma_f32_16x16x32_bf16 v[34:37], v[146:149], v[170:173], v[34:37]
	v_mfma_f32_16x16x32_bf16 v[22:25], v[122:125], v[178:181], v[22:25]
	v_mfma_f32_16x16x32_bf16 v[18:21], v[146:149], v[178:181], v[18:21]
	v_mfma_f32_16x16x32_bf16 v[6:9], v[122:125], v[186:189], v[6:9]
	v_mfma_f32_16x16x32_bf16 v[2:5], v[146:149], v[186:189], v[2:5]
	v_mfma_f32_16x16x32_bf16 v[54:57], v[134:137], v[166:169], v[54:57]
	v_mfma_f32_16x16x32_bf16 v[50:53], v[150:153], v[166:169], v[50:53]
	v_mfma_f32_16x16x32_bf16 v[38:41], v[134:137], v[174:177], v[38:41]
	v_mfma_f32_16x16x32_bf16 v[34:37], v[150:153], v[174:177], v[34:37]
	v_mfma_f32_16x16x32_bf16 v[22:25], v[134:137], v[182:185], v[22:25]
	v_mfma_f32_16x16x32_bf16 v[18:21], v[150:153], v[182:185], v[18:21]
	v_mfma_f32_16x16x32_bf16 v[6:9], v[134:137], v[202:205], v[6:9]
	v_mfma_f32_16x16x32_bf16 v[2:5], v[150:153], v[202:205], v[2:5]
	s_add_i32 s81, s81, 2
	s_add_u32 s2, s2, 0x100
	s_addc_u32 s3, s3, 0
	s_mov_b64 s[8:9], s[4:5]
	s_add_u32 s4, s8, 0x100
	s_addc_u32 s5, s9, 0
	s_add_i32 s84, 0, 0x10000
	s_cmpk_eq_i32 s81, 0x54
	s_cselect_b32 s31, s95, s5
	s_cselect_b32 s30, s94, s4
	s_cselect_b32 s7, s97, s3
	s_cselect_b32 s6, s96, s2
	s_add_i32 s85, 0, 0x14000
	s_cmpk_gt_u32 s81, 0x55
	s_barrier
.LBB0_786:
	v_add_u32_e32 v110, s84, v211
	v_add_u32_e32 v150, s85, v211
	ds_read_b128 v[78:81], v110
	ds_read_b128 v[86:89], v110 offset:1024
	ds_read_b128 v[102:105], v110 offset:2048
	ds_read_b128 v[110:113], v110 offset:3072
	ds_read_b128 v[122:125], v150
	ds_read_b128 v[134:137], v150 offset:1024
	ds_read_b128 v[146:149], v150 offset:2048
	ds_read_b128 v[150:153], v150 offset:3072
	v_lshl_add_u64 v[206:207], s[8:9], 0, v[198:199]
	s_add_i32 m0, s35, 0xc000
	ds_read_b128 v[162:165], v212
	ds_read_b128 v[166:169], v212 offset:1024
	ds_read_b128 v[170:173], v212 offset:2048
	ds_read_b128 v[174:177], v212 offset:3072
	ds_read_b128 v[178:181], v212 offset:4096
	ds_read_b128 v[182:185], v212 offset:5120
	ds_read_b128 v[186:189], v212 offset:6144
	ds_read_b128 v[202:205], v212 offset:7168
	global_load_lds_dwordx4 v[206:207], off
	v_lshl_add_u64 v[206:207], s[8:9], 0, v[200:201]
	s_add_i32 m0, s35, 0xe000
	s_nop 0
	global_load_lds_dwordx4 v[206:207], off
	s_waitcnt vmcnt(8)
	s_waitcnt lgkmcnt(0)
	s_barrier
; #define PG8_STAGE(bufoff, gbase, voff) do { _Pragma("unroll") for (int _i = 0; _i < 2; ++_i) \
;         __builtin_amdgcn_global_load_lds((const unsigned*)((const char*)(gbase) + (voff)[_i]), (PG8_LAS unsigned*)(lds + (bufoff) + ldsw + _i * 8192), 16, 0, 0); } while (0)
; #define PG8_LDA(dst, b, h) do { _Pragma("unroll") for (int m = 0; m < 4; ++m) _Pragma("unroll") for (int k = 0; k < 2; ++k) dst[m][k] = *(const PG8_LAS bf16x8*)(lds + PG8_SA(b, h) + aoff + m * 2048 + k * 1024); } while (0)
; #define PG8_MMA(ai, bj, At, Bt) do { __builtin_amdgcn_s_setprio(1); _Pragma("unroll") for (int m = 0; m < 4; ++m) _Pragma("unroll") for (int n = 0; n < 2; ++n) _Pragma("unroll") for (int k = 0; k < 2; ++k) \
;         acc[ai][bj][m][n] = __builtin_amdgcn_mfma_f32_16x16x32_bf16(Bt[n][k], At[m][k], acc[ai][bj][m][n], 0, 0, 0); __builtin_amdgcn_s_setprio(0); } while (0)
; #define PG8_WAIT_V(n) asm volatile("s_waitcnt vmcnt(" #n ")" ::: "memory")
; #define PG8_WAIT_L(n) asm volatile("s_waitcnt lgkmcnt(" #n ")" ::: "memory")
; #define PG8_BAR __builtin_amdgcn_s_barrier()
; #define PG8_SCHED __builtin_amdgcn_sched_barrier(0)
; template <class Epi, class Sched, bool ALIGN_EPI = false, bool SP2 = false>
; __device__ __forceinline__ void gemm_phase(PG8_LAS unsigned char* lds, const Gemm g, const Sched& S, const Epi& E, int wave_s) {
;     ...
;             PG8_WAIT_V(8); PG8_WAIT_L(0); PG8_BAR; PG8_MMA(0, 0, At, B0); PG8_MMA(0, 1, At, B1); PG8_BAR; PG8_SCHED;
;             PG8_LDA(At, 0, 1); PG8_STAGE(PG8_SB(0, 0), b2, voffB); PG8_STAGE(PG8_SB(0, 1), b2 + hstepB, voffB); PG8_STAGE(PG8_SA(0, 0), a2, voffA);
;             PG8_WAIT_V(8); PG8_WAIT_L(0); PG8_BAR; PG8_MMA(1, 0, At, B0); PG8_MMA(1, 1, At, B1); PG8_BAR; PG8_SCHED;
	s_waitcnt lgkmcnt(0)
	v_mfma_f32_16x16x32_bf16 v[158:161], v[78:81], v[162:165], v[158:161]
	v_mfma_f32_16x16x32_bf16 v[154:157], v[102:105], v[162:165], v[154:157]
	v_mfma_f32_16x16x32_bf16 v[130:133], v[78:81], v[170:173], v[130:133]
	v_mfma_f32_16x16x32_bf16 v[126:129], v[102:105], v[170:173], v[126:129]
	v_mfma_f32_16x16x32_bf16 v[106:109], v[78:81], v[178:181], v[106:109]
	v_mfma_f32_16x16x32_bf16 v[98:101], v[102:105], v[178:181], v[98:101]
	v_mfma_f32_16x16x32_bf16 v[82:85], v[78:81], v[186:189], v[82:85]
	v_mfma_f32_16x16x32_bf16 v[74:77], v[102:105], v[186:189], v[74:77]
	v_mfma_f32_16x16x32_bf16 v[158:161], v[86:89], v[166:169], v[158:161]
	v_mfma_f32_16x16x32_bf16 v[154:157], v[110:113], v[166:169], v[154:157]
	v_mfma_f32_16x16x32_bf16 v[130:133], v[86:89], v[174:177], v[130:133]
	v_mfma_f32_16x16x32_bf16 v[126:129], v[110:113], v[174:177], v[126:129]
	v_mfma_f32_16x16x32_bf16 v[106:109], v[86:89], v[182:185], v[106:109]
	v_mfma_f32_16x16x32_bf16 v[98:101], v[110:113], v[182:185], v[98:101]
	v_mfma_f32_16x16x32_bf16 v[82:85], v[86:89], v[202:205], v[82:85]
	v_mfma_f32_16x16x32_bf16 v[74:77], v[110:113], v[202:205], v[74:77]
	v_mfma_f32_16x16x32_bf16 v[142:145], v[122:125], v[162:165], v[142:145]
	v_mfma_f32_16x16x32_bf16 v[138:141], v[146:149], v[162:165], v[138:141]
	v_mfma_f32_16x16x32_bf16 v[118:121], v[122:125], v[170:173], v[118:121]
	v_mfma_f32_16x16x32_bf16 v[114:117], v[146:149], v[170:173], v[114:117]
	v_mfma_f32_16x16x32_bf16 v[94:97], v[122:125], v[178:181], v[94:97]
	v_mfma_f32_16x16x32_bf16 v[90:93], v[146:149], v[178:181], v[90:93]
	v_mfma_f32_16x16x32_bf16 v[70:73], v[122:125], v[186:189], v[70:73]
	v_mfma_f32_16x16x32_bf16 v[66:69], v[146:149], v[186:189], v[66:69]
	v_mfma_f32_16x16x32_bf16 v[142:145], v[134:137], v[166:169], v[142:145]
	v_mfma_f32_16x16x32_bf16 v[138:141], v[150:153], v[166:169], v[138:141]
	v_mfma_f32_16x16x32_bf16 v[118:121], v[134:137], v[174:177], v[118:121]
	v_mfma_f32_16x16x32_bf16 v[114:117], v[150:153], v[174:177], v[114:117]
	v_mfma_f32_16x16x32_bf16 v[94:97], v[134:137], v[182:185], v[94:97]
	v_mfma_f32_16x16x32_bf16 v[90:93], v[150:153], v[182:185], v[90:93]
	v_mfma_f32_16x16x32_bf16 v[70:73], v[134:137], v[202:205], v[70:73]
	v_mfma_f32_16x16x32_bf16 v[66:69], v[150:153], v[202:205], v[66:69]
	s_barrier
	s_add_i32 s8, s84, s22
	v_lshl_add_u64 v[206:207], s[6:7], 0, v[194:195]
	s_mov_b32 m0, s8
	ds_read_b128 v[162:165], v212 offset:16384
	ds_read_b128 v[166:169], v212 offset:17408
	ds_read_b128 v[170:173], v212 offset:18432
	ds_read_b128 v[174:177], v212 offset:19456
	ds_read_b128 v[178:181], v212 offset:20480
	ds_read_b128 v[182:185], v212 offset:21504
	ds_read_b128 v[186:189], v212 offset:22528
	ds_read_b128 v[202:205], v212 offset:23552
	global_load_lds_dwordx4 v[206:207], off
	s_add_i32 m0, s8, 0x2000
	s_add_u32 s8, s6, 0x160000
	v_lshl_add_u64 v[208:209], s[6:7], 0, v[190:191]
	s_addc_u32 s9, s7, 0
	s_add_i32 s84, s85, s22
	global_load_lds_dwordx4 v[208:209], off
	v_lshl_add_u64 v[214:215], s[8:9], 0, v[194:195]
	s_mov_b32 m0, s84
	v_lshl_add_u64 v[216:217], s[30:31], 0, v[192:193]
	global_load_lds_dwordx4 v[214:215], off
	v_lshl_add_u64 v[214:215], s[8:9], 0, v[190:191]
	s_add_i32 m0, s84, 0x2000
	s_nop 0
	global_load_lds_dwordx4 v[214:215], off
	v_lshl_add_u64 v[214:215], s[30:31], 0, v[196:197]
	s_mov_b32 m0, s35
	s_nop 0
	global_load_lds_dwordx4 v[214:215], off
	s_mov_b32 m0, s36
	s_nop 0
	global_load_lds_dwordx4 v[216:217], off
	s_waitcnt vmcnt(8)
	s_waitcnt lgkmcnt(0)
	s_barrier
	s_waitcnt lgkmcnt(0)
	v_mfma_f32_16x16x32_bf16 v[62:65], v[78:81], v[162:165], v[62:65]
	v_mfma_f32_16x16x32_bf16 v[58:61], v[102:105], v[162:165], v[58:61]
	v_mfma_f32_16x16x32_bf16 v[46:49], v[78:81], v[170:173], v[46:49]
	v_mfma_f32_16x16x32_bf16 v[42:45], v[102:105], v[170:173], v[42:45]
	v_mfma_f32_16x16x32_bf16 v[30:33], v[78:81], v[178:181], v[30:33]
	v_mfma_f32_16x16x32_bf16 v[26:29], v[102:105], v[178:181], v[26:29]
	v_mfma_f32_16x16x32_bf16 v[14:17], v[78:81], v[186:189], v[14:17]
	v_mfma_f32_16x16x32_bf16 v[10:13], v[102:105], v[186:189], v[10:13]
	v_mfma_f32_16x16x32_bf16 v[62:65], v[86:89], v[166:169], v[62:65]
	v_mfma_f32_16x16x32_bf16 v[58:61], v[110:113], v[166:169], v[58:61]
	v_mfma_f32_16x16x32_bf16 v[46:49], v[86:89], v[174:177], v[46:49]
	v_mfma_f32_16x16x32_bf16 v[42:45], v[110:113], v[174:177], v[42:45]
	v_mfma_f32_16x16x32_bf16 v[30:33], v[86:89], v[182:185], v[30:33]
	v_mfma_f32_16x16x32_bf16 v[26:29], v[110:113], v[182:185], v[26:29]
	v_mfma_f32_16x16x32_bf16 v[14:17], v[86:89], v[202:205], v[14:17]
	v_mfma_f32_16x16x32_bf16 v[10:13], v[110:113], v[202:205], v[10:13]
	v_mfma_f32_16x16x32_bf16 v[54:57], v[122:125], v[162:165], v[54:57]
	v_mfma_f32_16x16x32_bf16 v[50:53], v[146:149], v[162:165], v[50:53]
	v_mfma_f32_16x16x32_bf16 v[38:41], v[122:125], v[170:173], v[38:41]
	v_mfma_f32_16x16x32_bf16 v[34:37], v[146:149], v[170:173], v[34:37]
	v_mfma_f32_16x16x32_bf16 v[22:25], v[122:125], v[178:181], v[22:25]
	v_mfma_f32_16x16x32_bf16 v[18:21], v[146:149], v[178:181], v[18:21]
	v_mfma_f32_16x16x32_bf16 v[6:9], v[122:125], v[186:189], v[6:9]
	v_mfma_f32_16x16x32_bf16 v[2:5], v[146:149], v[186:189], v[2:5]
	v_mfma_f32_16x16x32_bf16 v[54:57], v[134:137], v[166:169], v[54:57]
	v_mfma_f32_16x16x32_bf16 v[50:53], v[150:153], v[166:169], v[50:53]
	v_mfma_f32_16x16x32_bf16 v[38:41], v[134:137], v[174:177], v[38:41]
	v_mfma_f32_16x16x32_bf16 v[34:37], v[150:153], v[174:177], v[34:37]
	v_mfma_f32_16x16x32_bf16 v[22:25], v[134:137], v[182:185], v[22:25]
	v_mfma_f32_16x16x32_bf16 v[18:21], v[150:153], v[182:185], v[18:21]
	v_mfma_f32_16x16x32_bf16 v[6:9], v[134:137], v[202:205], v[6:9]
	v_mfma_f32_16x16x32_bf16 v[2:5], v[150:153], v[202:205], v[2:5]
	s_barrier
; #define PG8_STAGE(bufoff, gbase, voff) do { _Pragma("unroll") for (int _i = 0; _i < 2; ++_i) \
;         __builtin_amdgcn_global_load_lds((const unsigned*)((const char*)(gbase) + (voff)[_i]), (PG8_LAS unsigned*)(lds + (bufoff) + ldsw + _i * 8192), 16, 0, 0); } while (0)
; #define PG8_LDA(dst, b, h) do { _Pragma("unroll") for (int m = 0; m < 4; ++m) _Pragma("unroll") for (int k = 0; k < 2; ++k) dst[m][k] = *(const PG8_LAS bf16x8*)(lds + PG8_SA(b, h) + aoff + m * 2048 + k * 1024); } while (0)
; #define PG8_LDB(dst, b, h) do { _Pragma("unroll") for (int n = 0; n < 2; ++n) _Pragma("unroll") for (int k = 0; k < 2; ++k) dst[n][k] = *(const PG8_LAS bf16x8*)(lds + PG8_SB(b, h) + boff + n * 2048 + k * 1024); } while (0)
; #define PG8_MMA(ai, bj, At, Bt) do { __builtin_amdgcn_s_setprio(1); _Pragma("unroll") for (int m = 0; m < 4; ++m) _Pragma("unroll") for (int n = 0; n < 2; ++n) _Pragma("unroll") for (int k = 0; k < 2; ++k) \
;         acc[ai][bj][m][n] = __builtin_amdgcn_mfma_f32_16x16x32_bf16(Bt[n][k], At[m][k], acc[ai][bj][m][n], 0, 0, 0); __builtin_amdgcn_s_setprio(0); } while (0)
; #define PG8_WAIT_V(n) asm volatile("s_waitcnt vmcnt(" #n ")" ::: "memory")
; #define PG8_WAIT_L(n) asm volatile("s_waitcnt lgkmcnt(" #n ")" ::: "memory")
; #define PG8_BAR __builtin_amdgcn_s_barrier()
; #define PG8_SCHED __builtin_amdgcn_sched_barrier(0)
; template <class Epi, class Sched, bool ALIGN_EPI = false, bool SP2 = false>
; __device__ __forceinline__ void gemm_phase(PG8_LAS unsigned char* lds, const Gemm g, const Sched& S, const Epi& E, int wave_s) {
;     ...
;             PG8_LDB(B0, 1, 0); PG8_LDB(B1, 1, 1); PG8_SCHED; PG8_LDA(At, 1, 0); PG8_STAGE(PG8_SA(0, 1), a2 + hstepA, voffA);
;             PG8_WAIT_V(8); PG8_WAIT_L(0); PG8_BAR; PG8_MMA(0, 0, At, B0); PG8_MMA(0, 1, At, B1); PG8_BAR; PG8_SCHED;
	s_add_i32 s84, 0, 0x18000
	s_add_i32 s85, 0, 0x1c000
	v_add_u32_e32 v110, s84, v211
	v_add_u32_e32 v150, s85, v211
	ds_read_b128 v[78:81], v110
	ds_read_b128 v[86:89], v110 offset:1024
	ds_read_b128 v[102:105], v110 offset:2048
	ds_read_b128 v[110:113], v110 offset:3072
	ds_read_b128 v[122:125], v150
	ds_read_b128 v[134:137], v150 offset:1024
	ds_read_b128 v[146:149], v150 offset:2048
	ds_read_b128 v[150:153], v150 offset:3072
	s_add_u32 s8, s30, 0x160000
	s_addc_u32 s9, s31, 0
	s_mov_b32 m0, s37
	v_lshl_add_u64 v[218:219], s[8:9], 0, v[196:197]
	ds_read_b128 v[162:165], v212 offset:32768
	ds_read_b128 v[166:169], v212 offset:33792
	ds_read_b128 v[170:173], v212 offset:34816
	ds_read_b128 v[174:177], v212 offset:35840
	ds_read_b128 v[178:181], v212 offset:36864
	ds_read_b128 v[182:185], v212 offset:37888
	ds_read_b128 v[186:189], v212 offset:38912
	ds_read_b128 v[202:205], v212 offset:39936
	global_load_lds_dwordx4 v[218:219], off
	v_lshl_add_u64 v[218:219], s[8:9], 0, v[192:193]
	s_mov_b32 m0, s40
	s_nop 0
	global_load_lds_dwordx4 v[218:219], off
	s_waitcnt vmcnt(8)
	s_waitcnt lgkmcnt(0)
	s_barrier
	s_waitcnt lgkmcnt(0)
	v_mfma_f32_16x16x32_bf16 v[158:161], v[78:81], v[162:165], v[158:161]
	v_mfma_f32_16x16x32_bf16 v[154:157], v[102:105], v[162:165], v[154:157]
	v_mfma_f32_16x16x32_bf16 v[130:133], v[78:81], v[170:173], v[130:133]
	v_mfma_f32_16x16x32_bf16 v[126:129], v[102:105], v[170:173], v[126:129]
	v_mfma_f32_16x16x32_bf16 v[106:109], v[78:81], v[178:181], v[106:109]
	v_mfma_f32_16x16x32_bf16 v[98:101], v[102:105], v[178:181], v[98:101]
	v_mfma_f32_16x16x32_bf16 v[82:85], v[78:81], v[186:189], v[82:85]
	v_mfma_f32_16x16x32_bf16 v[74:77], v[102:105], v[186:189], v[74:77]
	v_mfma_f32_16x16x32_bf16 v[158:161], v[86:89], v[166:169], v[158:161]
	v_mfma_f32_16x16x32_bf16 v[154:157], v[110:113], v[166:169], v[154:157]
	v_mfma_f32_16x16x32_bf16 v[130:133], v[86:89], v[174:177], v[130:133]
	v_mfma_f32_16x16x32_bf16 v[126:129], v[110:113], v[174:177], v[126:129]
	v_mfma_f32_16x16x32_bf16 v[106:109], v[86:89], v[182:185], v[106:109]
	v_mfma_f32_16x16x32_bf16 v[98:101], v[110:113], v[182:185], v[98:101]
	v_mfma_f32_16x16x32_bf16 v[82:85], v[86:89], v[202:205], v[82:85]
	v_mfma_f32_16x16x32_bf16 v[74:77], v[110:113], v[202:205], v[74:77]
	v_mfma_f32_16x16x32_bf16 v[142:145], v[122:125], v[162:165], v[142:145]
	v_mfma_f32_16x16x32_bf16 v[138:141], v[146:149], v[162:165], v[138:141]
	v_mfma_f32_16x16x32_bf16 v[118:121], v[122:125], v[170:173], v[118:121]
	v_mfma_f32_16x16x32_bf16 v[114:117], v[146:149], v[170:173], v[114:117]
	v_mfma_f32_16x16x32_bf16 v[94:97], v[122:125], v[178:181], v[94:97]
	v_mfma_f32_16x16x32_bf16 v[90:93], v[146:149], v[178:181], v[90:93]
	v_mfma_f32_16x16x32_bf16 v[70:73], v[122:125], v[186:189], v[70:73]
	v_mfma_f32_16x16x32_bf16 v[66:69], v[146:149], v[186:189], v[66:69]
	v_mfma_f32_16x16x32_bf16 v[142:145], v[134:137], v[166:169], v[142:145]
	v_mfma_f32_16x16x32_bf16 v[138:141], v[150:153], v[166:169], v[138:141]
	v_mfma_f32_16x16x32_bf16 v[118:121], v[134:137], v[174:177], v[118:121]
	v_mfma_f32_16x16x32_bf16 v[114:117], v[150:153], v[174:177], v[114:117]
	v_mfma_f32_16x16x32_bf16 v[94:97], v[134:137], v[182:185], v[94:97]
	v_mfma_f32_16x16x32_bf16 v[90:93], v[150:153], v[182:185], v[90:93]
	v_mfma_f32_16x16x32_bf16 v[70:73], v[134:137], v[202:205], v[70:73]
	v_mfma_f32_16x16x32_bf16 v[66:69], v[150:153], v[202:205], v[66:69]
	s_barrier
; #define PG8_STAGE(bufoff, gbase, voff) do { _Pragma("unroll") for (int _i = 0; _i < 2; ++_i) \
;         __builtin_amdgcn_global_load_lds((const unsigned*)((const char*)(gbase) + (voff)[_i]), (PG8_LAS unsigned*)(lds + (bufoff) + ldsw + _i * 8192), 16, 0, 0); } while (0)
; #define PG8_LDA(dst, b, h) do { _Pragma("unroll") for (int m = 0; m < 4; ++m) _Pragma("unroll") for (int k = 0; k < 2; ++k) dst[m][k] = *(const PG8_LAS bf16x8*)(lds + PG8_SA(b, h) + aoff + m * 2048 + k * 1024); } while (0)
; #define PG8_MMA(ai, bj, At, Bt) do { __builtin_amdgcn_s_setprio(1); _Pragma("unroll") for (int m = 0; m < 4; ++m) _Pragma("unroll") for (int n = 0; n < 2; ++n) _Pragma("unroll") for (int k = 0; k < 2; ++k) \
;         acc[ai][bj][m][n] = __builtin_amdgcn_mfma_f32_16x16x32_bf16(Bt[n][k], At[m][k], acc[ai][bj][m][n], 0, 0, 0); __builtin_amdgcn_s_setprio(0); } while (0)
; #define PG8_WAIT_V(n) asm volatile("s_waitcnt vmcnt(" #n ")" ::: "memory")
; #define PG8_WAIT_L(n) asm volatile("s_waitcnt lgkmcnt(" #n ")" ::: "memory")
; #define PG8_BAR __builtin_amdgcn_s_barrier()
; #define PG8_SCHED __builtin_amdgcn_sched_barrier(0)
; template <class Epi, class Sched, bool ALIGN_EPI = false, bool SP2 = false>
; __device__ __forceinline__ void gemm_phase(PG8_LAS unsigned char* lds, const Gemm g, const Sched& S, const Epi& E, int wave_s) {
;     ...
;             PG8_LDA(At, 1, 1); PG8_STAGE(PG8_SB(1, 0), b3, voffB); PG8_STAGE(PG8_SB(1, 1), b3 + hstepB, voffB); PG8_STAGE(PG8_SA(1, 0), a3, voffA);
;             PG8_WAIT_V(8); PG8_WAIT_L(0); PG8_BAR; PG8_MMA(1, 0, At, B0); PG8_MMA(1, 1, At, B1); PG8_BAR; PG8_SCHED;
;     ...
;         if constexpr (ALIGN_EPI) { if (wr == 0) PG8_BAR; }
	s_add_i32 s8, s84, s22
	v_lshl_add_u64 v[206:207], v[206:207], 0, s[60:61]
	s_mov_b32 m0, s8
	ds_read_b128 v[162:165], v212 offset:49152
	ds_read_b128 v[166:169], v212 offset:50176
	ds_read_b128 v[170:173], v212 offset:51200
	ds_read_b128 v[174:177], v212 offset:52224
	ds_read_b128 v[178:181], v212 offset:53248
	ds_read_b128 v[182:185], v212 offset:54272
	ds_read_b128 v[186:189], v212 offset:55296
	ds_read_b128 v[202:205], v212 offset:56320
	global_load_lds_dwordx4 v[206:207], off
	s_add_i32 m0, s8, 0x2000
	s_add_u32 s6, s6, 0x160080
	v_lshl_add_u64 v[206:207], v[208:209], 0, s[60:61]
	s_addc_u32 s7, s7, 0
	s_add_i32 s8, s85, s22
	global_load_lds_dwordx4 v[206:207], off
	v_lshl_add_u64 v[206:207], s[6:7], 0, v[194:195]
	s_mov_b32 m0, s8
	s_nop 0
	global_load_lds_dwordx4 v[206:207], off
	v_lshl_add_u64 v[206:207], s[6:7], 0, v[190:191]
	s_add_i32 m0, s8, 0x2000
	s_nop 0
	global_load_lds_dwordx4 v[206:207], off
	v_lshl_add_u64 v[206:207], v[214:215], 0, s[60:61]
	s_mov_b32 m0, s44
	s_nop 0
	global_load_lds_dwordx4 v[206:207], off
	v_lshl_add_u64 v[206:207], v[216:217], 0, s[60:61]
	s_mov_b32 m0, s45
	s_nop 0
	global_load_lds_dwordx4 v[206:207], off
	s_waitcnt vmcnt(8)
	s_waitcnt lgkmcnt(0)
	s_barrier
	s_waitcnt lgkmcnt(0)
	v_mfma_f32_16x16x32_bf16 v[62:65], v[78:81], v[162:165], v[62:65]
	v_mfma_f32_16x16x32_bf16 v[58:61], v[102:105], v[162:165], v[58:61]
	v_mfma_f32_16x16x32_bf16 v[46:49], v[78:81], v[170:173], v[46:49]
	v_mfma_f32_16x16x32_bf16 v[42:45], v[102:105], v[170:173], v[42:45]
	v_mfma_f32_16x16x32_bf16 v[30:33], v[78:81], v[178:181], v[30:33]
	v_mfma_f32_16x16x32_bf16 v[26:29], v[102:105], v[178:181], v[26:29]
	v_mfma_f32_16x16x32_bf16 v[14:17], v[78:81], v[186:189], v[14:17]
	v_mfma_f32_16x16x32_bf16 v[10:13], v[102:105], v[186:189], v[10:13]
	v_mfma_f32_16x16x32_bf16 v[62:65], v[86:89], v[166:169], v[62:65]
	v_mfma_f32_16x16x32_bf16 v[58:61], v[110:113], v[166:169], v[58:61]
	v_mfma_f32_16x16x32_bf16 v[46:49], v[86:89], v[174:177], v[46:49]
	v_mfma_f32_16x16x32_bf16 v[42:45], v[110:113], v[174:177], v[42:45]
	v_mfma_f32_16x16x32_bf16 v[30:33], v[86:89], v[182:185], v[30:33]
	v_mfma_f32_16x16x32_bf16 v[26:29], v[110:113], v[182:185], v[26:29]
	v_mfma_f32_16x16x32_bf16 v[14:17], v[86:89], v[202:205], v[14:17]
	v_mfma_f32_16x16x32_bf16 v[10:13], v[110:113], v[202:205], v[10:13]
	v_mfma_f32_16x16x32_bf16 v[54:57], v[122:125], v[162:165], v[54:57]
	v_mfma_f32_16x16x32_bf16 v[50:53], v[146:149], v[162:165], v[50:53]
	v_mfma_f32_16x16x32_bf16 v[38:41], v[122:125], v[170:173], v[38:41]
	v_mfma_f32_16x16x32_bf16 v[34:37], v[146:149], v[170:173], v[34:37]
	v_mfma_f32_16x16x32_bf16 v[22:25], v[122:125], v[178:181], v[22:25]
	v_mfma_f32_16x16x32_bf16 v[18:21], v[146:149], v[178:181], v[18:21]
	v_mfma_f32_16x16x32_bf16 v[6:9], v[122:125], v[186:189], v[6:9]
	v_mfma_f32_16x16x32_bf16 v[2:5], v[146:149], v[186:189], v[2:5]
	v_mfma_f32_16x16x32_bf16 v[54:57], v[134:137], v[166:169], v[54:57]
	v_mfma_f32_16x16x32_bf16 v[50:53], v[150:153], v[166:169], v[50:53]
	v_mfma_f32_16x16x32_bf16 v[38:41], v[134:137], v[174:177], v[38:41]
	v_mfma_f32_16x16x32_bf16 v[34:37], v[150:153], v[174:177], v[34:37]
	v_mfma_f32_16x16x32_bf16 v[22:25], v[134:137], v[182:185], v[22:25]
	v_mfma_f32_16x16x32_bf16 v[18:21], v[150:153], v[182:185], v[18:21]
	v_mfma_f32_16x16x32_bf16 v[6:9], v[134:137], v[202:205], v[6:9]
	v_mfma_f32_16x16x32_bf16 v[2:5], v[150:153], v[202:205], v[2:5]
	s_add_i32 s81, s81, 2
	s_add_u32 s2, s2, 0x100
	s_addc_u32 s3, s3, 0
	s_mov_b64 s[8:9], s[4:5]
	s_add_u32 s4, s8, 0x100
	s_addc_u32 s5, s9, 0
	s_add_i32 s84, 0, 0x10000
	s_cmpk_eq_i32 s81, 0x54
	s_cselect_b32 s31, s95, s5
	s_cselect_b32 s30, s94, s4
	s_cselect_b32 s7, s97, s3
	s_cselect_b32 s6, s96, s2
	s_add_i32 s85, 0, 0x14000
	s_cmpk_gt_u32 s81, 0x55
	s_barrier
	s_cbranch_scc0 .LBB0_786
	s_and_b64 vcc, exec, s[88:89]
	s_cbranch_vccz .LBB0_789
	s_barrier
